# xattn LDS fragment prefetch, route compare/select pipelining without nops, FoX max3 chain
# speedup vs baseline: 1.0110x; 1.0110x over previous
; __device__ __forceinline__ unsigned ordf(float f) { unsigned u = __float_as_uint(f); return u ^ ((unsigned)((int)u >> 31) | 0x80000000u); }
; __device__ __forceinline__ void route_half(const unsigned char* kp, const bf16* qptr, int r, int hf, unsigned (&L)[16]) {
;     ...
;     for (int blk = 0; blk < 4; ++blk) {
;         f32x16 sc;
; #pragma unroll
;         for (int i = 0; i < 16; ++i) sc[i] = 0.f;
; #pragma unroll
;         for (int ks = 0; ks < 8; ++ks) { const bf16x8 a = *(const bf16x8*)(kp + (blk * 32 + r) * RT_KP + (16 * ks + 8 * hf) * 2);
;             sc = __builtin_amdgcn_mfma_f32_32x32x16_bf16(a, qf[ks], sc, 0, 0, 0); }
;         unsigned kv[16];
; #pragma unroll
;         for (int i = 0; i < 16; ++i) { const unsigned n = (unsigned)(blk * 32 + (i & 3) + 8 * (i >> 2) + 4 * hf); kv[i] = (ordf(sc[i]) & ~0x7Fu) | n; }
;         sort16_desc(kv); merge16_desc(L, kv);
.LBB0_134:
	ds_read_b128 v[2:5], v115
	ds_read_b128 v[50:53], v115 offset:32
	v_add_u32_e32 v116, s0, v63
	s_add_i32 s0, s0, 32
	s_cmpk_lg_i32 s0, 0x80
	s_waitcnt vmcnt(7) lgkmcnt(1)
	v_mfma_f32_32x32x16_bf16 v[2:17], v[2:5], v[18:21], 0
	s_waitcnt vmcnt(6) lgkmcnt(0)
	v_mfma_f32_32x32x16_bf16 v[2:17], v[50:53], v[22:25], v[2:17]
	ds_read_b128 v[50:53], v115 offset:64
	s_waitcnt vmcnt(5) lgkmcnt(0)
	v_mfma_f32_32x32x16_bf16 v[2:17], v[50:53], v[26:29], v[2:17]
	ds_read_b128 v[50:53], v115 offset:96
	s_waitcnt vmcnt(4) lgkmcnt(0)
	v_mfma_f32_32x32x16_bf16 v[2:17], v[50:53], v[30:33], v[2:17]
	ds_read_b128 v[50:53], v115 offset:128
	s_waitcnt vmcnt(3) lgkmcnt(0)
	v_mfma_f32_32x32x16_bf16 v[2:17], v[50:53], v[34:37], v[2:17]
	ds_read_b128 v[50:53], v115 offset:160
	s_waitcnt vmcnt(2) lgkmcnt(0)
	v_mfma_f32_32x32x16_bf16 v[2:17], v[50:53], v[38:41], v[2:17]
	ds_read_b128 v[50:53], v115 offset:192
	s_waitcnt vmcnt(1) lgkmcnt(0)
	v_mfma_f32_32x32x16_bf16 v[2:17], v[50:53], v[42:45], v[2:17]
	ds_read_b128 v[50:53], v115 offset:224
	v_add_u32_e32 v115, 0x2200, v115
	s_waitcnt vmcnt(0) lgkmcnt(0)
	v_mfma_f32_32x32x16_bf16 v[2:17], v[50:53], v[46:49], v[2:17]
	s_nop 11
	v_ashrrev_i32_e32 v50, 31, v2
	v_ashrrev_i32_e32 v51, 31, v3
	v_ashrrev_i32_e32 v52, 31, v4
	v_ashrrev_i32_e32 v53, 31, v5
	v_ashrrev_i32_e32 v117, 31, v6
	v_ashrrev_i32_e32 v118, 31, v7
	v_ashrrev_i32_e32 v119, 31, v8
	v_ashrrev_i32_e32 v120, 31, v9
	v_ashrrev_i32_e32 v121, 31, v10
	v_ashrrev_i32_e32 v122, 31, v11
	v_ashrrev_i32_e32 v123, 31, v12
	v_ashrrev_i32_e32 v124, 31, v13
	v_ashrrev_i32_e32 v125, 31, v14
	v_ashrrev_i32_e32 v126, 31, v15
	v_ashrrev_i32_e32 v127, 31, v16
	v_ashrrev_i32_e32 v128, 31, v17
	v_or_b32_e32 v50, 0x80000000, v50
	v_or_b32_e32 v51, 0x80000000, v51
	v_or_b32_e32 v52, 0x80000000, v52
	v_or_b32_e32 v53, 0x80000000, v53
	v_or_b32_e32 v117, 0x80000000, v117
	v_or_b32_e32 v118, 0x80000000, v118
	v_or_b32_e32 v119, 0x80000000, v119
	v_or_b32_e32 v120, 0x80000000, v120
	v_or_b32_e32 v121, 0x80000000, v121
	v_or_b32_e32 v122, 0x80000000, v122
	v_or_b32_e32 v123, 0x80000000, v123
	v_or_b32_e32 v124, 0x80000000, v124
	v_or_b32_e32 v125, 0x80000000, v125
	v_or_b32_e32 v126, 0x80000000, v126
	v_or_b32_e32 v127, 0x80000000, v127
	v_or_b32_e32 v128, 0x80000000, v128
	v_bitop3_b32 v2, v50, s81, v2 bitop3:0x48
	v_bitop3_b32 v3, v51, s81, v3 bitop3:0x48
	v_bitop3_b32 v4, v52, s81, v4 bitop3:0x48
	v_bitop3_b32 v5, v53, s81, v5 bitop3:0x48
	v_bitop3_b32 v6, v117, s81, v6 bitop3:0x48
	v_bitop3_b32 v7, v118, s81, v7 bitop3:0x48
	v_bitop3_b32 v8, v119, s81, v8 bitop3:0x48
	v_bitop3_b32 v9, v120, s81, v9 bitop3:0x48
	v_bitop3_b32 v10, v121, s81, v10 bitop3:0x48
	v_bitop3_b32 v11, v122, s81, v11 bitop3:0x48
	v_bitop3_b32 v12, v123, s81, v12 bitop3:0x48
	v_bitop3_b32 v13, v124, s81, v13 bitop3:0x48
	v_bitop3_b32 v14, v125, s81, v14 bitop3:0x48
	v_bitop3_b32 v15, v126, s81, v15 bitop3:0x48
	v_bitop3_b32 v16, v127, s81, v16 bitop3:0x48
	v_bitop3_b32 v17, v128, s81, v17 bitop3:0x48
	v_add_u32_e32 v2, v116, v2
	v_add3_u32 v3, v116, v3, 1
	v_add3_u32 v4, v116, v4, 2
	v_add3_u32 v5, v116, v5, 3
	v_add3_u32 v6, v116, v6, 8
	v_add3_u32 v7, v116, v7, 9
	v_add3_u32 v8, v116, v8, 10
	v_add3_u32 v9, v116, v9, 11
	v_add3_u32 v10, v116, v10, 16
	v_add3_u32 v11, v116, v11, 17
	v_add3_u32 v12, v116, v12, 18
	v_add3_u32 v13, v116, v13, 19
	v_add3_u32 v14, v116, v14, 24
	v_add3_u32 v15, v116, v15, 25
	v_add3_u32 v16, v116, v16, 26
	v_add3_u32 v17, v116, v17, 27
	v_max_u32_e32 v50, v2, v3
	v_min_u32_e32 v2, v2, v3
	v_max_u32_e32 v3, v5, v4
	v_min_u32_e32 v4, v5, v4
	v_max_u32_e32 v5, v6, v7
	v_min_u32_e32 v6, v6, v7
	v_max_u32_e32 v7, v9, v8
	v_min_u32_e32 v8, v9, v8
	v_max_u32_e32 v9, v10, v11
	v_min_u32_e32 v10, v10, v11
	v_max_u32_e32 v11, v13, v12
	v_min_u32_e32 v12, v13, v12
	v_max_u32_e32 v13, v14, v15
	v_min_u32_e32 v14, v14, v15
	v_max_u32_e32 v15, v17, v16
	v_min_u32_e32 v16, v17, v16
	v_max_u32_e32 v17, v50, v4
	v_min_u32_e32 v4, v50, v4
	v_max_u32_e32 v50, v2, v3
	v_min_u32_e32 v2, v2, v3
	v_max_u32_e32 v3, v8, v5
	v_min_u32_e32 v5, v8, v5
	v_max_u32_e32 v8, v7, v6
	v_min_u32_e32 v6, v7, v6
	v_max_u32_e32 v7, v9, v12
	v_min_u32_e32 v9, v9, v12
	v_max_u32_e32 v12, v10, v11
	v_min_u32_e32 v10, v10, v11
	v_max_u32_e32 v11, v16, v13
	v_min_u32_e32 v13, v16, v13
	v_max_u32_e32 v16, v15, v14
	v_min_u32_e32 v14, v15, v14
	v_max_u32_e32 v15, v17, v50
	v_min_u32_e32 v17, v17, v50
	v_max_u32_e32 v50, v4, v2
	v_min_u32_e32 v2, v4, v2
	v_max_u32_e32 v4, v6, v5
	v_min_u32_e32 v5, v6, v5
	v_max_u32_e32 v6, v8, v3
	v_min_u32_e32 v3, v8, v3
	v_max_u32_e32 v8, v7, v12
	v_min_u32_e32 v7, v7, v12
	v_max_u32_e32 v12, v9, v10
	v_min_u32_e32 v9, v9, v10
	v_max_u32_e32 v10, v14, v13
	v_min_u32_e32 v13, v14, v13
	v_max_u32_e32 v14, v16, v11
	v_min_u32_e32 v11, v16, v11
	v_max_u32_e32 v16, v15, v5
	v_min_u32_e32 v5, v15, v5
	v_max_u32_e32 v15, v17, v4
	v_min_u32_e32 v4, v17, v4
	v_max_u32_e32 v17, v50, v3
	v_min_u32_e32 v3, v50, v3
	v_max_u32_e32 v50, v2, v6
	v_min_u32_e32 v2, v2, v6
	v_max_u32_e32 v6, v13, v8
	v_min_u32_e32 v8, v13, v8
	v_max_u32_e32 v13, v10, v7
	v_min_u32_e32 v7, v10, v7
	v_max_u32_e32 v10, v11, v12
	v_min_u32_e32 v11, v11, v12
	v_max_u32_e32 v12, v14, v9
	v_min_u32_e32 v9, v14, v9
	v_max_u32_e32 v14, v16, v17
	v_min_u32_e32 v16, v16, v17
	v_max_u32_e32 v17, v15, v50
	v_min_u32_e32 v15, v15, v50
	v_max_u32_e32 v50, v5, v3
	v_min_u32_e32 v3, v5, v3
	v_max_u32_e32 v5, v4, v2
	v_min_u32_e32 v2, v4, v2
	v_max_u32_e32 v4, v11, v8
	v_min_u32_e32 v8, v11, v8
	v_max_u32_e32 v11, v9, v7
	v_min_u32_e32 v7, v9, v7
	v_max_u32_e32 v9, v10, v6
	v_min_u32_e32 v6, v10, v6
	v_max_u32_e32 v10, v12, v13
; #define CE_DESC(a, b) do { const unsigned _h = max((a), (b)), _l = min((a), (b)); (a) = _h; (b) = _l; } while (0)
; __device__ __forceinline__ void sort16_desc(unsigned (&v)[16]) {
; #pragma unroll
;     for (int k = 2; k <= 16; k <<= 1)
; #pragma unroll
;         for (int j = k >> 1; j > 0; j >>= 1)
; #pragma unroll
;             for (int i = 0; i < 16; ++i) { const int p = i ^ j; if (p > i) { if ((i & k) == 0) CE_DESC(v[i], v[p]); else CE_DESC(v[p], v[i]); } }
; }
; __device__ __forceinline__ void merge16_desc(unsigned (&a)[16], const unsigned (&b)[16]) {
; #pragma unroll
;     for (int i = 0; i < 16; ++i) a[i] = max(a[i], b[15 - i]);
; #pragma unroll
;     for (int j = 8; j > 0; j >>= 1)
; #pragma unroll
;         for (int i = 0; i < 16; ++i) { const int p = i ^ j; if (p > i) CE_DESC(a[i], a[p]); }
; }
; __device__ __forceinline__ void route_half(const unsigned char* kp, const bf16* qptr, int r, int hf, unsigned (&L)[16]) {
;     ...
;         sort16_desc(kv); merge16_desc(L, kv);
	v_min_u32_e32 v12, v12, v13
	v_max_u32_e32 v13, v14, v17
	v_min_u32_e32 v14, v14, v17
	v_max_u32_e32 v17, v16, v15
	v_min_u32_e32 v15, v16, v15
	v_max_u32_e32 v16, v50, v5
	v_min_u32_e32 v5, v50, v5
	v_max_u32_e32 v50, v3, v2
	v_min_u32_e32 v2, v3, v2
	v_max_u32_e32 v3, v7, v8
	v_min_u32_e32 v7, v7, v8
	v_max_u32_e32 v8, v11, v4
	v_min_u32_e32 v4, v11, v4
	v_max_u32_e32 v11, v12, v6
	v_min_u32_e32 v6, v12, v6
	v_max_u32_e32 v12, v10, v9
	v_min_u32_e32 v9, v10, v9
	v_max_u32_e32 v10, v13, v7
	v_min_u32_e32 v7, v13, v7
	v_max_u32_e32 v13, v14, v3
	v_min_u32_e32 v3, v14, v3
	v_max_u32_e32 v14, v17, v4
	v_min_u32_e32 v4, v17, v4
	v_max_u32_e32 v17, v15, v8
	v_min_u32_e32 v8, v15, v8
	v_max_u32_e32 v15, v16, v6
	v_min_u32_e32 v6, v16, v6
	v_max_u32_e32 v16, v5, v11
	v_min_u32_e32 v5, v5, v11
	v_max_u32_e32 v11, v50, v9
	v_min_u32_e32 v9, v50, v9
	v_max_u32_e32 v50, v2, v12
	v_min_u32_e32 v2, v2, v12
	v_max_u32_e32 v12, v10, v15
	v_min_u32_e32 v10, v10, v15
	v_max_u32_e32 v15, v13, v16
	v_min_u32_e32 v13, v13, v16
	v_max_u32_e32 v16, v14, v11
	v_min_u32_e32 v11, v14, v11
	v_max_u32_e32 v14, v17, v50
	v_min_u32_e32 v17, v17, v50
	v_max_u32_e32 v50, v7, v6
	v_min_u32_e32 v6, v7, v6
	v_max_u32_e32 v7, v3, v5
	v_min_u32_e32 v3, v3, v5
	v_max_u32_e32 v5, v4, v9
	v_min_u32_e32 v4, v4, v9
	v_max_u32_e32 v9, v8, v2
	v_min_u32_e32 v2, v8, v2
	v_max_u32_e32 v8, v12, v16
	v_min_u32_e32 v12, v12, v16
	v_max_u32_e32 v16, v15, v14
	v_min_u32_e32 v14, v15, v14
	v_max_u32_e32 v15, v10, v11
	v_min_u32_e32 v10, v10, v11
	v_max_u32_e32 v11, v13, v17
	v_min_u32_e32 v13, v13, v17
	v_max_u32_e32 v17, v50, v5
	v_min_u32_e32 v5, v50, v5
	v_max_u32_e32 v50, v7, v9
	v_min_u32_e32 v7, v7, v9
	v_max_u32_e32 v9, v6, v4
	v_min_u32_e32 v4, v6, v4
	v_max_u32_e32 v6, v3, v2
	v_min_u32_e32 v2, v3, v2
	v_min_u32_e32 v3, v8, v16
	v_min_u32_e32 v51, v12, v14
	v_min_u32_e32 v52, v15, v11
	v_min_u32_e32 v53, v10, v13
	v_min_u32_e32 v116, v17, v50
	v_min_u32_e32 v117, v5, v7
	v_min_u32_e32 v118, v9, v6
	v_min_u32_e32 v119, v4, v2
	v_max3_u32 v2, v91, v4, v2
	v_max3_u32 v4, v92, v9, v6
	v_max3_u32 v5, v93, v5, v7
	v_max3_u32 v6, v95, v17, v50
	v_max3_u32 v7, v96, v10, v13
	v_max3_u32 v9, v98, v15, v11
	v_max3_u32 v10, v99, v12, v14
	v_max3_u32 v8, v101, v8, v16
	v_max_u32_e32 v11, v83, v119
	v_max_u32_e32 v12, v84, v118
	v_max_u32_e32 v13, v85, v117
	v_max_u32_e32 v14, v86, v116
	v_max_u32_e32 v15, v87, v53
	v_max_u32_e32 v16, v88, v52
	v_max_u32_e32 v17, v89, v51
	v_max_u32_e32 v3, v90, v3
	v_max_u32_e32 v50, v2, v7
	v_min_u32_e32 v2, v2, v7
	v_max_u32_e32 v7, v4, v9
	v_min_u32_e32 v4, v4, v9
	v_max_u32_e32 v9, v5, v10
	v_min_u32_e32 v5, v5, v10
	v_max_u32_e32 v10, v6, v8
	v_min_u32_e32 v6, v6, v8
	v_max_u32_e32 v8, v11, v15
	v_min_u32_e32 v11, v11, v15
	v_max_u32_e32 v15, v12, v16
	v_min_u32_e32 v12, v12, v16
	v_max_u32_e32 v16, v13, v17
	v_min_u32_e32 v13, v13, v17
	v_max_u32_e32 v17, v14, v3
	v_min_u32_e32 v3, v14, v3
	v_max_u32_e32 v14, v50, v9
	v_min_u32_e32 v9, v50, v9
	v_max_u32_e32 v50, v7, v10
	v_min_u32_e32 v7, v7, v10
	v_max_u32_e32 v10, v2, v5
	v_min_u32_e32 v2, v2, v5
	v_max_u32_e32 v5, v4, v6
	v_min_u32_e32 v4, v4, v6
	v_max_u32_e32 v6, v8, v16
	v_min_u32_e32 v8, v8, v16
	v_max_u32_e32 v16, v15, v17
	v_min_u32_e32 v15, v15, v17
	v_max_u32_e32 v17, v11, v13
	v_min_u32_e32 v11, v11, v13
	v_max_u32_e32 v13, v12, v3
	v_min_u32_e32 v3, v12, v3
	v_max_u32_e32 v12, v14, v50
	v_min_u32_e32 v14, v14, v50
	v_max_u32_e32 v50, v9, v7
	v_min_u32_e32 v7, v9, v7
	v_max_u32_e32 v9, v10, v5
	v_min_u32_e32 v5, v10, v5
	v_max_u32_e32 v10, v2, v4
	v_min_u32_e32 v2, v2, v4
	v_max_u32_e32 v4, v6, v16
	v_min_u32_e32 v6, v6, v16
	v_max_u32_e32 v16, v8, v15
	v_min_u32_e32 v8, v8, v15
	v_max_u32_e32 v15, v17, v13
	v_min_u32_e32 v13, v17, v13
	v_max_u32_e32 v17, v11, v3
	v_min_u32_e32 v3, v11, v3
	v_max_u32_e32 v83, v4, v12
	v_min_u32_e32 v91, v4, v12
	v_max_u32_e32 v84, v6, v14
	v_min_u32_e32 v92, v6, v14
	v_max_u32_e32 v85, v16, v50
	v_min_u32_e32 v93, v16, v50
	v_max_u32_e32 v86, v8, v7
	v_min_u32_e32 v95, v8, v7
	v_max_u32_e32 v87, v15, v9
	v_min_u32_e32 v96, v15, v9
	v_max_u32_e32 v88, v13, v5
	v_min_u32_e32 v98, v13, v5
	v_max_u32_e32 v89, v17, v10
	v_min_u32_e32 v99, v17, v10
	v_max_u32_e32 v90, v3, v2
	v_min_u32_e32 v101, v3, v2
	s_cbranch_scc1 .LBB0_134
; __device__ __forceinline__ float unordf(unsigned v) { return __uint_as_float(v ^ ((~(unsigned)((int)v >> 31)) | 0x80000000u)); }
; __device__ __forceinline__ void route_half(const unsigned char* kp, const bf16* qptr, int r, int hf, unsigned (&L)[16]) {
;     ...
;     unsigned pk[16];
; #pragma unroll
;     for (int j = 0; j < 16; ++j) pk[j] = (unsigned)__shfl_xor((int)L[j], 32);
;     merge16_desc(L, pk);
; __device__ __forceinline__ void phase_route(CArgs& A, int l, unsigned char* lds, int tid) {
;     ...
;         for (int j = 0; j < 16; ++j) { v1[j] = unordf(L1[j] & ~0x7Fu); v2[j] = unordf(L2[j] & ~0x7Fu); L3[j] = 0u; }
	v_max_u32_e32 v2, v67, v114
	v_max_u32_e32 v3, v68, v113
	v_max_u32_e32 v4, v69, v112
	v_max_u32_e32 v5, v70, v111
	v_max_u32_e32 v6, v71, v110
	v_max_u32_e32 v7, v72, v109
	v_max_u32_e32 v8, v73, v108
	v_max_u32_e32 v9, v74, v107
	v_max_u32_e32 v10, v75, v106
	v_max_u32_e32 v11, v76, v105
	v_max_u32_e32 v12, v77, v104
	v_max_u32_e32 v13, v78, v103
	v_max_u32_e32 v14, v79, v102
	v_max_u32_e32 v15, v80, v100
	v_max_u32_e32 v16, v81, v97
	v_max_u32_e32 v17, v82, v94
	v_max_u32_e32 v18, v2, v10
	v_min_u32_e32 v2, v2, v10
	v_max_u32_e32 v10, v3, v11
	v_min_u32_e32 v3, v3, v11
	v_max_u32_e32 v11, v4, v12
	v_min_u32_e32 v4, v4, v12
	v_max_u32_e32 v12, v5, v13
	v_min_u32_e32 v5, v5, v13
	v_max_u32_e32 v13, v6, v14
	v_min_u32_e32 v6, v6, v14
	v_max_u32_e32 v14, v7, v15
	v_min_u32_e32 v7, v7, v15
	v_max_u32_e32 v15, v8, v16
	v_min_u32_e32 v8, v8, v16
	v_max_u32_e32 v16, v9, v17
	v_min_u32_e32 v9, v9, v17
	v_max_u32_e32 v17, v18, v13
	v_min_u32_e32 v13, v18, v13
	v_max_u32_e32 v18, v10, v14
	v_min_u32_e32 v10, v10, v14
	v_max_u32_e32 v14, v11, v15
	v_min_u32_e32 v11, v11, v15
	v_max_u32_e32 v15, v12, v16
	v_min_u32_e32 v12, v12, v16
	v_max_u32_e32 v16, v2, v6
	v_min_u32_e32 v2, v2, v6
	v_max_u32_e32 v6, v3, v7
	v_min_u32_e32 v3, v3, v7
	v_max_u32_e32 v7, v4, v8
	v_min_u32_e32 v4, v4, v8
	v_max_u32_e32 v8, v5, v9
	v_min_u32_e32 v5, v5, v9
	v_max_u32_e32 v9, v17, v14
	v_min_u32_e32 v14, v17, v14
	v_max_u32_e32 v17, v18, v15
	v_min_u32_e32 v15, v18, v15
	v_max_u32_e32 v18, v13, v11
	v_min_u32_e32 v11, v13, v11
	v_max_u32_e32 v13, v10, v12
	v_min_u32_e32 v10, v10, v12
	v_max_u32_e32 v12, v16, v7
	v_min_u32_e32 v16, v16, v7
	v_max_u32_e32 v19, v6, v8
	v_min_u32_e32 v6, v6, v8
	v_max_u32_e32 v20, v2, v4
	v_min_u32_e32 v2, v2, v4
	v_max_u32_e32 v21, v3, v5
	v_min_u32_e32 v3, v3, v5
	v_max_u32_e32 v4, v9, v17
	v_max_u32_e32 v5, v14, v15
	v_max_u32_e32 v7, v18, v13
	v_max_u32_e32 v8, v11, v10
	v_max_u32_e32 v53, v12, v19
	v_max_u32_e32 v51, v16, v6
	v_max_u32_e32 v49, v20, v21
	v_max_u32_e32 v47, v2, v3
	v_min_u32_e32 v9, v9, v17
	v_min_u32_e32 v69, v14, v15
	v_min_u32_e32 v67, v18, v13
	v_min_u32_e32 v68, v11, v10
	v_min_u32_e32 v52, v12, v19
	v_min_u32_e32 v50, v16, v6
	v_min_u32_e32 v48, v20, v21
	v_min_u32_e32 v46, v2, v3
	ds_bpermute_b32 v2, v64, v83
	ds_bpermute_b32 v3, v64, v91
	ds_bpermute_b32 v6, v64, v84
	ds_bpermute_b32 v10, v64, v92
	ds_bpermute_b32 v11, v64, v85
	ds_bpermute_b32 v12, v64, v93
	ds_bpermute_b32 v13, v64, v86
	ds_bpermute_b32 v14, v64, v95
	ds_bpermute_b32 v15, v64, v87
	ds_bpermute_b32 v16, v64, v96
	ds_bpermute_b32 v17, v64, v88
	ds_bpermute_b32 v18, v64, v101
	ds_bpermute_b32 v19, v64, v90
	ds_bpermute_b32 v20, v64, v99
	ds_bpermute_b32 v21, v64, v89
	ds_bpermute_b32 v22, v64, v98
	s_waitcnt lgkmcnt(4)
	v_max_u32_e32 v18, v83, v18
	s_waitcnt lgkmcnt(3)
	v_max_u32_e32 v19, v91, v19
	s_waitcnt lgkmcnt(2)
	v_max_u32_e32 v20, v84, v20
	s_waitcnt lgkmcnt(1)
	v_max_u32_e32 v21, v92, v21
	s_waitcnt lgkmcnt(0)
	v_max_u32_e32 v22, v85, v22
	v_max_u32_e32 v17, v93, v17
	v_max_u32_e32 v16, v86, v16
	v_max_u32_e32 v15, v95, v15
	v_max_u32_e32 v14, v87, v14
	v_max_u32_e32 v13, v96, v13
	v_max_u32_e32 v12, v88, v12
	v_max_u32_e32 v11, v98, v11
	v_max_u32_e32 v10, v89, v10
	v_max_u32_e32 v6, v99, v6
	v_max_u32_e32 v3, v90, v3
	v_max_u32_e32 v2, v101, v2
	v_max_u32_e32 v23, v18, v14
	v_min_u32_e32 v14, v18, v14
	v_max_u32_e32 v18, v19, v13
	v_min_u32_e32 v13, v19, v13
	v_max_u32_e32 v19, v20, v12
	v_min_u32_e32 v12, v20, v12
	v_max_u32_e32 v20, v21, v11
	v_min_u32_e32 v11, v21, v11
	v_max_u32_e32 v21, v22, v10
	v_min_u32_e32 v10, v22, v10
	v_max_u32_e32 v22, v17, v6
	v_min_u32_e32 v6, v17, v6
	v_max_u32_e32 v17, v16, v3
	v_min_u32_e32 v3, v16, v3
	v_max_u32_e32 v16, v15, v2
	v_min_u32_e32 v2, v15, v2
	v_max_u32_e32 v15, v23, v21
	v_min_u32_e32 v21, v23, v21
	v_max_u32_e32 v23, v18, v22
	v_min_u32_e32 v18, v18, v22
	v_max_u32_e32 v22, v19, v17
	v_min_u32_e32 v17, v19, v17
	v_max_u32_e32 v19, v20, v16
	v_min_u32_e32 v16, v20, v16
	v_max_u32_e32 v20, v14, v10
	v_min_u32_e32 v10, v14, v10
	v_max_u32_e32 v14, v13, v6
	v_min_u32_e32 v6, v13, v6
	v_max_u32_e32 v13, v12, v3
	v_min_u32_e32 v3, v12, v3
	v_max_u32_e32 v12, v11, v2
	v_min_u32_e32 v2, v11, v2
	v_max_u32_e32 v11, v15, v22
	v_min_u32_e32 v15, v15, v22
	v_max_u32_e32 v22, v23, v19
	v_min_u32_e32 v19, v23, v19
	v_max_u32_e32 v23, v21, v17
	v_min_u32_e32 v17, v21, v17
	v_max_u32_e32 v21, v18, v16
	v_min_u32_e32 v16, v18, v16
	v_max_u32_e32 v18, v20, v13
	v_min_u32_e32 v13, v20, v13
	v_max_u32_e32 v20, v14, v12
	v_min_u32_e32 v12, v14, v12
	v_max_u32_e32 v14, v10, v3
	v_min_u32_e32 v3, v10, v3
	v_max_u32_e32 v10, v6, v2
	v_min_u32_e32 v2, v6, v2
	v_cmp_lt_i32_e32 vcc, -1, v4
	v_max_u32_e32 v45, v11, v22
	v_min_u32_e32 v44, v11, v22
	v_max_u32_e32 v11, v3, v2
	v_min_u32_e32 v6, v3, v2
	v_cndmask_b32_e64 v2, v182, -1, vcc
	v_cmp_lt_i32_e32 vcc, -1, v9
	v_max_u32_e32 v35, v13, v12
	v_min_u32_e32 v34, v13, v12
	v_bitop3_b32 v12, v2, v4, s81 bitop3:0x78
	v_cndmask_b32_e64 v2, v182, -1, vcc
	v_cmp_lt_i32_e32 vcc, -1, v44
	v_max_u32_e32 v43, v15, v19
	v_bitop3_b32 v13, v2, v9, s81 bitop3:0x78
	v_cndmask_b32_e64 v2, v182, -1, vcc
	v_cmp_lt_i32_e32 vcc, -1, v5
	v_max_u32_e32 v33, v14, v10
	v_min_u32_e32 v32, v14, v10
	v_bitop3_b32 v14, v2, v44, s81 bitop3:0x78
	v_cndmask_b32_e64 v2, v182, -1, vcc
	v_cmp_lt_i32_e32 vcc, -1, v43
	v_min_u32_e32 v42, v15, v19
	v_bitop3_b32 v15, v2, v5, s81 bitop3:0x78
	v_cndmask_b32_e64 v2, v182, -1, vcc
	v_cmp_lt_i32_e32 vcc, -1, v69
	v_max_u32_e32 v39, v17, v16
	v_min_u32_e32 v38, v17, v16
	v_bitop3_b32 v16, v2, v43, s81 bitop3:0x78
	v_cndmask_b32_e64 v2, v182, -1, vcc
; __device__ __forceinline__ unsigned ordf(float f) { unsigned u = __float_as_uint(f); return u ^ ((unsigned)((int)u >> 31) | 0x80000000u); }
; __device__ __forceinline__ float unordf(unsigned v) { return __uint_as_float(v ^ ((~(unsigned)((int)v >> 31)) | 0x80000000u)); }
; __device__ __forceinline__ void phase_route(CArgs& A, int l, unsigned char* lds, int tid) {
;     ...
;         for (int j = 0; j < 16; ++j) { v1[j] = unordf(L1[j] & ~0x7Fu); v2[j] = unordf(L2[j] & ~0x7Fu); L3[j] = 0u; }
;         {
;             constexpr CandTab CT = make_cand();
;             unsigned g1[16], g2[16];
; #pragma unroll
;             for (int k = 0; k < 16; ++k) {
;                 L3[k] = (ordf(v1[CT.i[k]] + v2[CT.j[k]]) & ~0xFFu) | (unsigned)(CT.i[k] * 16 + CT.j[k]);
;                 g1[k] = (ordf(v1[CT.i[16 + k]] + v2[CT.j[16 + k]]) & ~0xFFu) | (unsigned)(CT.i[16 + k] * 16 + CT.j[16 + k]);
;                 g2[k] = (ordf(v1[CT.i[32 + k]] + v2[CT.j[32 + k]]) & ~0xFFu) | (unsigned)(CT.i[32 + k] * 16 + CT.j[32 + k]); }
	v_cmp_lt_i32_e32 vcc, -1, v42
	v_max_u32_e32 v41, v23, v21
	v_bitop3_b32 v17, v2, v69, s81 bitop3:0x78
	v_cndmask_b32_e64 v2, v182, -1, vcc
	v_cmp_lt_i32_e32 vcc, -1, v7
	v_max_u32_e32 v37, v18, v20
	v_min_u32_e32 v36, v18, v20
	v_bitop3_b32 v18, v2, v42, s81 bitop3:0x78
	v_cndmask_b32_e64 v2, v182, -1, vcc
	v_cmp_lt_i32_e32 vcc, -1, v41
	v_min_u32_e32 v40, v23, v21
	v_bitop3_b32 v19, v2, v7, s81 bitop3:0x78
	v_cndmask_b32_e64 v2, v182, -1, vcc
	v_cmp_lt_i32_e32 vcc, -1, v67
	v_bitop3_b32 v20, v2, v41, s81 bitop3:0x78
	v_and_b32_e32 v78, 0xffffff80, v46
	v_cndmask_b32_e64 v2, v182, -1, vcc
	v_cmp_lt_i32_e32 vcc, -1, v40
	v_bitop3_b32 v21, v2, v67, s81 bitop3:0x78
	s_brev_b32 s0, 1
	v_cndmask_b32_e64 v2, v182, -1, vcc
	v_cmp_lt_i32_e32 vcc, -1, v8
	v_bitop3_b32 v22, v2, v40, s81 bitop3:0x78
	v_and_b32_e32 v40, 0x7f, v40
	v_cndmask_b32_e64 v2, v182, -1, vcc
	v_cmp_lt_i32_e32 vcc, -1, v39
	v_bitop3_b32 v23, v2, v8, s81 bitop3:0x78
	v_and_b32_e32 v41, 0x7f, v41
	v_cndmask_b32_e64 v2, v182, -1, vcc
	v_cmp_lt_i32_e32 vcc, -1, v68
	v_bitop3_b32 v24, v2, v39, s81 bitop3:0x78
	v_and_b32_e32 v39, 0x7f, v39
	v_cndmask_b32_e64 v2, v182, -1, vcc
	v_cmp_lt_i32_e32 vcc, -1, v38
	v_bitop3_b32 v25, v2, v68, s81 bitop3:0x78
	v_and_b32_e32 v42, 0x7f, v42
	v_cndmask_b32_e64 v2, v182, -1, vcc
	v_cmp_lt_i32_e32 vcc, -1, v53
	v_bitop3_b32 v26, v2, v38, s81 bitop3:0x78
	v_and_b32_e32 v38, 0x7f, v38
	v_cndmask_b32_e64 v2, v182, -1, vcc
	v_cmp_lt_i32_e32 vcc, -1, v37
	v_bitop3_b32 v27, v2, v53, s81 bitop3:0x78
	v_and_b32_e32 v43, 0x7f, v43
	v_cndmask_b32_e64 v2, v182, -1, vcc
	v_cmp_lt_i32_e32 vcc, -1, v52
	v_bitop3_b32 v28, v2, v37, s81 bitop3:0x78
	v_and_b32_e32 v37, 0x7f, v37
	v_cndmask_b32_e64 v2, v182, -1, vcc
	v_cmp_lt_i32_e32 vcc, -1, v36
	v_bitop3_b32 v29, v2, v52, s81 bitop3:0x78
	v_and_b32_e32 v44, 0x7f, v44
	v_cndmask_b32_e64 v2, v182, -1, vcc
	v_cmp_lt_i32_e32 vcc, -1, v51
	v_bitop3_b32 v30, v2, v36, s81 bitop3:0x78
	v_add_f32_e32 v30, v12, v30
	v_cndmask_b32_e64 v2, v182, -1, vcc
	v_cmp_lt_i32_e32 vcc, -1, v35
	v_bitop3_b32 v31, v2, v51, s81 bitop3:0x78
	v_and_b32_e32 v36, 0x7f, v36
	v_cndmask_b32_e64 v2, v182, -1, vcc
	v_cmp_lt_i32_e32 vcc, -1, v50
	v_bitop3_b32 v70, v2, v35, s81 bitop3:0x78
	v_add_f32_e32 v70, v12, v70
	v_cndmask_b32_e64 v2, v182, -1, vcc
	v_cmp_lt_i32_e32 vcc, -1, v34
	v_bitop3_b32 v71, v2, v50, s81 bitop3:0x78
	v_and_b32_e32 v35, 0x7f, v35
	v_cndmask_b32_e64 v2, v182, -1, vcc
	v_cmp_lt_i32_e32 vcc, -1, v49
	v_bitop3_b32 v72, v2, v34, s81 bitop3:0x78
	v_add_f32_e32 v72, v12, v72
	v_cndmask_b32_e64 v2, v182, -1, vcc
	v_cmp_lt_i32_e32 vcc, -1, v33
	v_bitop3_b32 v73, v2, v49, s81 bitop3:0x78
	v_and_b32_e32 v34, 0x7f, v34
	v_cndmask_b32_e64 v2, v182, -1, vcc
	v_cmp_lt_i32_e32 vcc, -1, v48
	v_bitop3_b32 v74, v2, v33, s81 bitop3:0x78
	v_add_f32_e32 v74, v12, v74
	v_cndmask_b32_e64 v2, v182, -1, vcc
	v_cmp_lt_i32_e32 vcc, -1, v32
	v_bitop3_b32 v75, v2, v48, s81 bitop3:0x78
	v_and_b32_e32 v33, 0x7f, v33
	v_cndmask_b32_e64 v2, v182, -1, vcc
	v_cmp_lt_i32_e32 vcc, -1, v47
	v_bitop3_b32 v76, v2, v32, s81 bitop3:0x78
	v_and_b32_e32 v32, 0x7f, v32
	v_cndmask_b32_e64 v2, v182, -1, vcc
	v_cmp_lt_i32_e32 vcc, -1, v11
	v_bitop3_b32 v10, v2, v47, s81 bitop3:0x78
	v_and_b32_e32 v47, 0x7f, v47
	v_cndmask_b32_e64 v2, v182, -1, vcc
	v_cmp_lt_i32_e32 vcc, -1, v46
	v_bitop3_b32 v77, v2, v11, s81 bitop3:0x78
	v_and_b32_e32 v2, 0xffffff80, v45
	v_cndmask_b32_e64 v79, v182, -1, vcc
	v_cmp_lt_i32_e32 vcc, -1, v45
	v_add_f32_e32 v77, v12, v77
	v_and_b32_e32 v11, 0x7f, v11
	v_cndmask_b32_e64 v3, v182, -1, vcc
	v_xor_b32_e32 v3, v3, v2
	v_xor_b32_e32 v2, v79, v78
	v_add_f32_e32 v79, v3, v12
	v_ashrrev_i32_e32 v80, 31, v79
	v_or_b32_e32 v80, 0x80000000, v80
	v_bitop3_b32 v79, v80, s82, v79 bitop3:0x48
	v_add_f32_e32 v80, v3, v13
	v_ashrrev_i32_e32 v81, 31, v80
	v_bitop3_b32 v80, v81, v80, s0 bitop3:0x36
	v_add_f32_e32 v81, v17, v18
	v_ashrrev_i32_e32 v82, 31, v81
	v_bitop3_b32 v81, v82, v81, s0 bitop3:0x36
	v_add_f32_e32 v82, v12, v14
	v_ashrrev_i32_e32 v83, 31, v82
	v_bitop3_b32 v82, v83, v82, s0 bitop3:0x36
	v_add_f32_e32 v83, v13, v14
	v_ashrrev_i32_e32 v84, 31, v83
	v_bitop3_b32 v83, v84, v83, s0 bitop3:0x36
	v_add_f32_e32 v84, v3, v19
	v_ashrrev_i32_e32 v85, 31, v84
	v_bitop3_b32 v84, v85, v84, s0 bitop3:0x36
	v_add_f32_e32 v85, v12, v16
	v_ashrrev_i32_e32 v86, 31, v85
	v_bitop3_b32 v85, v86, v85, s0 bitop3:0x36
	v_add_f32_e32 v86, v13, v16
	v_ashrrev_i32_e32 v87, 31, v86
	v_bitop3_b32 v86, v87, v86, s0 bitop3:0x36
	v_add_f32_e32 v87, v19, v14
	v_ashrrev_i32_e32 v88, 31, v87
	v_or_b32_e32 v88, 0x80000000, v88
	v_bitop3_b32 v87, v88, s82, v87 bitop3:0x48
	v_add_f32_e32 v88, v12, v18
	v_ashrrev_i32_e32 v89, 31, v88
	v_bitop3_b32 v88, v89, v88, s0 bitop3:0x36
	v_add_f32_e32 v89, v13, v18
	v_ashrrev_i32_e32 v90, 31, v89
	v_add_f32_e32 v19, v19, v16
	v_bitop3_b32 v89, v90, v89, s0 bitop3:0x36
	v_ashrrev_i32_e32 v90, 31, v19
	v_or_b32_e32 v90, 0x80000000, v90
	v_bitop3_b32 v19, v90, s82, v19 bitop3:0x48
	v_add_f32_e32 v90, v12, v20
	v_ashrrev_i32_e32 v91, 31, v90
	v_bitop3_b32 v90, v91, v90, s0 bitop3:0x36
	v_add_f32_e32 v91, v13, v20
	v_ashrrev_i32_e32 v92, 31, v91
	v_bitop3_b32 v91, v92, v91, s0 bitop3:0x36
	v_add_f32_e32 v92, v3, v21
	v_ashrrev_i32_e32 v93, 31, v92
	v_or_b32_e32 v93, 0x80000000, v93
	v_bitop3_b32 v92, v93, s82, v92 bitop3:0x48
	v_add_f32_e32 v93, v12, v22
	v_ashrrev_i32_e32 v94, 31, v93
	v_add_f32_e32 v22, v13, v22
	v_bitop3_b32 v93, v94, v93, s0 bitop3:0x36
	v_ashrrev_i32_e32 v94, 31, v22
	v_add_f32_e32 v21, v21, v14
	v_bitop3_b32 v22, v94, v22, s0 bitop3:0x36
	v_ashrrev_i32_e32 v94, 31, v21
	v_or_b32_e32 v94, 0x80000000, v94
; __device__ __forceinline__ unsigned ordf(float f) { unsigned u = __float_as_uint(f); return u ^ ((unsigned)((int)u >> 31) | 0x80000000u); }
; __device__ __forceinline__ void phase_route(CArgs& A, int l, unsigned char* lds, int tid) {
;     ...
;                 L3[k] = (ordf(v1[CT.i[k]] + v2[CT.j[k]]) & ~0xFFu) | (unsigned)(CT.i[k] * 16 + CT.j[k]);
;                 g1[k] = (ordf(v1[CT.i[16 + k]] + v2[CT.j[16 + k]]) & ~0xFFu) | (unsigned)(CT.i[16 + k] * 16 + CT.j[16 + k]);
;                 g2[k] = (ordf(v1[CT.i[32 + k]] + v2[CT.j[32 + k]]) & ~0xFFu) | (unsigned)(CT.i[32 + k] * 16 + CT.j[32 + k]); }
;             sort16_desc(L3); sort16_desc(g1); sort16_desc(g2); merge16_desc(L3, g1); merge16_desc(L3, g2);
	v_bitop3_b32 v21, v94, s82, v21 bitop3:0x48
	v_add_f32_e32 v94, v12, v24
	v_ashrrev_i32_e32 v95, 31, v94
	v_add_f32_e32 v24, v13, v24
	v_bitop3_b32 v94, v95, v94, s0 bitop3:0x36
	v_ashrrev_i32_e32 v95, 31, v24
	v_bitop3_b32 v24, v95, v24, s0 bitop3:0x36
	v_add_f32_e32 v95, v3, v23
	v_ashrrev_i32_e32 v96, 31, v95
	v_or_b32_e32 v96, 0x80000000, v96
	v_add_f32_e32 v13, v13, v26
	v_bitop3_b32 v95, v96, s82, v95 bitop3:0x48
	v_add_f32_e32 v96, v12, v26
	v_ashrrev_i32_e32 v26, 31, v13
	v_add_f32_e32 v23, v23, v14
	v_bitop3_b32 v13, v26, v13, s0 bitop3:0x36
	v_ashrrev_i32_e32 v26, 31, v23
	v_or_b32_e32 v26, 0x80000000, v26
	v_bitop3_b32 v23, v26, s82, v23 bitop3:0x48
	v_add_f32_e32 v26, v12, v28
	v_ashrrev_i32_e32 v28, 31, v26
	v_ashrrev_i32_e32 v97, 31, v96
	v_bitop3_b32 v26, v28, v26, s0 bitop3:0x36
	v_add_f32_e32 v28, v3, v15
	v_bitop3_b32 v96, v97, v96, s0 bitop3:0x36
	v_ashrrev_i32_e32 v97, 31, v28
	v_bitop3_b32 v28, v97, v28, s0 bitop3:0x36
	v_add_f32_e32 v97, v3, v25
	v_ashrrev_i32_e32 v98, 31, v97
	v_or_b32_e32 v98, 0x80000000, v98
	v_bitop3_b32 v97, v98, s82, v97 bitop3:0x48
	v_ashrrev_i32_e32 v98, 31, v30
	v_bitop3_b32 v30, v98, v30, s0 bitop3:0x36
	v_add_f32_e32 v98, v15, v14
	v_ashrrev_i32_e32 v99, 31, v98
	v_add_f32_e32 v25, v25, v14
	v_bitop3_b32 v98, v99, v98, s0 bitop3:0x36
	v_ashrrev_i32_e32 v99, 31, v25
	v_or_b32_e32 v99, 0x80000000, v99
	v_bitop3_b32 v25, v99, s82, v25 bitop3:0x48
	v_ashrrev_i32_e32 v99, 31, v70
	v_bitop3_b32 v70, v99, v70, s0 bitop3:0x36
	v_add_f32_e32 v99, v15, v16
	v_ashrrev_i32_e32 v100, 31, v99
	v_add_f32_e32 v27, v3, v27
	v_add_f32_e32 v18, v15, v18
	v_add_f32_e32 v15, v15, v20
	v_bitop3_b32 v99, v100, v99, s0 bitop3:0x36
	v_ashrrev_i32_e32 v100, 31, v27
	v_ashrrev_i32_e32 v20, 31, v15
	v_or_b32_e32 v100, 0x80000000, v100
	v_bitop3_b32 v15, v20, v15, s0 bitop3:0x36
	v_add_f32_e32 v20, v3, v31
	v_bitop3_b32 v27, v100, s82, v27 bitop3:0x48
	v_ashrrev_i32_e32 v100, 31, v72
	v_ashrrev_i32_e32 v31, 31, v20
	v_bitop3_b32 v72, v100, v72, s0 bitop3:0x36
	v_ashrrev_i32_e32 v100, 31, v18
	v_add_f32_e32 v29, v3, v29
	v_or_b32_e32 v31, 0x80000000, v31
	v_bitop3_b32 v18, v100, v18, s0 bitop3:0x36
	v_ashrrev_i32_e32 v100, 31, v29
	v_bitop3_b32 v20, v31, s82, v20 bitop3:0x48
	v_add_f32_e32 v31, v12, v76
	v_or_b32_e32 v100, 0x80000000, v100
	v_ashrrev_i32_e32 v76, 31, v31
	v_bitop3_b32 v29, v100, s82, v29 bitop3:0x48
	v_ashrrev_i32_e32 v100, 31, v74
	v_bitop3_b32 v31, v76, v31, s0 bitop3:0x36
	v_add_f32_e32 v76, v3, v17
	v_cmp_lt_i32_e32 vcc, -1, v6
	v_bitop3_b32 v74, v100, v74, s0 bitop3:0x36
	v_ashrrev_i32_e32 v100, 31, v76
	v_add_f32_e32 v71, v3, v71
	v_cndmask_b32_e64 v78, v182, -1, vcc
	v_bitop3_b32 v76, v100, v76, s0 bitop3:0x36
	v_ashrrev_i32_e32 v100, 31, v71
	v_bitop3_b32 v78, v78, v6, s81 bitop3:0x78
	v_or_b32_e32 v100, 0x80000000, v100
	v_add_f32_e32 v16, v17, v16
	v_bitop3_b32 v71, v100, s82, v71 bitop3:0x48
	v_ashrrev_i32_e32 v100, 31, v77
	v_add_f32_e32 v14, v17, v14
	v_add_f32_e32 v12, v12, v78
	v_ashrrev_i32_e32 v17, 31, v16
	v_bitop3_b32 v77, v100, v77, s0 bitop3:0x36
	v_ashrrev_i32_e32 v100, 31, v14
	v_ashrrev_i32_e32 v78, 31, v12
	v_bitop3_b32 v16, v17, v16, s0 bitop3:0x36
	v_add_f32_e32 v17, v3, v75
	v_bitop3_b32 v14, v100, v14, s0 bitop3:0x36
	v_bitop3_b32 v12, v78, v12, s0 bitop3:0x36
	v_ashrrev_i32_e32 v75, 31, v17
	v_and_or_b32 v80, v80, s82, 16
	v_and_or_b32 v82, v82, s82, 1
	v_and_or_b32 v83, v83, s82, 17
	v_and_or_b32 v85, v85, s82, 2
	v_and_or_b32 v86, v86, s82, 18
	v_and_or_b32 v88, v88, s82, 3
	v_and_or_b32 v89, v89, s82, 19
	v_and_or_b32 v90, v90, s82, 4
	v_and_or_b32 v91, v91, s82, 20
	v_and_or_b32 v93, v93, s82, 5
	v_and_or_b32 v22, v22, s82, 21
	v_and_or_b32 v94, v94, s82, 6
	v_and_or_b32 v24, v24, s82, 22
	v_and_or_b32 v96, v96, s82, 7
	v_and_or_b32 v13, v13, s82, 23
	v_and_or_b32 v26, v26, s82, 8
	v_and_or_b32 v28, v28, s82, 32
	v_and_or_b32 v30, v30, s82, 9
	v_and_or_b32 v98, v98, s82, 33
	v_and_or_b32 v70, v70, s82, 10
	v_and_or_b32 v99, v99, s82, 34
	v_and_or_b32 v72, v72, s82, 11
	v_and_or_b32 v18, v18, s82, 35
	v_and_or_b32 v74, v74, s82, 12
	v_and_or_b32 v15, v15, s82, 36
	v_and_or_b32 v31, v31, s82, 13
	v_and_or_b32 v76, v76, s82, 48
	v_and_or_b32 v77, v77, s82, 14
	v_and_or_b32 v14, v14, s82, 49
	v_and_or_b32 v12, v12, s82, 15
	v_and_or_b32 v16, v16, s82, 50
	v_or_b32_e32 v75, 0x80000000, v75
	v_add_f32_e32 v73, v3, v73
	v_bitop3_b32 v17, v75, s82, v17 bitop3:0x48
	v_max_u32_e32 v75, v79, v82
	v_min_u32_e32 v78, v79, v82
	v_max_u32_e32 v79, v88, v85
	v_min_u32_e32 v82, v88, v85
	v_max_u32_e32 v85, v90, v93
	v_min_u32_e32 v88, v90, v93
	v_max_u32_e32 v90, v96, v94
	v_min_u32_e32 v93, v96, v94
	v_max_u32_e32 v94, v26, v30
	v_min_u32_e32 v26, v26, v30
	v_max_u32_e32 v30, v72, v70
	v_min_u32_e32 v70, v72, v70
	v_max_u32_e32 v72, v74, v31
	v_min_u32_e32 v31, v74, v31
	v_max_u32_e32 v74, v12, v77
	v_min_u32_e32 v12, v12, v77
	v_max_u32_e32 v106, v80, v83
	v_min_u32_e32 v80, v80, v83
	v_max_u32_e32 v83, v89, v86
	v_min_u32_e32 v86, v89, v86
	v_max_u32_e32 v89, v91, v22
	v_min_u32_e32 v22, v91, v22
	v_max_u32_e32 v91, v13, v24
	v_min_u32_e32 v13, v13, v24
	v_max_u32_e32 v24, v28, v98
	v_min_u32_e32 v28, v28, v98
	v_max_u32_e32 v98, v18, v99
	v_min_u32_e32 v18, v18, v99
	v_max_u32_e32 v99, v15, v76
	v_min_u32_e32 v15, v15, v76
	v_max_u32_e32 v76, v16, v14
	v_min_u32_e32 v14, v16, v14
	v_ashrrev_i32_e32 v100, 31, v73
	v_max_u32_e32 v77, v75, v82
	v_min_u32_e32 v75, v75, v82
	v_max_u32_e32 v82, v78, v79
	v_min_u32_e32 v78, v78, v79
	v_max_u32_e32 v79, v93, v85
	v_min_u32_e32 v85, v93, v85
	v_max_u32_e32 v93, v90, v88
	v_min_u32_e32 v88, v90, v88
	v_max_u32_e32 v90, v94, v70
; __device__ __forceinline__ unsigned ordf(float f) { unsigned u = __float_as_uint(f); return u ^ ((unsigned)((int)u >> 31) | 0x80000000u); }
; #define CE_DESC(a, b) do { const unsigned _h = max((a), (b)), _l = min((a), (b)); (a) = _h; (b) = _l; } while (0)
; __device__ __forceinline__ void sort16_desc(unsigned (&v)[16]) {
; #pragma unroll
;     for (int k = 2; k <= 16; k <<= 1)
; #pragma unroll
;         for (int j = k >> 1; j > 0; j >>= 1)
; #pragma unroll
;             for (int i = 0; i < 16; ++i) { const int p = i ^ j; if (p > i) { if ((i & k) == 0) CE_DESC(v[i], v[p]); else CE_DESC(v[p], v[i]); } }
; }
; __device__ __forceinline__ void phase_route(CArgs& A, int l, unsigned char* lds, int tid) {
;     ...
;                 L3[k] = (ordf(v1[CT.i[k]] + v2[CT.j[k]]) & ~0xFFu) | (unsigned)(CT.i[k] * 16 + CT.j[k]);
;                 g1[k] = (ordf(v1[CT.i[16 + k]] + v2[CT.j[16 + k]]) & ~0xFFu) | (unsigned)(CT.i[16 + k] * 16 + CT.j[16 + k]);
;                 g2[k] = (ordf(v1[CT.i[32 + k]] + v2[CT.j[32 + k]]) & ~0xFFu) | (unsigned)(CT.i[32 + k] * 16 + CT.j[32 + k]); }
;             sort16_desc(L3); sort16_desc(g1); sort16_desc(g2); merge16_desc(L3, g1); merge16_desc(L3, g2);
	v_min_u32_e32 v70, v94, v70
	v_max_u32_e32 v94, v26, v30
	v_min_u32_e32 v26, v26, v30
	v_max_u32_e32 v30, v12, v72
	v_min_u32_e32 v12, v12, v72
	v_max_u32_e32 v72, v74, v31
	v_min_u32_e32 v31, v74, v31
	v_max_u32_e32 v16, v106, v86
	v_min_u32_e32 v86, v106, v86
	v_max_u32_e32 v106, v80, v83
	v_min_u32_e32 v80, v80, v83
	v_max_u32_e32 v83, v13, v89
	v_min_u32_e32 v13, v13, v89
	v_max_u32_e32 v89, v91, v22
	v_min_u32_e32 v22, v91, v22
	v_max_u32_e32 v91, v24, v18
	v_min_u32_e32 v18, v24, v18
	v_max_u32_e32 v24, v28, v98
	v_min_u32_e32 v28, v28, v98
	v_max_u32_e32 v98, v14, v99
	v_min_u32_e32 v14, v14, v99
	v_max_u32_e32 v99, v76, v15
	v_min_u32_e32 v15, v76, v15
	v_or_b32_e32 v100, 0x80000000, v100
	v_max_u32_e32 v74, v77, v82
	v_min_u32_e32 v77, v77, v82
	v_max_u32_e32 v82, v75, v78
	v_min_u32_e32 v75, v75, v78
	v_max_u32_e32 v78, v88, v85
	v_min_u32_e32 v85, v88, v85
	v_max_u32_e32 v88, v93, v79
	v_min_u32_e32 v79, v93, v79
	v_max_u32_e32 v93, v90, v94
	v_min_u32_e32 v90, v90, v94
	v_max_u32_e32 v94, v70, v26
	v_min_u32_e32 v26, v70, v26
	v_max_u32_e32 v70, v31, v12
	v_min_u32_e32 v12, v31, v12
	v_max_u32_e32 v31, v72, v30
	v_min_u32_e32 v30, v72, v30
	v_max_u32_e32 v76, v16, v106
	v_min_u32_e32 v16, v16, v106
	v_max_u32_e32 v106, v86, v80
	v_min_u32_e32 v80, v86, v80
	v_max_u32_e32 v86, v22, v13
	v_min_u32_e32 v13, v22, v13
	v_max_u32_e32 v22, v89, v83
	v_min_u32_e32 v83, v89, v83
	v_max_u32_e32 v89, v91, v24
	v_min_u32_e32 v24, v91, v24
	v_max_u32_e32 v91, v18, v28
	v_min_u32_e32 v18, v18, v28
	v_max_u32_e32 v28, v15, v14
	v_min_u32_e32 v14, v15, v14
	v_max_u32_e32 v15, v99, v98
	v_min_u32_e32 v98, v99, v98
	v_bitop3_b32 v73, v100, s82, v73 bitop3:0x48
	v_max_u32_e32 v72, v74, v85
	v_min_u32_e32 v74, v74, v85
	v_max_u32_e32 v85, v77, v78
	v_min_u32_e32 v77, v77, v78
	v_max_u32_e32 v78, v82, v79
	v_min_u32_e32 v79, v82, v79
	v_max_u32_e32 v82, v75, v88
	v_min_u32_e32 v75, v75, v88
	v_max_u32_e32 v88, v12, v93
	v_min_u32_e32 v12, v12, v93
	v_max_u32_e32 v93, v70, v90
	v_min_u32_e32 v70, v70, v90
	v_max_u32_e32 v90, v30, v94
	v_min_u32_e32 v30, v30, v94
	v_max_u32_e32 v94, v31, v26
	v_min_u32_e32 v26, v31, v26
	v_max_u32_e32 v99, v76, v13
	v_min_u32_e32 v13, v76, v13
	v_max_u32_e32 v76, v16, v86
	v_min_u32_e32 v16, v16, v86
	v_max_u32_e32 v86, v106, v83
	v_min_u32_e32 v83, v106, v83
	v_max_u32_e32 v106, v80, v22
	v_min_u32_e32 v22, v80, v22
	v_max_u32_e32 v80, v14, v89
	v_min_u32_e32 v14, v14, v89
	v_max_u32_e32 v89, v28, v24
	v_min_u32_e32 v24, v28, v24
	v_max_u32_e32 v28, v98, v91
	v_min_u32_e32 v91, v98, v91
	v_max_u32_e32 v98, v15, v18
	v_min_u32_e32 v15, v15, v18
	v_and_or_b32 v81, v81, s82, 51
	v_and_or_b32 v84, v84, s82, 64
	v_or_b32_e32 v87, 0x41, v87
	v_or_b32_e32 v19, 0x42, v19
	v_or_b32_e32 v92, 0x50, v92
	v_or_b32_e32 v21, 0x51, v21
	v_or_b32_e32 v95, 0x60, v95
	v_or_b32_e32 v23, 0x61, v23
	v_or_b32_e32 v97, 0x70, v97
	v_or_b32_e32 v25, 0x71, v25
	v_or_b32_e32 v27, 0x80, v27
	v_or_b32_e32 v29, 0x90, v29
	v_or_b32_e32 v20, 0xa0, v20
	v_or_b32_e32 v71, 0xb0, v71
	v_or_b32_e32 v73, 0xc0, v73
	v_or_b32_e32 v17, 0xd0, v17
	v_max_u32_e32 v31, v72, v78
	v_min_u32_e32 v72, v72, v78
	v_max_u32_e32 v78, v85, v82
	v_min_u32_e32 v82, v85, v82
	v_max_u32_e32 v85, v74, v79
	v_min_u32_e32 v74, v74, v79
	v_max_u32_e32 v79, v77, v75
	v_min_u32_e32 v75, v77, v75
	v_max_u32_e32 v77, v30, v12
	v_min_u32_e32 v12, v30, v12
	v_max_u32_e32 v30, v26, v70
	v_min_u32_e32 v26, v26, v70
	v_max_u32_e32 v70, v90, v88
	v_min_u32_e32 v88, v90, v88
	v_max_u32_e32 v90, v94, v93
	v_min_u32_e32 v93, v94, v93
	v_max_u32_e32 v18, v99, v86
	v_min_u32_e32 v86, v99, v86
	v_max_u32_e32 v99, v76, v106
	v_min_u32_e32 v76, v76, v106
	v_max_u32_e32 v106, v13, v83
	v_min_u32_e32 v13, v13, v83
	v_max_u32_e32 v83, v16, v22
	v_min_u32_e32 v16, v16, v22
	v_max_u32_e32 v22, v91, v14
	v_min_u32_e32 v14, v91, v14
	v_max_u32_e32 v91, v15, v24
	v_min_u32_e32 v15, v15, v24
	v_max_u32_e32 v24, v28, v80
	v_min_u32_e32 v28, v28, v80
	v_max_u32_e32 v80, v98, v89
	v_min_u32_e32 v89, v98, v89
	v_max_u32_e32 v94, v31, v78
	v_min_u32_e32 v31, v31, v78
	v_max_u32_e32 v78, v72, v82
	v_min_u32_e32 v72, v72, v82
	v_max_u32_e32 v82, v85, v79
	v_min_u32_e32 v79, v85, v79
	v_max_u32_e32 v85, v74, v75
	v_min_u32_e32 v74, v74, v75
	v_max_u32_e32 v75, v26, v12
	v_min_u32_e32 v12, v26, v12
	v_max_u32_e32 v26, v30, v77
	v_min_u32_e32 v30, v30, v77
	v_max_u32_e32 v77, v93, v88
	v_min_u32_e32 v88, v93, v88
	v_max_u32_e32 v93, v90, v70
	v_min_u32_e32 v70, v90, v70
	v_max_u32_e32 v98, v18, v99
	v_min_u32_e32 v18, v18, v99
	v_max_u32_e32 v99, v86, v76
	v_min_u32_e32 v76, v86, v76
	v_max_u32_e32 v86, v106, v83
	v_min_u32_e32 v83, v106, v83
	v_max_u32_e32 v106, v13, v16
	v_min_u32_e32 v13, v13, v16
	v_max_u32_e32 v16, v15, v14
	v_min_u32_e32 v14, v15, v14
	v_max_u32_e32 v15, v91, v22
	v_min_u32_e32 v22, v91, v22
	v_max_u32_e32 v91, v89, v28
	v_min_u32_e32 v28, v89, v28
	v_max_u32_e32 v89, v80, v24
	v_min_u32_e32 v24, v80, v24
	v_max_u32_e32 v114, v81, v84
	v_min_u32_e32 v81, v81, v84
	v_max_u32_e32 v84, v19, v87
	v_min_u32_e32 v19, v19, v87
	v_max_u32_e32 v87, v92, v21
	v_min_u32_e32 v21, v92, v21
	v_max_u32_e32 v92, v23, v95
	v_min_u32_e32 v23, v23, v95
	v_max_u32_e32 v95, v97, v25
	v_min_u32_e32 v25, v97, v25
	v_max_u32_e32 v97, v29, v27
	v_min_u32_e32 v27, v29, v27
	v_max_u32_e32 v29, v20, v71
	v_min_u32_e32 v20, v20, v71
	v_max_u32_e32 v71, v17, v73
	v_min_u32_e32 v17, v17, v73
	v_max_u32_e32 v90, v94, v12
	v_min_u32_e32 v12, v94, v12
	v_max_u32_e32 v94, v31, v75
	v_min_u32_e32 v31, v31, v75
	v_max_u32_e32 v75, v78, v30
	v_min_u32_e32 v30, v78, v30
	v_max_u32_e32 v78, v72, v26
	v_min_u32_e32 v26, v72, v26
; #define CE_DESC(a, b) do { const unsigned _h = max((a), (b)), _l = min((a), (b)); (a) = _h; (b) = _l; } while (0)
; __device__ __forceinline__ void sort16_desc(unsigned (&v)[16]) {
; #pragma unroll
;     for (int k = 2; k <= 16; k <<= 1)
; #pragma unroll
;         for (int j = k >> 1; j > 0; j >>= 1)
; #pragma unroll
;             for (int i = 0; i < 16; ++i) { const int p = i ^ j; if (p > i) { if ((i & k) == 0) CE_DESC(v[i], v[p]); else CE_DESC(v[p], v[i]); } }
; }
; __device__ __forceinline__ void merge16_desc(unsigned (&a)[16], const unsigned (&b)[16]) {
; #pragma unroll
;     for (int i = 0; i < 16; ++i) a[i] = max(a[i], b[15 - i]);
; #pragma unroll
;     for (int j = 8; j > 0; j >>= 1)
; #pragma unroll
;         for (int i = 0; i < 16; ++i) { const int p = i ^ j; if (p > i) CE_DESC(a[i], a[p]); }
; }
; __device__ __forceinline__ void phase_route(CArgs& A, int l, unsigned char* lds, int tid) {
;     ...
;             sort16_desc(L3); sort16_desc(g1); sort16_desc(g2); merge16_desc(L3, g1); merge16_desc(L3, g2);
	v_max_u32_e32 v72, v82, v88
	v_min_u32_e32 v82, v82, v88
	v_max_u32_e32 v88, v79, v77
	v_min_u32_e32 v77, v79, v77
	v_max_u32_e32 v79, v85, v70
	v_min_u32_e32 v70, v85, v70
	v_max_u32_e32 v85, v74, v93
	v_min_u32_e32 v74, v74, v93
	v_max_u32_e32 v80, v98, v14
	v_min_u32_e32 v14, v98, v14
	v_max_u32_e32 v98, v18, v16
	v_min_u32_e32 v16, v18, v16
	v_max_u32_e32 v18, v99, v22
	v_min_u32_e32 v22, v99, v22
	v_max_u32_e32 v99, v76, v15
	v_min_u32_e32 v15, v76, v15
	v_max_u32_e32 v76, v86, v28
	v_min_u32_e32 v28, v86, v28
	v_max_u32_e32 v86, v83, v91
	v_min_u32_e32 v83, v83, v91
	v_max_u32_e32 v91, v106, v24
	v_min_u32_e32 v24, v106, v24
	v_max_u32_e32 v106, v13, v89
	v_min_u32_e32 v13, v13, v89
	v_max_u32_e32 v73, v114, v19
	v_min_u32_e32 v19, v114, v19
	v_max_u32_e32 v114, v81, v84
	v_min_u32_e32 v81, v81, v84
	v_max_u32_e32 v84, v23, v87
	v_min_u32_e32 v23, v23, v87
	v_max_u32_e32 v87, v92, v21
	v_min_u32_e32 v21, v92, v21
	v_max_u32_e32 v92, v95, v27
	v_min_u32_e32 v27, v95, v27
	v_max_u32_e32 v95, v25, v97
	v_min_u32_e32 v25, v25, v97
	v_max_u32_e32 v97, v17, v29
	v_min_u32_e32 v17, v17, v29
	v_max_u32_e32 v29, v71, v20
	v_min_u32_e32 v20, v71, v20
	v_max_u32_e32 v93, v90, v72
	v_min_u32_e32 v72, v90, v72
	v_max_u32_e32 v90, v94, v88
	v_min_u32_e32 v88, v94, v88
	v_max_u32_e32 v94, v75, v79
	v_min_u32_e32 v75, v75, v79
	v_max_u32_e32 v79, v78, v85
	v_min_u32_e32 v78, v78, v85
	v_max_u32_e32 v85, v12, v82
	v_min_u32_e32 v12, v12, v82
	v_max_u32_e32 v82, v31, v77
	v_min_u32_e32 v31, v31, v77
	v_max_u32_e32 v77, v30, v70
	v_min_u32_e32 v30, v30, v70
	v_max_u32_e32 v70, v26, v74
	v_min_u32_e32 v26, v26, v74
	v_max_u32_e32 v89, v80, v76
	v_min_u32_e32 v76, v80, v76
	v_max_u32_e32 v80, v98, v86
	v_min_u32_e32 v86, v98, v86
	v_max_u32_e32 v98, v18, v91
	v_min_u32_e32 v18, v18, v91
	v_max_u32_e32 v91, v99, v106
	v_min_u32_e32 v99, v99, v106
	v_max_u32_e32 v106, v14, v28
	v_min_u32_e32 v14, v14, v28
	v_max_u32_e32 v28, v16, v83
	v_min_u32_e32 v16, v16, v83
	v_max_u32_e32 v83, v22, v24
	v_min_u32_e32 v22, v22, v24
	v_max_u32_e32 v24, v15, v13
	v_min_u32_e32 v13, v15, v13
	v_max_u32_e32 v71, v73, v114
	v_min_u32_e32 v73, v73, v114
	v_max_u32_e32 v114, v19, v81
	v_min_u32_e32 v19, v19, v81
	v_max_u32_e32 v81, v21, v23
	v_min_u32_e32 v21, v21, v23
	v_max_u32_e32 v23, v87, v84
	v_min_u32_e32 v84, v87, v84
	v_max_u32_e32 v87, v92, v95
	v_min_u32_e32 v92, v92, v95
	v_max_u32_e32 v95, v27, v25
	v_min_u32_e32 v25, v27, v25
	v_max_u32_e32 v27, v20, v17
	v_min_u32_e32 v17, v20, v17
	v_max_u32_e32 v20, v29, v97
	v_min_u32_e32 v29, v29, v97
	v_max_u32_e32 v74, v93, v94
	v_min_u32_e32 v93, v93, v94
	v_max_u32_e32 v94, v90, v79
	v_min_u32_e32 v79, v90, v79
	v_max_u32_e32 v90, v72, v75
	v_min_u32_e32 v72, v72, v75
	v_max_u32_e32 v75, v88, v78
	v_min_u32_e32 v78, v88, v78
	v_max_u32_e32 v88, v85, v77
	v_min_u32_e32 v77, v85, v77
	v_max_u32_e32 v85, v82, v70
	v_min_u32_e32 v70, v82, v70
	v_max_u32_e32 v82, v12, v30
	v_min_u32_e32 v12, v12, v30
	v_max_u32_e32 v30, v31, v26
	v_min_u32_e32 v26, v31, v26
	v_max_u32_e32 v15, v89, v98
	v_min_u32_e32 v89, v89, v98
	v_max_u32_e32 v98, v80, v91
	v_min_u32_e32 v80, v80, v91
	v_max_u32_e32 v91, v76, v18
	v_min_u32_e32 v18, v76, v18
	v_max_u32_e32 v76, v86, v99
	v_min_u32_e32 v86, v86, v99
	v_max_u32_e32 v99, v106, v83
	v_min_u32_e32 v83, v106, v83
	v_max_u32_e32 v106, v28, v24
	v_min_u32_e32 v24, v28, v24
	v_max_u32_e32 v28, v14, v22
	v_min_u32_e32 v14, v14, v22
	v_max_u32_e32 v22, v16, v13
	v_min_u32_e32 v13, v16, v13
	v_max_u32_e32 v97, v71, v21
	v_min_u32_e32 v21, v71, v21
	v_max_u32_e32 v71, v73, v81
	v_min_u32_e32 v73, v73, v81
	v_max_u32_e32 v81, v114, v84
	v_min_u32_e32 v84, v114, v84
	v_max_u32_e32 v114, v19, v23
	v_min_u32_e32 v19, v19, v23
	v_max_u32_e32 v23, v17, v87
	v_min_u32_e32 v17, v17, v87
	v_max_u32_e32 v87, v27, v92
	v_min_u32_e32 v27, v27, v92
	v_max_u32_e32 v92, v29, v95
	v_min_u32_e32 v29, v29, v95
	v_max_u32_e32 v95, v20, v25
	v_min_u32_e32 v20, v20, v25
	v_min_u32_e32 v31, v74, v94
	v_min_u32_e32 v96, v93, v79
	v_min_u32_e32 v100, v90, v75
	v_min_u32_e32 v101, v72, v78
	v_min_u32_e32 v102, v88, v85
	v_min_u32_e32 v103, v77, v70
	v_min_u32_e32 v104, v82, v30
	v_min_u32_e32 v105, v12, v26
	v_min_u32_e32 v16, v15, v98
	v_min_u32_e32 v107, v89, v80
	v_min_u32_e32 v108, v91, v76
	v_min_u32_e32 v109, v18, v86
	v_min_u32_e32 v110, v99, v106
	v_min_u32_e32 v111, v83, v24
	v_min_u32_e32 v112, v28, v22
	v_min_u32_e32 v113, v14, v13
	v_max_u32_e32 v25, v97, v81
	v_min_u32_e32 v81, v97, v81
	v_max_u32_e32 v97, v71, v114
	v_min_u32_e32 v71, v71, v114
	v_max_u32_e32 v114, v21, v84
	v_min_u32_e32 v21, v21, v84
	v_max_u32_e32 v84, v73, v19
	v_min_u32_e32 v19, v73, v19
	v_max_u32_e32 v73, v29, v17
	v_min_u32_e32 v17, v29, v17
	v_max_u32_e32 v29, v20, v27
	v_min_u32_e32 v20, v20, v27
	v_max_u32_e32 v27, v92, v23
	v_min_u32_e32 v23, v92, v23
	v_max_u32_e32 v92, v95, v87
	v_min_u32_e32 v87, v95, v87
	v_max_u32_e32 v95, v25, v97
	v_min_u32_e32 v25, v25, v97
	v_max_u32_e32 v97, v81, v71
	v_min_u32_e32 v71, v81, v71
	v_max_u32_e32 v81, v114, v84
	v_min_u32_e32 v84, v114, v84
	v_max_u32_e32 v114, v21, v19
	v_min_u32_e32 v19, v21, v19
	v_max_u32_e32 v21, v20, v17
	v_min_u32_e32 v17, v20, v17
	v_max_u32_e32 v20, v29, v73
	v_min_u32_e32 v29, v29, v73
	v_max_u32_e32 v73, v87, v23
	v_min_u32_e32 v23, v87, v23
	v_max_u32_e32 v87, v92, v27
	v_min_u32_e32 v27, v92, v27
	v_max3_u32 v74, v74, v94, v113
	v_max3_u32 v13, v31, v14, v13
	v_max3_u32 v14, v93, v79, v112
	v_max3_u32 v22, v96, v28, v22
	v_max3_u32 v28, v90, v75, v111
	v_max3_u32 v24, v100, v83, v24
	v_max3_u32 v31, v72, v78, v110
	v_max3_u32 v72, v101, v99, v106
; __device__ __forceinline__ unsigned ordf(float f) { unsigned u = __float_as_uint(f); return u ^ ((unsigned)((int)u >> 31) | 0x80000000u); }
; #define INSERT16(L, key) do { unsigned _k = (key); _Pragma("unroll") for (int _j = 0; _j < 16; ++_j) { const unsigned _hi = max(L[_j], _k); _k = min(L[_j], _k); L[_j] = _hi; } } while (0)
; #define CE_DESC(a, b) do { const unsigned _h = max((a), (b)), _l = min((a), (b)); (a) = _h; (b) = _l; } while (0)
; __device__ __forceinline__ void merge16_desc(unsigned (&a)[16], const unsigned (&b)[16]) {
; #pragma unroll
;     for (int i = 0; i < 16; ++i) a[i] = max(a[i], b[15 - i]);
; #pragma unroll
;     for (int j = 8; j > 0; j >>= 1)
; #pragma unroll
;         for (int i = 0; i < 16; ++i) { const int p = i ^ j; if (p > i) CE_DESC(a[i], a[p]); }
; }
; __device__ __forceinline__ void phase_route(CArgs& A, int l, unsigned char* lds, int tid) {
;     ...
;             sort16_desc(L3); sort16_desc(g1); sort16_desc(g2); merge16_desc(L3, g1); merge16_desc(L3, g2);
;             INSERT16(L3, (ordf(v1[CT.i[48]] + v2[CT.j[48]]) & ~0xFFu) | (unsigned)(CT.i[48] * 16 + CT.j[48]));
	v_max3_u32 v75, v88, v85, v109
	v_max3_u32 v18, v102, v18, v86
	v_max3_u32 v70, v77, v70, v108
	v_max3_u32 v76, v103, v91, v76
	v_max3_u32 v30, v82, v30, v107
	v_max3_u32 v77, v104, v89, v80
	v_max3_u32 v12, v12, v26, v16
	v_max3_u32 v15, v105, v15, v98
	v_max_u32_e32 v92, v95, v17
	v_min_u32_e32 v17, v95, v17
	v_max_u32_e32 v95, v25, v21
	v_min_u32_e32 v21, v25, v21
	v_max_u32_e32 v25, v97, v29
	v_min_u32_e32 v29, v97, v29
	v_max_u32_e32 v97, v71, v20
	v_min_u32_e32 v20, v71, v20
	v_max_u32_e32 v71, v81, v23
	v_min_u32_e32 v23, v81, v23
	v_max_u32_e32 v81, v84, v73
	v_min_u32_e32 v73, v84, v73
	v_max_u32_e32 v84, v114, v27
	v_min_u32_e32 v27, v114, v27
	v_max_u32_e32 v114, v19, v87
	v_min_u32_e32 v19, v19, v87
	v_max_u32_e32 v16, v74, v75
	v_min_u32_e32 v26, v74, v75
	v_max_u32_e32 v74, v13, v18
	v_min_u32_e32 v13, v13, v18
	v_max_u32_e32 v18, v14, v70
	v_min_u32_e32 v14, v14, v70
	v_max_u32_e32 v70, v22, v76
	v_min_u32_e32 v22, v22, v76
	v_max_u32_e32 v75, v28, v30
	v_min_u32_e32 v28, v28, v30
	v_max_u32_e32 v30, v24, v77
	v_min_u32_e32 v24, v24, v77
	v_max_u32_e32 v76, v31, v12
	v_min_u32_e32 v12, v31, v12
	v_max_u32_e32 v31, v72, v15
	v_min_u32_e32 v15, v72, v15
	v_max_u32_e32 v87, v92, v71
	v_min_u32_e32 v71, v92, v71
	v_max_u32_e32 v92, v95, v81
	v_min_u32_e32 v81, v95, v81
	v_max_u32_e32 v95, v25, v84
	v_min_u32_e32 v25, v25, v84
	v_max_u32_e32 v84, v97, v114
	v_min_u32_e32 v97, v97, v114
	v_max_u32_e32 v114, v17, v23
	v_min_u32_e32 v17, v17, v23
	v_max_u32_e32 v23, v21, v73
	v_min_u32_e32 v21, v21, v73
	v_max_u32_e32 v73, v29, v27
	v_min_u32_e32 v27, v29, v27
	v_max_u32_e32 v29, v20, v19
	v_min_u32_e32 v19, v20, v19
	v_max_u32_e32 v72, v16, v75
	v_min_u32_e32 v16, v16, v75
	v_max_u32_e32 v75, v74, v30
	v_min_u32_e32 v30, v74, v30
	v_max_u32_e32 v74, v18, v76
	v_min_u32_e32 v18, v18, v76
	v_max_u32_e32 v76, v70, v31
	v_min_u32_e32 v31, v70, v31
	v_max_u32_e32 v70, v26, v28
	v_min_u32_e32 v26, v26, v28
	v_max_u32_e32 v28, v13, v24
	v_min_u32_e32 v13, v13, v24
	v_max_u32_e32 v24, v14, v12
	v_min_u32_e32 v12, v14, v12
	v_max_u32_e32 v14, v22, v15
	v_min_u32_e32 v15, v22, v15
	v_max_u32_e32 v20, v87, v95
	v_min_u32_e32 v87, v87, v95
	v_max_u32_e32 v95, v92, v84
	v_min_u32_e32 v84, v92, v84
	v_max_u32_e32 v92, v71, v25
	v_min_u32_e32 v25, v71, v25
	v_max_u32_e32 v71, v81, v97
	v_min_u32_e32 v81, v81, v97
	v_max_u32_e32 v97, v114, v73
	v_min_u32_e32 v73, v114, v73
	v_max_u32_e32 v114, v23, v29
	v_min_u32_e32 v23, v23, v29
	v_max_u32_e32 v29, v17, v27
	v_min_u32_e32 v17, v17, v27
	v_max_u32_e32 v27, v21, v19
	v_min_u32_e32 v19, v21, v19
	v_max_u32_e32 v22, v72, v74
	v_min_u32_e32 v72, v72, v74
	v_max_u32_e32 v74, v75, v76
	v_min_u32_e32 v75, v75, v76
	v_max_u32_e32 v76, v16, v18
	v_min_u32_e32 v16, v16, v18
	v_max_u32_e32 v18, v30, v31
	v_min_u32_e32 v30, v30, v31
	v_max_u32_e32 v31, v70, v24
	v_min_u32_e32 v24, v70, v24
	v_max_u32_e32 v70, v28, v14
	v_min_u32_e32 v14, v28, v14
	v_max_u32_e32 v28, v26, v12
	v_min_u32_e32 v12, v26, v12
	v_max_u32_e32 v26, v13, v15
	v_min_u32_e32 v13, v13, v15
	v_min_u32_e32 v21, v20, v95
	v_min_u32_e32 v115, v87, v84
	v_min_u32_e32 v116, v92, v71
	v_min_u32_e32 v117, v25, v81
	v_min_u32_e32 v118, v97, v114
	v_min_u32_e32 v119, v73, v23
	v_min_u32_e32 v120, v29, v27
	v_min_u32_e32 v121, v17, v19
	v_min_u32_e32 v15, v22, v74
	v_min_u32_e32 v77, v72, v75
	v_min_u32_e32 v78, v76, v18
	v_min_u32_e32 v79, v16, v30
	v_min_u32_e32 v80, v31, v70
	v_min_u32_e32 v82, v24, v14
	v_min_u32_e32 v83, v28, v26
	v_min_u32_e32 v85, v12, v13
	v_max3_u32 v22, v22, v74, v121
	v_max3_u32 v15, v15, v17, v19
	v_max3_u32 v17, v72, v75, v120
	v_max3_u32 v19, v77, v29, v27
	v_max3_u32 v18, v76, v18, v119
	v_max3_u32 v23, v78, v73, v23
	v_max3_u32 v16, v16, v30, v118
	v_max3_u32 v27, v79, v97, v114
	v_max3_u32 v29, v31, v70, v117
	v_max3_u32 v25, v80, v25, v81
	v_max3_u32 v14, v24, v14, v116
	v_max3_u32 v24, v82, v92, v71
	v_max3_u32 v26, v28, v26, v115
	v_max3_u32 v28, v83, v87, v84
	v_max3_u32 v12, v12, v13, v21
	v_max3_u32 v13, v85, v20, v95
	v_max_u32_e32 v20, v22, v29
	v_min_u32_e32 v21, v22, v29
	v_max_u32_e32 v22, v15, v25
	v_min_u32_e32 v15, v15, v25
	v_max_u32_e32 v25, v17, v14
	v_min_u32_e32 v14, v17, v14
	v_max_u32_e32 v17, v19, v24
	v_min_u32_e32 v19, v19, v24
	v_max_u32_e32 v24, v18, v26
	v_min_u32_e32 v18, v18, v26
	v_max_u32_e32 v26, v23, v28
	v_min_u32_e32 v23, v23, v28
	v_max_u32_e32 v28, v16, v12
	v_min_u32_e32 v12, v16, v12
	v_max_u32_e32 v16, v27, v13
	v_min_u32_e32 v13, v27, v13
	v_max_u32_e32 v27, v20, v24
	v_min_u32_e32 v20, v20, v24
	v_max_u32_e32 v24, v22, v26
	v_min_u32_e32 v22, v22, v26
	v_max_u32_e32 v26, v25, v28
	v_min_u32_e32 v25, v25, v28
	v_max_u32_e32 v28, v17, v16
	v_min_u32_e32 v16, v17, v16
	v_max_u32_e32 v17, v21, v18
	v_min_u32_e32 v18, v21, v18
	v_max_u32_e32 v21, v15, v23
	v_min_u32_e32 v15, v15, v23
	v_max_u32_e32 v23, v14, v12
	v_min_u32_e32 v12, v14, v12
	v_max_u32_e32 v14, v19, v13
	v_min_u32_e32 v13, v19, v13
	v_max_u32_e32 v19, v27, v26
	v_min_u32_e32 v26, v27, v26
	v_max_u32_e32 v27, v24, v28
	v_min_u32_e32 v24, v24, v28
	v_max_u32_e32 v28, v20, v25
	v_min_u32_e32 v20, v20, v25
	v_max_u32_e32 v25, v22, v16
	v_min_u32_e32 v16, v22, v16
	v_max_u32_e32 v22, v17, v23
	v_min_u32_e32 v17, v17, v23
	v_max_u32_e32 v23, v21, v14
	v_min_u32_e32 v14, v21, v14
	v_max_u32_e32 v21, v18, v12
	v_min_u32_e32 v12, v18, v12
	v_max_u32_e32 v18, v15, v13
	v_min_u32_e32 v13, v15, v13
	v_add_f32_e32 v10, v3, v10
	v_max_u32_e32 v80, v12, v13
	v_min_u32_e32 v12, v12, v13
	v_ashrrev_i32_e32 v13, 31, v10
	v_or_b32_e32 v13, 0x80000000, v13
	v_bitop3_b32 v10, v13, s82, v10 bitop3:0x48
	v_max_u32_e32 v15, v19, v27
; __device__ __forceinline__ unsigned ordf(float f) { unsigned u = __float_as_uint(f); return u ^ ((unsigned)((int)u >> 31) | 0x80000000u); }
; __device__ __forceinline__ float unordf(unsigned v) { return __uint_as_float(v ^ ((~(unsigned)((int)v >> 31)) | 0x80000000u)); }
; #define INSERT16(L, key) do { unsigned _k = (key); _Pragma("unroll") for (int _j = 0; _j < 16; ++_j) { const unsigned _hi = max(L[_j], _k); _k = min(L[_j], _k); L[_j] = _hi; } } while (0)
; __device__ __forceinline__ void phase_route(CArgs& A, int l, unsigned char* lds, int tid) {
;     ...
;             INSERT16(L3, (ordf(v1[CT.i[48]] + v2[CT.j[48]]) & ~0xFFu) | (unsigned)(CT.i[48] * 16 + CT.j[48]));
;             INSERT16(L3, (ordf(v1[CT.i[49]] + v2[CT.j[49]]) & ~0xFFu) | (unsigned)(CT.i[49] * 16 + CT.j[49]));
;             static_assert(CT.i[49] >= 0 && CT.i[50] < 0, "50 candidates");
;         }
;         float e[16], sum = 0.f; const float mx = unordf(L3[0] & ~0xFFu);
; #pragma unroll
;         for (int k = 0; k < 16; ++k) { e[k] = expf(unordf(L3[k] & ~0xFFu) - mx); sum += e[k]; }
	v_or_b32_e32 v10, 0xe0, v10
	v_min_u32_e32 v29, v19, v27
	v_max_u32_e32 v13, v15, v10
	v_min_u32_e32 v15, v15, v10
	v_max_u32_e32 v30, v26, v24
	v_min_u32_e32 v15, v29, v15
	v_min_u32_e32 v31, v26, v24
	v_med3_u32 v10, v19, v27, v10
	v_min_u32_e32 v27, v30, v15
	v_max_u32_e32 v70, v28, v25
	v_max_u32_e32 v19, v30, v15
	v_med3_u32 v15, v26, v24, v15
	v_min_u32_e32 v24, v31, v27
	v_min_u32_e32 v71, v28, v25
	v_min_u32_e32 v27, v70, v24
	v_max_u32_e32 v72, v20, v16
	v_max_u32_e32 v26, v70, v24
	v_med3_u32 v24, v28, v25, v24
	v_min_u32_e32 v25, v71, v27
	v_pk_add_f32 v[2:3], v[2:3], v[2:3] op_sel:[1,0] op_sel_hi:[0,1]
	v_min_u32_e32 v73, v20, v16
	v_min_u32_e32 v28, v72, v25
	v_ashrrev_i32_e32 v3, 31, v2
	v_max_u32_e32 v74, v22, v23
	v_med3_u32 v16, v20, v16, v25
	v_min_u32_e32 v20, v73, v28
	v_or_b32_e32 v3, 0x80000000, v3
	v_min_u32_e32 v75, v22, v23
	v_min_u32_e32 v28, v74, v20
	v_bitop3_b32 v2, v3, s82, v2 bitop3:0x48
	v_max_u32_e32 v76, v17, v14
	v_max_u32_e32 v27, v72, v25
	v_max_u32_e32 v25, v74, v20
	v_med3_u32 v20, v22, v23, v20
	v_min_u32_e32 v22, v75, v28
	v_or_b32_e32 v2, 0xf0, v2
	v_min_u32_e32 v77, v17, v14
	v_min_u32_e32 v28, v76, v22
	v_max_u32_e32 v73, v13, v2
	v_min_u32_e32 v2, v13, v2
	v_max_u32_e32 v78, v21, v18
	v_med3_u32 v14, v17, v14, v22
	v_min_u32_e32 v17, v77, v28
	v_max_u32_e32 v74, v10, v2
	v_min_u32_e32 v2, v10, v2
	v_min_u32_e32 v79, v21, v18
	v_max_u32_e32 v23, v76, v22
	v_min_u32_e32 v28, v78, v17
	v_max_u32_e32 v76, v19, v2
	v_min_u32_e32 v2, v19, v2
	v_max_u32_e32 v22, v78, v17
	v_med3_u32 v17, v21, v18, v17
	v_min_u32_e32 v18, v79, v28
	v_max_u32_e32 v78, v15, v2
	v_min_u32_e32 v2, v15, v2
	v_max_u32_e32 v21, v80, v18
	v_min_u32_e32 v18, v80, v18
	v_max_u32_e32 v80, v26, v2
	v_min_u32_e32 v2, v26, v2
	v_max_u32_e32 v82, v24, v2
	v_min_u32_e32 v2, v24, v2
	v_max_u32_e32 v83, v27, v2
	v_min_u32_e32 v2, v27, v2
	v_max_u32_e32 v84, v16, v2
	v_min_u32_e32 v2, v16, v2
	v_max_u32_e32 v75, v25, v2
	v_min_u32_e32 v2, v25, v2
	v_cmp_lt_i32_e32 vcc, -1, v73
	v_max_u32_e32 v77, v20, v2
	v_min_u32_e32 v2, v20, v2
	v_cndmask_b32_e64 v13, v182, -1, vcc
	v_max_u32_e32 v79, v23, v2
	v_min_u32_e32 v2, v23, v2
	v_bitop3_b32 v13, v13, v73, s82 bitop3:0x78
	v_max_u32_e32 v81, v14, v2
	v_min_u32_e32 v3, v14, v2
	v_sub_f32_e32 v14, v13, v13
	v_min_u32_e32 v10, v22, v3
	v_mul_f32_e32 v15, 0x3fb8aa3b, v14
	v_max_u32_e32 v2, v22, v3
	v_max_u32_e32 v3, v17, v10
	v_min_u32_e32 v10, v17, v10
	v_fma_f32 v16, v14, s83, -v15
	v_rndne_f32_e32 v17, v15
	v_fmac_f32_e32 v16, 0x32a5705f, v14
	v_sub_f32_e32 v15, v15, v17
	v_add_f32_e32 v15, v15, v16
	v_exp_f32_e32 v15, v15
	v_cvt_i32_f32_e32 v16, v17
	v_max_u32_e32 v85, v21, v10
	v_min_u32_e32 v10, v21, v10
	v_cmp_lt_i32_e32 vcc, -1, v74
	v_max3_u32 v86, v12, v18, v10
	v_ldexp_f32 v10, v15, v16
	v_cndmask_b32_e64 v12, v182, -1, vcc
	v_bitop3_b32 v12, v12, v74, s82 bitop3:0x78
	v_sub_f32_e32 v12, v12, v13
	v_mul_f32_e32 v15, 0x3fb8aa3b, v12
	v_fma_f32 v16, v12, s83, -v15
	v_rndne_f32_e32 v17, v15
	v_fmac_f32_e32 v16, 0x32a5705f, v12
	v_sub_f32_e32 v15, v15, v17
	v_add_f32_e32 v15, v15, v16
	v_exp_f32_e32 v15, v15
	v_cvt_i32_f32_e32 v17, v17
	v_cmp_ngt_f32_e32 vcc, s76, v14
	v_and_b32_e32 v6, 0x7f, v6
	v_and_b32_e32 v45, 0x7f, v45
	v_cndmask_b32_e32 v10, 0, v10, vcc
	v_cmp_nlt_f32_e32 vcc, s77, v14
	v_and_b32_e32 v46, 0x7f, v46
	v_and_b32_e32 v48, 0x7f, v48
	v_cndmask_b32_e32 v16, v181, v10, vcc
	v_ldexp_f32 v10, v15, v17
	v_cmp_ngt_f32_e32 vcc, s76, v12
	v_and_b32_e32 v49, 0x7f, v49
	v_and_b32_e32 v50, 0x7f, v50
	v_cndmask_b32_e32 v10, 0, v10, vcc
	v_cmp_lt_i32_e32 vcc, -1, v76
	v_and_b32_e32 v51, 0x7f, v51
	v_and_b32_e32 v52, 0x7f, v52
	v_cndmask_b32_e64 v14, v182, -1, vcc
	v_bitop3_b32 v14, v14, v76, s82 bitop3:0x78
	v_sub_f32_e32 v14, v14, v13
	v_mul_f32_e32 v15, 0x3fb8aa3b, v14
	v_fma_f32 v17, v14, s83, -v15
	v_rndne_f32_e32 v18, v15
	v_fmac_f32_e32 v17, 0x32a5705f, v14
	v_sub_f32_e32 v15, v15, v18
	v_add_f32_e32 v15, v15, v17
	v_exp_f32_e32 v15, v15
	v_cvt_i32_f32_e32 v18, v18
	v_cmp_nlt_f32_e32 vcc, s77, v12
	v_and_b32_e32 v53, 0x7f, v53
	v_and_b32_e32 v67, 0x7f, v67
	v_cndmask_b32_e32 v17, v181, v10, vcc
	v_ldexp_f32 v12, v15, v18
	v_cmp_ngt_f32_e32 vcc, s76, v14
	v_add_f32_e32 v10, v16, v17
	v_and_b32_e32 v69, 0x7f, v69
	v_cndmask_b32_e32 v12, 0, v12, vcc
	v_cmp_lt_i32_e32 vcc, -1, v78
	v_and_b32_e32 v71, 0x7f, v9
	v_and_b32_e32 v72, 0x7f, v4
	v_cndmask_b32_e64 v15, v182, -1, vcc
	v_bitop3_b32 v15, v15, v78, s82 bitop3:0x78
	v_sub_f32_e32 v15, v15, v13
	v_mul_f32_e32 v18, 0x3fb8aa3b, v15
	v_fma_f32 v19, v15, s83, -v18
	v_rndne_f32_e32 v20, v18
	v_fmac_f32_e32 v19, 0x32a5705f, v15
	v_sub_f32_e32 v18, v18, v20
	v_add_f32_e32 v18, v18, v19
	v_exp_f32_e32 v19, v18
	v_cvt_i32_f32_e32 v20, v20
	v_cmp_nlt_f32_e32 vcc, s77, v14
	s_nop 1
	v_cndmask_b32_e32 v18, v181, v12, vcc
	v_ldexp_f32 v12, v19, v20
	v_cmp_ngt_f32_e32 vcc, s76, v15
	v_add_f32_e32 v10, v10, v18
	s_nop 0
	v_cndmask_b32_e32 v12, 0, v12, vcc
	v_cmp_lt_i32_e32 vcc, -1, v80
	s_nop 1
	v_cndmask_b32_e64 v14, v182, -1, vcc
	v_bitop3_b32 v14, v14, v80, s82 bitop3:0x78
	v_sub_f32_e32 v14, v14, v13
	v_mul_f32_e32 v19, 0x3fb8aa3b, v14
	v_fma_f32 v20, v14, s83, -v19
	v_rndne_f32_e32 v21, v19
	v_fmac_f32_e32 v20, 0x32a5705f, v14
	v_sub_f32_e32 v19, v19, v21
	v_add_f32_e32 v19, v19, v20
	v_exp_f32_e32 v20, v19
	v_cvt_i32_f32_e32 v21, v21
	v_cmp_nlt_f32_e32 vcc, s77, v15
	s_nop 1
	v_cndmask_b32_e32 v19, v181, v12, vcc
	v_ldexp_f32 v12, v20, v21
	v_cmp_ngt_f32_e32 vcc, s76, v14
	v_add_f32_e32 v10, v10, v19
	s_nop 0
	v_cndmask_b32_e32 v12, 0, v12, vcc
	v_cmp_lt_i32_e32 vcc, -1, v82
	s_nop 1
	v_cndmask_b32_e64 v15, v182, -1, vcc
; __device__ __forceinline__ float unordf(unsigned v) { return __uint_as_float(v ^ ((~(unsigned)((int)v >> 31)) | 0x80000000u)); }
; __device__ __forceinline__ void phase_route(CArgs& A, int l, unsigned char* lds, int tid) {
;     ...
;         float e[16], sum = 0.f; const float mx = unordf(L3[0] & ~0xFFu);
; #pragma unroll
;         for (int k = 0; k < 16; ++k) { e[k] = expf(unordf(L3[k] & ~0xFFu) - mx); sum += e[k]; }
	v_bitop3_b32 v15, v15, v82, s82 bitop3:0x78
	v_sub_f32_e32 v15, v15, v13
	v_mul_f32_e32 v20, 0x3fb8aa3b, v15
	v_fma_f32 v21, v15, s83, -v20
	v_rndne_f32_e32 v22, v20
	v_fmac_f32_e32 v21, 0x32a5705f, v15
	v_sub_f32_e32 v20, v20, v22
	v_add_f32_e32 v20, v20, v21
	v_exp_f32_e32 v21, v20
	v_cvt_i32_f32_e32 v22, v22
	v_cmp_nlt_f32_e32 vcc, s77, v14
	s_nop 1
	v_cndmask_b32_e32 v20, v181, v12, vcc
	v_ldexp_f32 v12, v21, v22
	v_cmp_ngt_f32_e32 vcc, s76, v15
	v_add_f32_e32 v10, v10, v20
	s_nop 0
	v_cndmask_b32_e32 v12, 0, v12, vcc
	v_cmp_lt_i32_e32 vcc, -1, v83
	s_nop 1
	v_cndmask_b32_e64 v14, v182, -1, vcc
	v_bitop3_b32 v14, v14, v83, s82 bitop3:0x78
	v_sub_f32_e32 v14, v14, v13
	v_mul_f32_e32 v21, 0x3fb8aa3b, v14
	v_fma_f32 v22, v14, s83, -v21
	v_rndne_f32_e32 v23, v21
	v_fmac_f32_e32 v22, 0x32a5705f, v14
	v_sub_f32_e32 v21, v21, v23
	v_add_f32_e32 v21, v21, v22
	v_exp_f32_e32 v22, v21
	v_cvt_i32_f32_e32 v23, v23
	v_cmp_nlt_f32_e32 vcc, s77, v15
	s_nop 1
	v_cndmask_b32_e32 v21, v181, v12, vcc
	v_ldexp_f32 v12, v22, v23
	v_cmp_ngt_f32_e32 vcc, s76, v14
	v_add_f32_e32 v10, v10, v21
	s_nop 0
	v_cndmask_b32_e32 v12, 0, v12, vcc
	v_cmp_lt_i32_e32 vcc, -1, v84
	s_nop 1
	v_cndmask_b32_e64 v15, v182, -1, vcc
	v_bitop3_b32 v15, v15, v84, s82 bitop3:0x78
	v_sub_f32_e32 v15, v15, v13
	v_mul_f32_e32 v22, 0x3fb8aa3b, v15
	v_fma_f32 v23, v15, s83, -v22
	v_rndne_f32_e32 v24, v22
	v_fmac_f32_e32 v23, 0x32a5705f, v15
	v_sub_f32_e32 v22, v22, v24
	v_add_f32_e32 v22, v22, v23
	v_exp_f32_e32 v23, v22
	v_cvt_i32_f32_e32 v24, v24
	v_cmp_nlt_f32_e32 vcc, s77, v14
	s_nop 1
	v_cndmask_b32_e32 v22, v181, v12, vcc
	v_ldexp_f32 v12, v23, v24
	v_cmp_ngt_f32_e32 vcc, s76, v15
	v_add_f32_e32 v10, v10, v22
	s_nop 0
	v_cndmask_b32_e32 v12, 0, v12, vcc
	v_cmp_lt_i32_e32 vcc, -1, v75
	s_nop 1
	v_cndmask_b32_e64 v14, v182, -1, vcc
	v_bitop3_b32 v14, v14, v75, s82 bitop3:0x78
	v_sub_f32_e32 v14, v14, v13
	v_mul_f32_e32 v23, 0x3fb8aa3b, v14
	v_fma_f32 v24, v14, s83, -v23
	v_rndne_f32_e32 v25, v23
	v_fmac_f32_e32 v24, 0x32a5705f, v14
	v_sub_f32_e32 v23, v23, v25
	v_add_f32_e32 v23, v23, v24
	v_exp_f32_e32 v24, v23
	v_cvt_i32_f32_e32 v25, v25
	v_cmp_nlt_f32_e32 vcc, s77, v15
	s_nop 1
	v_cndmask_b32_e32 v23, v181, v12, vcc
	v_ldexp_f32 v12, v24, v25
	v_cmp_ngt_f32_e32 vcc, s76, v14
	v_add_f32_e32 v10, v10, v23
	s_nop 0
	v_cndmask_b32_e32 v12, 0, v12, vcc
	v_cmp_lt_i32_e32 vcc, -1, v77
	s_nop 1
	v_cndmask_b32_e64 v15, v182, -1, vcc
	v_bitop3_b32 v15, v15, v77, s82 bitop3:0x78
	v_sub_f32_e32 v15, v15, v13
	v_mul_f32_e32 v24, 0x3fb8aa3b, v15
	v_fma_f32 v25, v15, s83, -v24
	v_rndne_f32_e32 v26, v24
	v_fmac_f32_e32 v25, 0x32a5705f, v15
	v_sub_f32_e32 v24, v24, v26
	v_add_f32_e32 v24, v24, v25
	v_exp_f32_e32 v25, v24
	v_cvt_i32_f32_e32 v26, v26
	v_cmp_nlt_f32_e32 vcc, s77, v14
	s_nop 1
	v_cndmask_b32_e32 v24, v181, v12, vcc
	v_ldexp_f32 v12, v25, v26
	v_cmp_ngt_f32_e32 vcc, s76, v15
	v_add_f32_e32 v10, v10, v24
	s_nop 0
	v_cndmask_b32_e32 v12, 0, v12, vcc
	v_cmp_lt_i32_e32 vcc, -1, v79
	s_nop 1
	v_cndmask_b32_e64 v14, v182, -1, vcc
	v_bitop3_b32 v14, v14, v79, s82 bitop3:0x78
	v_sub_f32_e32 v14, v14, v13
	v_mul_f32_e32 v25, 0x3fb8aa3b, v14
	v_fma_f32 v26, v14, s83, -v25
	v_rndne_f32_e32 v27, v25
	v_fmac_f32_e32 v26, 0x32a5705f, v14
	v_sub_f32_e32 v25, v25, v27
	v_add_f32_e32 v25, v25, v26
	v_exp_f32_e32 v26, v25
	v_cvt_i32_f32_e32 v27, v27
	v_cmp_nlt_f32_e32 vcc, s77, v15
	s_nop 1
	v_cndmask_b32_e32 v25, v181, v12, vcc
	v_ldexp_f32 v12, v26, v27
	v_cmp_ngt_f32_e32 vcc, s76, v14
	v_add_f32_e32 v10, v10, v25
	s_nop 0
	v_cndmask_b32_e32 v12, 0, v12, vcc
	v_cmp_lt_i32_e32 vcc, -1, v81
	s_nop 1
	v_cndmask_b32_e64 v15, v182, -1, vcc
	v_bitop3_b32 v15, v15, v81, s82 bitop3:0x78
	v_sub_f32_e32 v15, v15, v13
	v_mul_f32_e32 v26, 0x3fb8aa3b, v15
	v_fma_f32 v27, v15, s83, -v26
	v_rndne_f32_e32 v28, v26
	v_fmac_f32_e32 v27, 0x32a5705f, v15
	v_sub_f32_e32 v26, v26, v28
	v_add_f32_e32 v26, v26, v27
	v_exp_f32_e32 v27, v26
	v_cvt_i32_f32_e32 v28, v28
	v_cmp_nlt_f32_e32 vcc, s77, v14
	s_nop 1
	v_cndmask_b32_e32 v26, v181, v12, vcc
	v_ldexp_f32 v12, v27, v28
	v_cmp_ngt_f32_e32 vcc, s76, v15
	v_add_f32_e32 v10, v10, v26
	s_nop 0
	v_cndmask_b32_e32 v12, 0, v12, vcc
	v_cmp_lt_i32_e32 vcc, -1, v2
	s_nop 1
	v_cndmask_b32_e64 v14, v182, -1, vcc
	v_bitop3_b32 v14, v14, v2, s82 bitop3:0x78
	v_sub_f32_e32 v14, v14, v13
	v_mul_f32_e32 v27, 0x3fb8aa3b, v14
	v_fma_f32 v28, v14, s83, -v27
	v_rndne_f32_e32 v29, v27
	v_fmac_f32_e32 v28, 0x32a5705f, v14
	v_sub_f32_e32 v27, v27, v29
	v_add_f32_e32 v27, v27, v28
	v_exp_f32_e32 v28, v27
	v_cvt_i32_f32_e32 v29, v29
	v_cmp_nlt_f32_e32 vcc, s77, v15
	s_nop 1
	v_cndmask_b32_e32 v27, v181, v12, vcc
	v_ldexp_f32 v12, v28, v29
	v_cmp_ngt_f32_e32 vcc, s76, v14
	v_add_f32_e32 v10, v10, v27
	s_nop 0
	v_cndmask_b32_e32 v12, 0, v12, vcc
	v_cmp_lt_i32_e32 vcc, -1, v3
	s_nop 1
	v_cndmask_b32_e64 v15, v182, -1, vcc
	v_bitop3_b32 v15, v15, v3, s82 bitop3:0x78
	v_sub_f32_e32 v15, v15, v13
	v_mul_f32_e32 v28, 0x3fb8aa3b, v15
	v_fma_f32 v29, v15, s83, -v28
	v_rndne_f32_e32 v30, v28
	v_fmac_f32_e32 v29, 0x32a5705f, v15
	v_sub_f32_e32 v28, v28, v30
	v_add_f32_e32 v28, v28, v29
	v_exp_f32_e32 v29, v28
	v_cvt_i32_f32_e32 v30, v30
	v_cmp_nlt_f32_e32 vcc, s77, v14
	s_nop 1
	v_cndmask_b32_e32 v28, v181, v12, vcc
	v_ldexp_f32 v12, v29, v30
	v_cmp_ngt_f32_e32 vcc, s76, v15
	v_add_f32_e32 v10, v10, v28
	s_nop 0
	v_cndmask_b32_e32 v12, 0, v12, vcc
	v_cmp_lt_i32_e32 vcc, -1, v85
	s_nop 1
	v_cndmask_b32_e64 v14, v182, -1, vcc
	v_bitop3_b32 v14, v14, v85, s82 bitop3:0x78
	v_sub_f32_e32 v14, v14, v13
	v_mul_f32_e32 v29, 0x3fb8aa3b, v14
	v_fma_f32 v30, v14, s83, -v29
	v_rndne_f32_e32 v31, v29
; __device__ __forceinline__ float unordf(unsigned v) { return __uint_as_float(v ^ ((~(unsigned)((int)v >> 31)) | 0x80000000u)); }
; __device__ __forceinline__ void phase_route(CArgs& A, int l, unsigned char* lds, int tid) {
;     ...
;         float e[16], sum = 0.f; const float mx = unordf(L3[0] & ~0xFFu);
; #pragma unroll
;         for (int k = 0; k < 16; ++k) { e[k] = expf(unordf(L3[k] & ~0xFFu) - mx); sum += e[k]; }
;         const float inv = 1.f / sum;
;         int ex[16];
; #pragma unroll
;         for (int k = 0; k < 16; ++k) { const unsigned ci = L3[k] & 0xFFu, i = ci >> 4, j = ci & 15u; unsigned e1 = 0u, e2 = 0u;
; #pragma unroll
;             for (int ii = 0; ii < 16; ++ii) { e1 = (i == (unsigned)ii) ? (L1[ii] & 0x7Fu) : e1; e2 = (j == (unsigned)ii) ? (L2[ii] & 0x7Fu) : e2; }
;             ex[k] = (int)(e1 * 128u + e2); e[k] *= inv; }
;         int* ip = IDX + (size_t)t * 128 + hd * 16; float* gp = GATE + (size_t)t * 128 + hd * 16;
;         if (hf == 0) {
;             *(int4*)ip = make_int4(ex[0], ex[1], ex[2], ex[3]); *(int4*)(ip + 4) = make_int4(ex[4], ex[5], ex[6], ex[7]);
;             *(f32x4*)gp = (f32x4){e[0], e[1], e[2], e[3]}; *(f32x4*)(gp + 4) = (f32x4){e[4], e[5], e[6], e[7]};
;         } else {
;             *(int4*)(ip + 8) = make_int4(ex[8], ex[9], ex[10], ex[11]); *(int4*)(ip + 12) = make_int4(ex[12], ex[13], ex[14], ex[15]);
;             *(f32x4*)(gp + 8) = (f32x4){e[8], e[9], e[10], e[11]}; *(f32x4*)(gp + 12) = (f32x4){e[12], e[13], e[14], e[15]};
	v_fmac_f32_e32 v30, 0x32a5705f, v14
	v_sub_f32_e32 v29, v29, v31
	v_add_f32_e32 v29, v29, v30
	v_exp_f32_e32 v30, v29
	v_cvt_i32_f32_e32 v31, v31
	v_cmp_nlt_f32_e32 vcc, s77, v15
	s_nop 1
	v_cndmask_b32_e32 v29, v181, v12, vcc
	v_ldexp_f32 v12, v30, v31
	v_cmp_ngt_f32_e32 vcc, s76, v14
	v_add_f32_e32 v10, v10, v29
	s_nop 0
	v_cndmask_b32_e32 v12, 0, v12, vcc
	v_cmp_lt_i32_e32 vcc, -1, v86
	s_nop 1
	v_cndmask_b32_e64 v15, v182, -1, vcc
	v_bitop3_b32 v15, v15, v86, s82 bitop3:0x78
	v_sub_f32_e32 v13, v15, v13
	v_mul_f32_e32 v15, 0x3fb8aa3b, v13
	v_fma_f32 v30, v13, s83, -v15
	v_rndne_f32_e32 v31, v15
	v_fmac_f32_e32 v30, 0x32a5705f, v13
	v_sub_f32_e32 v15, v15, v31
	v_add_f32_e32 v15, v15, v30
	v_exp_f32_e32 v15, v15
	v_cvt_i32_f32_e32 v31, v31
	v_cmp_nlt_f32_e32 vcc, s77, v14
	s_nop 1
	v_cndmask_b32_e32 v30, v181, v12, vcc
	v_ldexp_f32 v12, v15, v31
	v_cmp_ngt_f32_e32 vcc, s76, v13
	v_add_f32_e32 v10, v10, v30
	s_nop 0
	v_cndmask_b32_e32 v12, 0, v12, vcc
	v_cmp_nlt_f32_e32 vcc, s77, v13
	s_nop 1
	v_cndmask_b32_e32 v31, v181, v12, vcc
	v_add_f32_e32 v10, v10, v31
	v_div_scale_f32 v12, s[0:1], v10, v10, 1.0
	v_rcp_f32_e32 v13, v12
	s_nop 0
	v_fma_f32 v14, -v12, v13, 1.0
	v_fmac_f32_e32 v13, v14, v13
	v_div_scale_f32 v14, vcc, 1.0, v10, 1.0
	v_mul_f32_e32 v15, v14, v13
	v_fma_f32 v70, -v12, v15, v14
	v_fmac_f32_e32 v15, v70, v13
	v_fma_f32 v12, -v12, v15, v14
	v_div_fmas_f32 v12, v12, v13, v15
	v_div_fixup_f32 v10, v12, v10, 1.0
	v_lshlrev_b64 v[12:13], 9, v[60:61]
	v_lshl_add_u64 v[14:15], v[54:55], 0, v[12:13]
	v_lshl_add_u64 v[12:13], v[56:57], 0, v[12:13]
	v_and_b32_e32 v60, 0x7f, v68
	v_and_b32_e32 v61, 0x7f, v8
	v_and_b32_e32 v68, 0x7f, v7
	v_and_b32_e32 v70, 0x7f, v5
	s_and_saveexec_b64 s[0:1], s[40:41]
	s_xor_b64 s[4:5], exec, s[0:1]
	s_cbranch_execz .LBB0_137
	v_and_b32_e32 v4, 15, v86
	v_cmp_eq_u32_e32 vcc, 0, v4
	v_mov_b64_e32 v[22:23], v[30:31]
	v_mov_b64_e32 v[20:21], v[28:29]
	v_cndmask_b32_e32 v5, 0, v45, vcc
	v_cmp_eq_u32_e64 s[98:99], 1, v4
	v_cmp_eq_u32_e32 vcc, 2, v4
	v_cmp_eq_u32_e64 s[100:101], 3, v4
	v_cndmask_b32_e64 v5, v5, v44, s[98:99]
	v_cmp_eq_u32_e64 s[98:99], 4, v4
	v_cndmask_b32_e32 v5, v5, v43, vcc
	v_cmp_eq_u32_e32 vcc, 5, v4
	v_cndmask_b32_e64 v5, v5, v42, s[100:101]
	v_cmp_eq_u32_e64 s[100:101], 6, v4
	v_cndmask_b32_e64 v5, v5, v41, s[98:99]
	v_cmp_eq_u32_e64 s[98:99], 7, v4
	v_cndmask_b32_e32 v5, v5, v40, vcc
	v_cmp_eq_u32_e32 vcc, 8, v4
	v_cndmask_b32_e64 v5, v5, v39, s[100:101]
	v_cmp_eq_u32_e64 s[100:101], 9, v4
	v_cndmask_b32_e64 v5, v5, v38, s[98:99]
	v_cmp_eq_u32_e64 s[98:99], 10, v4
	v_cndmask_b32_e32 v5, v5, v37, vcc
	v_cmp_eq_u32_e32 vcc, 11, v4
	v_cndmask_b32_e64 v5, v5, v36, s[100:101]
	v_cmp_eq_u32_e64 s[100:101], 12, v4
	v_cndmask_b32_e64 v5, v5, v35, s[98:99]
	v_cmp_eq_u32_e64 s[98:99], 13, v4
	v_cndmask_b32_e32 v5, v5, v34, vcc
	v_cmp_eq_u32_e32 vcc, 14, v4
	v_cndmask_b32_e64 v5, v5, v33, s[100:101]
	v_cndmask_b32_e64 v5, v5, v32, s[98:99]
	v_cndmask_b32_e32 v5, v5, v11, vcc
	v_cmp_eq_u32_e32 vcc, 15, v4
	v_bfe_u32 v4, v86, 4, 4
	s_nop 0
	v_cndmask_b32_e32 v5, v5, v6, vcc
	v_cmp_eq_u32_e64 s[100:101], 0, v4
	v_cmp_eq_u32_e64 s[98:99], 1, v4
	v_cmp_eq_u32_e32 vcc, 2, v4
	v_cndmask_b32_e64 v7, 0, v72, s[100:101]
	v_cmp_eq_u32_e64 s[100:101], 3, v4
	v_cndmask_b32_e64 v7, v7, v71, s[98:99]
	v_cmp_eq_u32_e64 s[98:99], 4, v4
	v_cndmask_b32_e32 v7, v7, v70, vcc
	v_cmp_eq_u32_e32 vcc, 5, v4
	v_cndmask_b32_e64 v7, v7, v69, s[100:101]
	v_cmp_eq_u32_e64 s[100:101], 6, v4
	v_cndmask_b32_e64 v7, v7, v68, s[98:99]
	v_cmp_eq_u32_e64 s[98:99], 7, v4
	v_cndmask_b32_e32 v7, v7, v67, vcc
	v_cmp_eq_u32_e32 vcc, 8, v4
	v_cndmask_b32_e64 v7, v7, v61, s[100:101]
	v_cmp_eq_u32_e64 s[100:101], 9, v4
	v_cndmask_b32_e64 v7, v7, v60, s[98:99]
	v_cmp_eq_u32_e64 s[98:99], 10, v4
	v_cndmask_b32_e32 v7, v7, v53, vcc
	v_cmp_eq_u32_e32 vcc, 11, v4
	v_cndmask_b32_e64 v7, v7, v52, s[100:101]
	v_cmp_eq_u32_e64 s[100:101], 12, v4
	v_cndmask_b32_e64 v7, v7, v51, s[98:99]
	v_cmp_eq_u32_e64 s[98:99], 13, v4
	v_cndmask_b32_e32 v7, v7, v50, vcc
	v_cmp_eq_u32_e32 vcc, 14, v4
	v_cndmask_b32_e64 v7, v7, v49, s[100:101]
	v_cndmask_b32_e64 v7, v7, v48, s[98:99]
	v_cndmask_b32_e32 v7, v7, v47, vcc
	v_cmp_eq_u32_e32 vcc, 15, v4
	v_bfe_u32 v4, v85, 4, 4
	s_nop 0
	v_cndmask_b32_e32 v16, v7, v46, vcc
	v_cmp_eq_u32_e32 vcc, 0, v4
	v_lshl_add_u32 v5, v16, 7, v5
	s_nop 0
	v_cndmask_b32_e32 v7, 0, v72, vcc
	v_cmp_eq_u32_e64 s[100:101], 1, v4
	v_cmp_eq_u32_e64 s[98:99], 2, v4
	v_cmp_eq_u32_e32 vcc, 3, v4
	v_cndmask_b32_e64 v7, v7, v71, s[100:101]
	v_cmp_eq_u32_e64 s[100:101], 4, v4
	v_cndmask_b32_e64 v7, v7, v70, s[98:99]
	v_cmp_eq_u32_e64 s[98:99], 5, v4
	v_cndmask_b32_e32 v7, v7, v69, vcc
	v_cmp_eq_u32_e32 vcc, 6, v4
	v_cndmask_b32_e64 v7, v7, v68, s[100:101]
	v_cmp_eq_u32_e64 s[100:101], 7, v4
	v_cndmask_b32_e64 v7, v7, v67, s[98:99]
	v_cmp_eq_u32_e64 s[98:99], 8, v4
	v_cndmask_b32_e32 v7, v7, v61, vcc
	v_cmp_eq_u32_e32 vcc, 9, v4
	v_cndmask_b32_e64 v7, v7, v60, s[100:101]
	v_cmp_eq_u32_e64 s[100:101], 10, v4
	v_cndmask_b32_e64 v7, v7, v53, s[98:99]
	v_cmp_eq_u32_e64 s[98:99], 11, v4
	v_cndmask_b32_e32 v7, v7, v52, vcc
	v_cmp_eq_u32_e32 vcc, 12, v4
	v_cndmask_b32_e64 v7, v7, v51, s[100:101]
	v_cmp_eq_u32_e64 s[100:101], 13, v4
	v_cndmask_b32_e64 v7, v7, v50, s[98:99]
	v_cmp_eq_u32_e64 s[98:99], 14, v4
	v_cndmask_b32_e32 v7, v7, v49, vcc
	v_cmp_eq_u32_e32 vcc, 15, v4
	v_cndmask_b32_e64 v7, v7, v48, s[100:101]
	v_cndmask_b32_e64 v7, v7, v47, s[98:99]
	v_cndmask_b32_e32 v4, v7, v46, vcc
	v_and_b32_e32 v7, 15, v85
	v_cmp_eq_u32_e32 vcc, 0, v7
	v_cmp_eq_u32_e64 s[100:101], 1, v7
	v_cmp_eq_u32_e64 s[98:99], 2, v7
	v_cndmask_b32_e32 v8, 0, v45, vcc
; __device__ __forceinline__ void phase_route(CArgs& A, int l, unsigned char* lds, int tid) {
;     ...
;         for (int k = 0; k < 16; ++k) { const unsigned ci = L3[k] & 0xFFu, i = ci >> 4, j = ci & 15u; unsigned e1 = 0u, e2 = 0u;
; #pragma unroll
;             for (int ii = 0; ii < 16; ++ii) { e1 = (i == (unsigned)ii) ? (L1[ii] & 0x7Fu) : e1; e2 = (j == (unsigned)ii) ? (L2[ii] & 0x7Fu) : e2; }
;             ex[k] = (int)(e1 * 128u + e2); e[k] *= inv; }
	v_cmp_eq_u32_e32 vcc, 3, v7
	v_cndmask_b32_e64 v8, v8, v44, s[100:101]
	v_cmp_eq_u32_e64 s[100:101], 4, v7
	v_cndmask_b32_e64 v8, v8, v43, s[98:99]
	v_cmp_eq_u32_e64 s[98:99], 5, v7
	v_cndmask_b32_e32 v8, v8, v42, vcc
	v_cmp_eq_u32_e32 vcc, 6, v7
	v_cndmask_b32_e64 v8, v8, v41, s[100:101]
	v_cmp_eq_u32_e64 s[100:101], 7, v7
	v_cndmask_b32_e64 v8, v8, v40, s[98:99]
	v_cmp_eq_u32_e64 s[98:99], 8, v7
	v_cndmask_b32_e32 v8, v8, v39, vcc
	v_cmp_eq_u32_e32 vcc, 9, v7
	v_cndmask_b32_e64 v8, v8, v38, s[100:101]
	v_cmp_eq_u32_e64 s[100:101], 10, v7
	v_cndmask_b32_e64 v8, v8, v37, s[98:99]
	v_cmp_eq_u32_e64 s[98:99], 11, v7
	v_cndmask_b32_e32 v8, v8, v36, vcc
	v_cmp_eq_u32_e32 vcc, 12, v7
	v_cndmask_b32_e64 v8, v8, v35, s[100:101]
	v_cmp_eq_u32_e64 s[100:101], 13, v7
	v_cndmask_b32_e64 v8, v8, v34, s[98:99]
	v_cmp_eq_u32_e64 s[98:99], 14, v7
	v_cndmask_b32_e32 v8, v8, v33, vcc
	v_cmp_eq_u32_e32 vcc, 15, v7
	v_cndmask_b32_e64 v8, v8, v32, s[100:101]
	v_cndmask_b32_e64 v8, v8, v11, s[98:99]
	v_cndmask_b32_e32 v7, v8, v6, vcc
	v_lshl_add_u32 v4, v4, 7, v7
	v_bfe_u32 v7, v3, 4, 4
	v_cmp_eq_u32_e32 vcc, 0, v7
	v_and_b32_e32 v3, 15, v3
	s_nop 0
	v_cndmask_b32_e32 v8, 0, v72, vcc
	v_cmp_eq_u32_e32 vcc, 1, v7
	v_cmp_eq_u32_e64 s[100:101], 2, v7
	v_cmp_eq_u32_e64 s[98:99], 3, v7
	v_cndmask_b32_e32 v8, v8, v71, vcc
	v_cmp_eq_u32_e32 vcc, 4, v7
	v_cndmask_b32_e64 v8, v8, v70, s[100:101]
	v_cmp_eq_u32_e64 s[100:101], 5, v7
	v_cndmask_b32_e64 v8, v8, v69, s[98:99]
	v_cmp_eq_u32_e64 s[98:99], 6, v7
	v_cndmask_b32_e32 v8, v8, v68, vcc
	v_cmp_eq_u32_e32 vcc, 7, v7
	v_cndmask_b32_e64 v8, v8, v67, s[100:101]
	v_cmp_eq_u32_e64 s[100:101], 8, v7
	v_cndmask_b32_e64 v8, v8, v61, s[98:99]
	v_cmp_eq_u32_e64 s[98:99], 9, v7
	v_cndmask_b32_e32 v8, v8, v60, vcc
	v_cmp_eq_u32_e32 vcc, 10, v7
	v_cndmask_b32_e64 v8, v8, v53, s[100:101]
	v_cmp_eq_u32_e64 s[100:101], 11, v7
	v_cndmask_b32_e64 v8, v8, v52, s[98:99]
	v_cmp_eq_u32_e64 s[98:99], 12, v7
	v_cndmask_b32_e32 v8, v8, v51, vcc
	v_cmp_eq_u32_e32 vcc, 13, v7
	v_cndmask_b32_e64 v8, v8, v50, s[100:101]
	v_cmp_eq_u32_e64 s[100:101], 14, v7
	v_cndmask_b32_e64 v8, v8, v49, s[98:99]
	v_cmp_eq_u32_e64 s[98:99], 15, v7
	v_cndmask_b32_e32 v8, v8, v48, vcc
	v_cmp_eq_u32_e32 vcc, 0, v3
	v_cndmask_b32_e64 v8, v8, v47, s[100:101]
	v_cmp_eq_u32_e64 s[100:101], 1, v3
	v_cndmask_b32_e64 v7, v8, v46, s[98:99]
	v_cmp_eq_u32_e64 s[98:99], 2, v3
	v_cndmask_b32_e32 v8, 0, v45, vcc
	v_cmp_eq_u32_e32 vcc, 3, v3
	v_cndmask_b32_e64 v8, v8, v44, s[100:101]
	v_cmp_eq_u32_e64 s[100:101], 4, v3
	v_cndmask_b32_e64 v8, v8, v43, s[98:99]
	v_cmp_eq_u32_e64 s[98:99], 5, v3
	v_cndmask_b32_e32 v8, v8, v42, vcc
	v_cmp_eq_u32_e32 vcc, 6, v3
	v_cndmask_b32_e64 v8, v8, v41, s[100:101]
	v_cmp_eq_u32_e64 s[100:101], 7, v3
	v_cndmask_b32_e64 v8, v8, v40, s[98:99]
	v_cmp_eq_u32_e64 s[98:99], 8, v3
	v_cndmask_b32_e32 v8, v8, v39, vcc
	v_cmp_eq_u32_e32 vcc, 9, v3
	v_cndmask_b32_e64 v8, v8, v38, s[100:101]
	v_cmp_eq_u32_e64 s[100:101], 10, v3
	v_cndmask_b32_e64 v8, v8, v37, s[98:99]
	v_cmp_eq_u32_e64 s[98:99], 11, v3
	v_cndmask_b32_e32 v8, v8, v36, vcc
	v_cmp_eq_u32_e32 vcc, 12, v3
	v_cndmask_b32_e64 v8, v8, v35, s[100:101]
	v_cmp_eq_u32_e64 s[100:101], 13, v3
	v_cndmask_b32_e64 v8, v8, v34, s[98:99]
	v_cmp_eq_u32_e64 s[98:99], 14, v3
	v_cndmask_b32_e32 v8, v8, v33, vcc
	v_cmp_eq_u32_e32 vcc, 15, v3
	v_cndmask_b32_e64 v8, v8, v32, s[100:101]
	v_cndmask_b32_e64 v8, v8, v11, s[98:99]
	v_cndmask_b32_e32 v3, v8, v6, vcc
	v_lshl_add_u32 v3, v7, 7, v3
	v_bfe_u32 v7, v2, 4, 4
	v_cmp_eq_u32_e32 vcc, 0, v7
	v_and_b32_e32 v2, 15, v2
	s_nop 0
	v_cndmask_b32_e32 v8, 0, v72, vcc
	v_cmp_eq_u32_e32 vcc, 1, v7
	v_cmp_eq_u32_e64 s[100:101], 2, v7
	v_cmp_eq_u32_e64 s[98:99], 3, v7
	v_cndmask_b32_e32 v8, v8, v71, vcc
	v_cmp_eq_u32_e32 vcc, 4, v7
	v_cndmask_b32_e64 v8, v8, v70, s[100:101]
	v_cmp_eq_u32_e64 s[100:101], 5, v7
	v_cndmask_b32_e64 v8, v8, v69, s[98:99]
	v_cmp_eq_u32_e64 s[98:99], 6, v7
	v_cndmask_b32_e32 v8, v8, v68, vcc
	v_cmp_eq_u32_e32 vcc, 7, v7
	v_cndmask_b32_e64 v8, v8, v67, s[100:101]
	v_cmp_eq_u32_e64 s[100:101], 8, v7
	v_cndmask_b32_e64 v8, v8, v61, s[98:99]
	v_cmp_eq_u32_e64 s[98:99], 9, v7
	v_cndmask_b32_e32 v8, v8, v60, vcc
	v_cmp_eq_u32_e32 vcc, 10, v7
	v_cndmask_b32_e64 v8, v8, v53, s[100:101]
	v_cmp_eq_u32_e64 s[100:101], 11, v7
	v_cndmask_b32_e64 v8, v8, v52, s[98:99]
	v_cmp_eq_u32_e64 s[98:99], 12, v7
	v_cndmask_b32_e32 v8, v8, v51, vcc
	v_cmp_eq_u32_e32 vcc, 13, v7
	v_cndmask_b32_e64 v8, v8, v50, s[100:101]
	v_cmp_eq_u32_e64 s[100:101], 14, v7
	v_cndmask_b32_e64 v8, v8, v49, s[98:99]
	v_cmp_eq_u32_e64 s[98:99], 15, v7
	v_cndmask_b32_e32 v8, v8, v48, vcc
	v_cmp_eq_u32_e32 vcc, 0, v2
	v_cndmask_b32_e64 v8, v8, v47, s[100:101]
	v_cmp_eq_u32_e64 s[100:101], 1, v2
	v_cndmask_b32_e64 v7, v8, v46, s[98:99]
	v_cmp_eq_u32_e64 s[98:99], 2, v2
	v_cndmask_b32_e32 v8, 0, v45, vcc
	v_cmp_eq_u32_e32 vcc, 3, v2
	v_cndmask_b32_e64 v8, v8, v44, s[100:101]
	v_cmp_eq_u32_e64 s[100:101], 4, v2
	v_cndmask_b32_e64 v8, v8, v43, s[98:99]
	v_cmp_eq_u32_e64 s[98:99], 5, v2
	v_cndmask_b32_e32 v8, v8, v42, vcc
	v_cmp_eq_u32_e32 vcc, 6, v2
	v_cndmask_b32_e64 v8, v8, v41, s[100:101]
	v_cmp_eq_u32_e64 s[100:101], 7, v2
	v_cndmask_b32_e64 v8, v8, v40, s[98:99]
	v_cmp_eq_u32_e64 s[98:99], 8, v2
	v_cndmask_b32_e32 v8, v8, v39, vcc
	v_cmp_eq_u32_e32 vcc, 9, v2
	v_cndmask_b32_e64 v8, v8, v38, s[100:101]
	v_cmp_eq_u32_e64 s[100:101], 10, v2
	v_cndmask_b32_e64 v8, v8, v37, s[98:99]
	v_cmp_eq_u32_e64 s[98:99], 11, v2
	v_cndmask_b32_e32 v8, v8, v36, vcc
	v_cmp_eq_u32_e32 vcc, 12, v2
	v_cndmask_b32_e64 v8, v8, v35, s[100:101]
	v_cmp_eq_u32_e64 s[100:101], 13, v2
	v_cndmask_b32_e64 v8, v8, v34, s[98:99]
; __device__ __forceinline__ void phase_route(CArgs& A, int l, unsigned char* lds, int tid) {
;     ...
;         for (int k = 0; k < 16; ++k) { const unsigned ci = L3[k] & 0xFFu, i = ci >> 4, j = ci & 15u; unsigned e1 = 0u, e2 = 0u;
; #pragma unroll
;             for (int ii = 0; ii < 16; ++ii) { e1 = (i == (unsigned)ii) ? (L1[ii] & 0x7Fu) : e1; e2 = (j == (unsigned)ii) ? (L2[ii] & 0x7Fu) : e2; }
;             ex[k] = (int)(e1 * 128u + e2); e[k] *= inv; }
	v_cmp_eq_u32_e64 s[98:99], 14, v2
	v_cndmask_b32_e32 v8, v8, v33, vcc
	v_cmp_eq_u32_e32 vcc, 15, v2
	v_cndmask_b32_e64 v8, v8, v32, s[100:101]
	v_cndmask_b32_e64 v8, v8, v11, s[98:99]
	v_cndmask_b32_e32 v2, v8, v6, vcc
	v_lshl_add_u32 v2, v7, 7, v2
	v_bfe_u32 v7, v81, 4, 4
	v_cmp_eq_u32_e32 vcc, 0, v7
	v_cmp_eq_u32_e64 s[100:101], 1, v7
	v_cmp_eq_u32_e64 s[98:99], 2, v7
	v_cndmask_b32_e32 v8, 0, v72, vcc
	v_cmp_eq_u32_e32 vcc, 3, v7
	v_cndmask_b32_e64 v8, v8, v71, s[100:101]
	v_cmp_eq_u32_e64 s[100:101], 4, v7
	v_cndmask_b32_e64 v8, v8, v70, s[98:99]
	v_cmp_eq_u32_e64 s[98:99], 5, v7
	v_cndmask_b32_e32 v8, v8, v69, vcc
	v_cmp_eq_u32_e32 vcc, 6, v7
	v_cndmask_b32_e64 v8, v8, v68, s[100:101]
	v_cmp_eq_u32_e64 s[100:101], 7, v7
	v_cndmask_b32_e64 v8, v8, v67, s[98:99]
	v_cmp_eq_u32_e64 s[98:99], 8, v7
	v_cndmask_b32_e32 v8, v8, v61, vcc
	v_cmp_eq_u32_e32 vcc, 9, v7
	v_cndmask_b32_e64 v8, v8, v60, s[100:101]
	v_cmp_eq_u32_e64 s[100:101], 10, v7
	v_cndmask_b32_e64 v8, v8, v53, s[98:99]
	v_cmp_eq_u32_e64 s[98:99], 11, v7
	v_cndmask_b32_e32 v8, v8, v52, vcc
	v_cmp_eq_u32_e32 vcc, 12, v7
	v_cndmask_b32_e64 v8, v8, v51, s[100:101]
	v_cmp_eq_u32_e64 s[100:101], 13, v7
	v_cndmask_b32_e64 v8, v8, v50, s[98:99]
	v_cmp_eq_u32_e64 s[98:99], 14, v7
	v_cndmask_b32_e32 v8, v8, v49, vcc
	v_cmp_eq_u32_e32 vcc, 15, v7
	v_cndmask_b32_e64 v8, v8, v48, s[100:101]
	v_cndmask_b32_e64 v8, v8, v47, s[98:99]
	v_cndmask_b32_e32 v7, v8, v46, vcc
	v_and_b32_e32 v8, 15, v81
	v_cmp_eq_u32_e32 vcc, 0, v8
	v_cmp_eq_u32_e64 s[100:101], 1, v8
	v_cmp_eq_u32_e64 s[98:99], 2, v8
	v_cndmask_b32_e32 v9, 0, v45, vcc
	v_cmp_eq_u32_e32 vcc, 3, v8
	v_cndmask_b32_e64 v9, v9, v44, s[100:101]
	v_cmp_eq_u32_e64 s[100:101], 4, v8
	v_cndmask_b32_e64 v9, v9, v43, s[98:99]
	v_cmp_eq_u32_e64 s[98:99], 5, v8
	v_cndmask_b32_e32 v9, v9, v42, vcc
	v_cmp_eq_u32_e32 vcc, 6, v8
	v_cndmask_b32_e64 v9, v9, v41, s[100:101]
	v_cmp_eq_u32_e64 s[100:101], 7, v8
	v_cndmask_b32_e64 v9, v9, v40, s[98:99]
	v_cmp_eq_u32_e64 s[98:99], 8, v8
	v_cndmask_b32_e32 v9, v9, v39, vcc
	v_cmp_eq_u32_e32 vcc, 9, v8
	v_cndmask_b32_e64 v9, v9, v38, s[100:101]
	v_cmp_eq_u32_e64 s[100:101], 10, v8
	v_cndmask_b32_e64 v9, v9, v37, s[98:99]
	v_cmp_eq_u32_e64 s[98:99], 11, v8
	v_cndmask_b32_e32 v9, v9, v36, vcc
	v_cmp_eq_u32_e32 vcc, 12, v8
	v_cndmask_b32_e64 v9, v9, v35, s[100:101]
	v_cmp_eq_u32_e64 s[100:101], 13, v8
	v_cndmask_b32_e64 v9, v9, v34, s[98:99]
	v_cmp_eq_u32_e64 s[98:99], 14, v8
	v_cndmask_b32_e32 v9, v9, v33, vcc
	v_cmp_eq_u32_e32 vcc, 15, v8
	v_cndmask_b32_e64 v9, v9, v32, s[100:101]
	v_cndmask_b32_e64 v9, v9, v11, s[98:99]
	v_cndmask_b32_e32 v8, v9, v6, vcc
	v_lshl_add_u32 v9, v7, 7, v8
	v_bfe_u32 v7, v79, 4, 4
	v_cmp_eq_u32_e32 vcc, 0, v7
	v_cmp_eq_u32_e64 s[100:101], 1, v7
	v_cmp_eq_u32_e64 s[98:99], 2, v7
	v_cndmask_b32_e32 v8, 0, v72, vcc
	v_cmp_eq_u32_e32 vcc, 3, v7
	v_cndmask_b32_e64 v8, v8, v71, s[100:101]
	v_cmp_eq_u32_e64 s[100:101], 4, v7
	v_cndmask_b32_e64 v8, v8, v70, s[98:99]
	v_cmp_eq_u32_e64 s[98:99], 5, v7
	v_cndmask_b32_e32 v8, v8, v69, vcc
	v_cmp_eq_u32_e32 vcc, 6, v7
	v_cndmask_b32_e64 v8, v8, v68, s[100:101]
	v_cmp_eq_u32_e64 s[100:101], 7, v7
	v_cndmask_b32_e64 v8, v8, v67, s[98:99]
	v_cmp_eq_u32_e64 s[98:99], 8, v7
	v_cndmask_b32_e32 v8, v8, v61, vcc
	v_cmp_eq_u32_e32 vcc, 9, v7
	v_cndmask_b32_e64 v8, v8, v60, s[100:101]
	v_cmp_eq_u32_e64 s[100:101], 10, v7
	v_cndmask_b32_e64 v8, v8, v53, s[98:99]
	v_cmp_eq_u32_e64 s[98:99], 11, v7
	v_cndmask_b32_e32 v8, v8, v52, vcc
	v_cmp_eq_u32_e32 vcc, 12, v7
	v_cndmask_b32_e64 v8, v8, v51, s[100:101]
	v_cmp_eq_u32_e64 s[100:101], 13, v7
	v_cndmask_b32_e64 v8, v8, v50, s[98:99]
	v_cmp_eq_u32_e64 s[98:99], 14, v7
	v_cndmask_b32_e32 v8, v8, v49, vcc
	v_cmp_eq_u32_e32 vcc, 15, v7
	v_cndmask_b32_e64 v8, v8, v48, s[100:101]
	v_cndmask_b32_e64 v8, v8, v47, s[98:99]
	v_cndmask_b32_e32 v7, v8, v46, vcc
	v_and_b32_e32 v8, 15, v79
	v_cmp_eq_u32_e32 vcc, 0, v8
	v_cmp_eq_u32_e64 s[100:101], 1, v8
	v_cmp_eq_u32_e64 s[98:99], 2, v8
	v_cndmask_b32_e32 v17, 0, v45, vcc
	v_cmp_eq_u32_e32 vcc, 3, v8
	v_cndmask_b32_e64 v17, v17, v44, s[100:101]
	v_cmp_eq_u32_e64 s[100:101], 4, v8
	v_cndmask_b32_e64 v17, v17, v43, s[98:99]
	v_cmp_eq_u32_e64 s[98:99], 5, v8
	v_cndmask_b32_e32 v17, v17, v42, vcc
	v_cmp_eq_u32_e32 vcc, 6, v8
	v_cndmask_b32_e64 v17, v17, v41, s[100:101]
	v_cmp_eq_u32_e64 s[100:101], 7, v8
	v_cndmask_b32_e64 v17, v17, v40, s[98:99]
	v_cmp_eq_u32_e64 s[98:99], 8, v8
	v_cndmask_b32_e32 v17, v17, v39, vcc
	v_cmp_eq_u32_e32 vcc, 9, v8
	v_cndmask_b32_e64 v17, v17, v38, s[100:101]
	v_cmp_eq_u32_e64 s[100:101], 10, v8
	v_cndmask_b32_e64 v17, v17, v37, s[98:99]
	v_cmp_eq_u32_e64 s[98:99], 11, v8
	v_cndmask_b32_e32 v17, v17, v36, vcc
	v_cmp_eq_u32_e32 vcc, 12, v8
	v_cndmask_b32_e64 v17, v17, v35, s[100:101]
	v_cmp_eq_u32_e64 s[100:101], 13, v8
	v_cndmask_b32_e64 v17, v17, v34, s[98:99]
	v_cmp_eq_u32_e64 s[98:99], 14, v8
	v_cndmask_b32_e32 v17, v17, v33, vcc
	v_cmp_eq_u32_e32 vcc, 15, v8
	v_cndmask_b32_e64 v17, v17, v32, s[100:101]
	v_cndmask_b32_e64 v17, v17, v11, s[98:99]
	v_cndmask_b32_e32 v8, v17, v6, vcc
	v_lshl_add_u32 v8, v7, 7, v8
	v_bfe_u32 v7, v77, 4, 4
	v_cmp_eq_u32_e32 vcc, 0, v7
	v_cmp_eq_u32_e64 s[100:101], 1, v7
	v_cmp_eq_u32_e64 s[98:99], 2, v7
	v_cndmask_b32_e32 v17, 0, v72, vcc
	v_cmp_eq_u32_e32 vcc, 3, v7
	v_cndmask_b32_e64 v17, v17, v71, s[100:101]
	v_cmp_eq_u32_e64 s[100:101], 4, v7
	v_cndmask_b32_e64 v17, v17, v70, s[98:99]
	v_cmp_eq_u32_e64 s[98:99], 5, v7
	v_cndmask_b32_e32 v17, v17, v69, vcc
	v_cmp_eq_u32_e32 vcc, 6, v7
	v_cndmask_b32_e64 v17, v17, v68, s[100:101]
	v_cmp_eq_u32_e64 s[100:101], 7, v7
	v_cndmask_b32_e64 v17, v17, v67, s[98:99]
; __device__ __forceinline__ void phase_route(CArgs& A, int l, unsigned char* lds, int tid) {
;     ...
;         for (int k = 0; k < 16; ++k) { const unsigned ci = L3[k] & 0xFFu, i = ci >> 4, j = ci & 15u; unsigned e1 = 0u, e2 = 0u;
; #pragma unroll
;             for (int ii = 0; ii < 16; ++ii) { e1 = (i == (unsigned)ii) ? (L1[ii] & 0x7Fu) : e1; e2 = (j == (unsigned)ii) ? (L2[ii] & 0x7Fu) : e2; }
;             ex[k] = (int)(e1 * 128u + e2); e[k] *= inv; }
;         int* ip = IDX + (size_t)t * 128 + hd * 16; float* gp = GATE + (size_t)t * 128 + hd * 16;
;         if (hf == 0) {
;             *(int4*)ip = make_int4(ex[0], ex[1], ex[2], ex[3]); *(int4*)(ip + 4) = make_int4(ex[4], ex[5], ex[6], ex[7]);
;             *(f32x4*)gp = (f32x4){e[0], e[1], e[2], e[3]}; *(f32x4*)(gp + 4) = (f32x4){e[4], e[5], e[6], e[7]};
;         } else {
;             *(int4*)(ip + 8) = make_int4(ex[8], ex[9], ex[10], ex[11]); *(int4*)(ip + 12) = make_int4(ex[12], ex[13], ex[14], ex[15]);
;             *(f32x4*)(gp + 8) = (f32x4){e[8], e[9], e[10], e[11]}; *(f32x4*)(gp + 12) = (f32x4){e[12], e[13], e[14], e[15]};
	v_cmp_eq_u32_e64 s[98:99], 8, v7
	v_cndmask_b32_e32 v17, v17, v61, vcc
	v_cmp_eq_u32_e32 vcc, 9, v7
	v_cndmask_b32_e64 v17, v17, v60, s[100:101]
	v_cmp_eq_u32_e64 s[100:101], 10, v7
	v_cndmask_b32_e64 v17, v17, v53, s[98:99]
	v_cmp_eq_u32_e64 s[98:99], 11, v7
	v_cndmask_b32_e32 v17, v17, v52, vcc
	v_cmp_eq_u32_e32 vcc, 12, v7
	v_cndmask_b32_e64 v17, v17, v51, s[100:101]
	v_cmp_eq_u32_e64 s[100:101], 13, v7
	v_cndmask_b32_e64 v17, v17, v50, s[98:99]
	v_cmp_eq_u32_e64 s[98:99], 14, v7
	v_cndmask_b32_e32 v17, v17, v49, vcc
	v_cmp_eq_u32_e32 vcc, 15, v7
	v_cndmask_b32_e64 v17, v17, v48, s[100:101]
	v_cndmask_b32_e64 v17, v17, v47, s[98:99]
	v_cndmask_b32_e32 v7, v17, v46, vcc
	v_and_b32_e32 v17, 15, v77
	v_cmp_eq_u32_e32 vcc, 0, v17
	v_cmp_eq_u32_e64 s[100:101], 1, v17
	v_cmp_eq_u32_e64 s[98:99], 2, v17
	v_cndmask_b32_e32 v18, 0, v45, vcc
	v_cmp_eq_u32_e32 vcc, 3, v17
	v_cndmask_b32_e64 v18, v18, v44, s[100:101]
	v_cmp_eq_u32_e64 s[100:101], 4, v17
	v_cndmask_b32_e64 v18, v18, v43, s[98:99]
	v_cmp_eq_u32_e64 s[98:99], 5, v17
	v_cndmask_b32_e32 v18, v18, v42, vcc
	v_cmp_eq_u32_e32 vcc, 6, v17
	v_cndmask_b32_e64 v18, v18, v41, s[100:101]
	v_cmp_eq_u32_e64 s[100:101], 7, v17
	v_cndmask_b32_e64 v18, v18, v40, s[98:99]
	v_cmp_eq_u32_e64 s[98:99], 8, v17
	v_cndmask_b32_e32 v18, v18, v39, vcc
	v_cmp_eq_u32_e32 vcc, 9, v17
	v_cndmask_b32_e64 v18, v18, v38, s[100:101]
	v_cmp_eq_u32_e64 s[100:101], 10, v17
	v_cndmask_b32_e64 v18, v18, v37, s[98:99]
	v_cmp_eq_u32_e64 s[98:99], 11, v17
	v_cndmask_b32_e32 v18, v18, v36, vcc
	v_cmp_eq_u32_e32 vcc, 12, v17
	v_cndmask_b32_e64 v18, v18, v35, s[100:101]
	v_cmp_eq_u32_e64 s[100:101], 13, v17
	v_cndmask_b32_e64 v18, v18, v34, s[98:99]
	v_cmp_eq_u32_e64 s[98:99], 14, v17
	v_cndmask_b32_e32 v18, v18, v33, vcc
	v_cmp_eq_u32_e32 vcc, 15, v17
	v_cndmask_b32_e64 v18, v18, v32, s[100:101]
	v_cndmask_b32_e64 v18, v18, v11, s[98:99]
	v_cndmask_b32_e32 v17, v18, v6, vcc
	v_lshl_add_u32 v7, v7, 7, v17
	v_bfe_u32 v17, v75, 4, 4
	v_cmp_eq_u32_e32 vcc, 0, v17
	v_cmp_eq_u32_e64 s[100:101], 1, v17
	v_cmp_eq_u32_e64 s[98:99], 2, v17
	v_cndmask_b32_e32 v18, 0, v72, vcc
	v_cmp_eq_u32_e32 vcc, 3, v17
	v_cndmask_b32_e64 v18, v18, v71, s[100:101]
	v_cmp_eq_u32_e64 s[100:101], 4, v17
	v_cndmask_b32_e64 v18, v18, v70, s[98:99]
	v_cmp_eq_u32_e64 s[98:99], 5, v17
	v_cndmask_b32_e32 v18, v18, v69, vcc
	v_cmp_eq_u32_e32 vcc, 6, v17
	v_cndmask_b32_e64 v18, v18, v68, s[100:101]
	v_cmp_eq_u32_e64 s[100:101], 7, v17
	v_cndmask_b32_e64 v18, v18, v67, s[98:99]
	v_cmp_eq_u32_e64 s[98:99], 8, v17
	v_cndmask_b32_e32 v18, v18, v61, vcc
	v_cmp_eq_u32_e32 vcc, 9, v17
	v_cndmask_b32_e64 v18, v18, v60, s[100:101]
	v_cmp_eq_u32_e64 s[100:101], 10, v17
	v_cndmask_b32_e64 v18, v18, v53, s[98:99]
	v_cmp_eq_u32_e64 s[98:99], 11, v17
	v_cndmask_b32_e32 v18, v18, v52, vcc
	v_cmp_eq_u32_e32 vcc, 12, v17
	v_cndmask_b32_e64 v18, v18, v51, s[100:101]
	v_cmp_eq_u32_e64 s[100:101], 13, v17
	v_cndmask_b32_e64 v18, v18, v50, s[98:99]
	v_cmp_eq_u32_e64 s[98:99], 14, v17
	v_cndmask_b32_e32 v18, v18, v49, vcc
	v_cmp_eq_u32_e32 vcc, 15, v17
	v_cndmask_b32_e64 v18, v18, v48, s[100:101]
	v_cndmask_b32_e64 v18, v18, v47, s[98:99]
	v_cndmask_b32_e32 v17, v18, v46, vcc
	v_and_b32_e32 v18, 15, v75
	v_cmp_eq_u32_e32 vcc, 0, v18
	v_cmp_eq_u32_e64 s[100:101], 1, v18
	v_cmp_eq_u32_e64 s[98:99], 2, v18
	v_cndmask_b32_e32 v19, 0, v45, vcc
	v_cmp_eq_u32_e32 vcc, 3, v18
	v_cndmask_b32_e64 v19, v19, v44, s[100:101]
	v_cmp_eq_u32_e64 s[100:101], 4, v18
	v_cndmask_b32_e64 v19, v19, v43, s[98:99]
	v_cmp_eq_u32_e64 s[98:99], 5, v18
	v_cndmask_b32_e32 v19, v19, v42, vcc
	v_cmp_eq_u32_e32 vcc, 6, v18
	v_cndmask_b32_e64 v19, v19, v41, s[100:101]
	v_cmp_eq_u32_e64 s[100:101], 7, v18
	v_cndmask_b32_e64 v19, v19, v40, s[98:99]
	v_cmp_eq_u32_e64 s[98:99], 8, v18
	v_cndmask_b32_e32 v19, v19, v39, vcc
	v_cmp_eq_u32_e32 vcc, 9, v18
	v_cndmask_b32_e64 v19, v19, v38, s[100:101]
	v_cmp_eq_u32_e64 s[100:101], 10, v18
	v_cndmask_b32_e64 v19, v19, v37, s[98:99]
	v_cmp_eq_u32_e64 s[98:99], 11, v18
	v_cndmask_b32_e32 v19, v19, v36, vcc
	v_cmp_eq_u32_e32 vcc, 12, v18
	v_cndmask_b32_e64 v19, v19, v35, s[100:101]
	v_cmp_eq_u32_e64 s[100:101], 13, v18
	v_cndmask_b32_e64 v19, v19, v34, s[98:99]
	v_cmp_eq_u32_e64 s[98:99], 14, v18
	v_cndmask_b32_e32 v19, v19, v33, vcc
	v_cmp_eq_u32_e32 vcc, 15, v18
	v_cndmask_b32_e64 v19, v19, v32, s[100:101]
	v_cndmask_b32_e64 v11, v19, v11, s[98:99]
	v_cndmask_b32_e32 v6, v11, v6, vcc
	v_lshl_add_u32 v6, v17, 7, v6
	global_store_dwordx4 v[14:15], v[6:9], off offset:32
	global_store_dwordx4 v[14:15], v[2:5], off offset:48
	s_nop 1
	v_pk_mul_f32 v[4:5], v[26:27], v[10:11] op_sel_hi:[1,0]
	v_pk_mul_f32 v[2:3], v[24:25], v[10:11] op_sel_hi:[1,0]
	global_store_dwordx4 v[12:13], v[2:5], off offset:32
; __device__ __forceinline__ void phase_route(CArgs& A, int l, unsigned char* lds, int tid) {
;     ...
;         for (int k = 0; k < 16; ++k) { const unsigned ci = L3[k] & 0xFFu, i = ci >> 4, j = ci & 15u; unsigned e1 = 0u, e2 = 0u;
; #pragma unroll
;             for (int ii = 0; ii < 16; ++ii) { e1 = (i == (unsigned)ii) ? (L1[ii] & 0x7Fu) : e1; e2 = (j == (unsigned)ii) ? (L2[ii] & 0x7Fu) : e2; }
;             ex[k] = (int)(e1 * 128u + e2); e[k] *= inv; }
;         int* ip = IDX + (size_t)t * 128 + hd * 16; float* gp = GATE + (size_t)t * 128 + hd * 16;
;         if (hf == 0) {
;             *(int4*)ip = make_int4(ex[0], ex[1], ex[2], ex[3]); *(int4*)(ip + 4) = make_int4(ex[4], ex[5], ex[6], ex[7]);
;             *(f32x4*)gp = (f32x4){e[0], e[1], e[2], e[3]}; *(f32x4*)(gp + 4) = (f32x4){e[4], e[5], e[6], e[7]};
.LBB0_137:
	s_or_saveexec_b64 s[4:5], s[4:5]
	s_nop 0
	v_mov_b64_e32 v[2:3], 48
	s_xor_b64 exec, exec, s[4:5]
	s_cbranch_execz .LBB0_130
	v_bfe_u32 v2, v84, 4, 4
	v_cmp_eq_u32_e32 vcc, 0, v2
	v_cmp_eq_u32_e64 s[100:101], 1, v2
	v_cmp_eq_u32_e64 s[98:99], 2, v2
	v_cndmask_b32_e32 v3, 0, v72, vcc
	v_cmp_eq_u32_e32 vcc, 3, v2
	v_cndmask_b32_e64 v3, v3, v71, s[100:101]
	v_cmp_eq_u32_e64 s[100:101], 4, v2
	v_cndmask_b32_e64 v3, v3, v70, s[98:99]
	v_cmp_eq_u32_e64 s[98:99], 5, v2
	v_cndmask_b32_e32 v3, v3, v69, vcc
	v_cmp_eq_u32_e32 vcc, 6, v2
	v_cndmask_b32_e64 v3, v3, v68, s[100:101]
	v_cmp_eq_u32_e64 s[100:101], 7, v2
	v_cndmask_b32_e64 v3, v3, v67, s[98:99]
	v_cmp_eq_u32_e64 s[98:99], 8, v2
	v_cndmask_b32_e32 v3, v3, v61, vcc
	v_cmp_eq_u32_e32 vcc, 9, v2
	v_cndmask_b32_e64 v3, v3, v60, s[100:101]
	v_cmp_eq_u32_e64 s[100:101], 10, v2
	v_cndmask_b32_e64 v3, v3, v53, s[98:99]
	v_cmp_eq_u32_e64 s[98:99], 11, v2
	v_cndmask_b32_e32 v3, v3, v52, vcc
	v_cmp_eq_u32_e32 vcc, 12, v2
	v_cndmask_b32_e64 v3, v3, v51, s[100:101]
	v_cmp_eq_u32_e64 s[100:101], 13, v2
	v_cndmask_b32_e64 v3, v3, v50, s[98:99]
	v_cmp_eq_u32_e64 s[98:99], 14, v2
	v_cndmask_b32_e32 v3, v3, v49, vcc
	v_cmp_eq_u32_e32 vcc, 15, v2
	v_cndmask_b32_e64 v3, v3, v48, s[100:101]
	v_cndmask_b32_e64 v3, v3, v47, s[98:99]
	v_cndmask_b32_e32 v2, v3, v46, vcc
	v_and_b32_e32 v3, 15, v84
	v_cmp_eq_u32_e32 vcc, 0, v3
	v_cmp_eq_u32_e64 s[100:101], 1, v3
	v_cmp_eq_u32_e64 s[98:99], 2, v3
	v_cndmask_b32_e32 v4, 0, v45, vcc
	v_cmp_eq_u32_e32 vcc, 3, v3
	v_cndmask_b32_e64 v4, v4, v44, s[100:101]
	v_cmp_eq_u32_e64 s[100:101], 4, v3
	v_cndmask_b32_e64 v4, v4, v43, s[98:99]
	v_cmp_eq_u32_e64 s[98:99], 5, v3
	v_cndmask_b32_e32 v4, v4, v42, vcc
	v_cmp_eq_u32_e32 vcc, 6, v3
	v_cndmask_b32_e64 v4, v4, v41, s[100:101]
	v_cmp_eq_u32_e64 s[100:101], 7, v3
	v_cndmask_b32_e64 v4, v4, v40, s[98:99]
	v_cmp_eq_u32_e64 s[98:99], 8, v3
	v_cndmask_b32_e32 v4, v4, v39, vcc
	v_cmp_eq_u32_e32 vcc, 9, v3
	v_cndmask_b32_e64 v4, v4, v38, s[100:101]
	v_cmp_eq_u32_e64 s[100:101], 10, v3
	v_cndmask_b32_e64 v4, v4, v37, s[98:99]
	v_cmp_eq_u32_e64 s[98:99], 11, v3
	v_cndmask_b32_e32 v4, v4, v36, vcc
	v_cmp_eq_u32_e32 vcc, 12, v3
	v_cndmask_b32_e64 v4, v4, v35, s[100:101]
	v_cmp_eq_u32_e64 s[100:101], 13, v3
	v_cndmask_b32_e64 v4, v4, v34, s[98:99]
	v_cmp_eq_u32_e64 s[98:99], 14, v3
	v_cndmask_b32_e32 v4, v4, v33, vcc
	v_cmp_eq_u32_e32 vcc, 15, v3
	v_cndmask_b32_e64 v4, v4, v32, s[100:101]
	v_cndmask_b32_e64 v4, v4, v11, s[98:99]
	v_cndmask_b32_e32 v3, v4, v6, vcc
	v_lshl_add_u32 v5, v2, 7, v3
	v_bfe_u32 v2, v83, 4, 4
	v_cmp_eq_u32_e32 vcc, 0, v2
	v_cmp_eq_u32_e64 s[100:101], 1, v2
	v_cmp_eq_u32_e64 s[98:99], 2, v2
	v_cndmask_b32_e32 v3, 0, v72, vcc
	v_cmp_eq_u32_e32 vcc, 3, v2
	v_cndmask_b32_e64 v3, v3, v71, s[100:101]
	v_cmp_eq_u32_e64 s[100:101], 4, v2
	v_cndmask_b32_e64 v3, v3, v70, s[98:99]
	v_cmp_eq_u32_e64 s[98:99], 5, v2
	v_cndmask_b32_e32 v3, v3, v69, vcc
	v_cmp_eq_u32_e32 vcc, 6, v2
	v_cndmask_b32_e64 v3, v3, v68, s[100:101]
	v_cmp_eq_u32_e64 s[100:101], 7, v2
	v_cndmask_b32_e64 v3, v3, v67, s[98:99]
	v_cmp_eq_u32_e64 s[98:99], 8, v2
	v_cndmask_b32_e32 v3, v3, v61, vcc
	v_cmp_eq_u32_e32 vcc, 9, v2
	v_cndmask_b32_e64 v3, v3, v60, s[100:101]
	v_cmp_eq_u32_e64 s[100:101], 10, v2
	v_cndmask_b32_e64 v3, v3, v53, s[98:99]
	v_cmp_eq_u32_e64 s[98:99], 11, v2
	v_cndmask_b32_e32 v3, v3, v52, vcc
	v_cmp_eq_u32_e32 vcc, 12, v2
	v_cndmask_b32_e64 v3, v3, v51, s[100:101]
	v_cmp_eq_u32_e64 s[100:101], 13, v2
	v_cndmask_b32_e64 v3, v3, v50, s[98:99]
	v_cmp_eq_u32_e64 s[98:99], 14, v2
	v_cndmask_b32_e32 v3, v3, v49, vcc
	v_cmp_eq_u32_e32 vcc, 15, v2
	v_cndmask_b32_e64 v3, v3, v48, s[100:101]
	v_cndmask_b32_e64 v3, v3, v47, s[98:99]
	v_cndmask_b32_e32 v2, v3, v46, vcc
	v_and_b32_e32 v3, 15, v83
	v_cmp_eq_u32_e32 vcc, 0, v3
	v_cmp_eq_u32_e64 s[100:101], 1, v3
	v_cmp_eq_u32_e64 s[98:99], 2, v3
	v_cndmask_b32_e32 v4, 0, v45, vcc
	v_cmp_eq_u32_e32 vcc, 3, v3
	v_cndmask_b32_e64 v4, v4, v44, s[100:101]
	v_cmp_eq_u32_e64 s[100:101], 4, v3
	v_cndmask_b32_e64 v4, v4, v43, s[98:99]
	v_cmp_eq_u32_e64 s[98:99], 5, v3
	v_cndmask_b32_e32 v4, v4, v42, vcc
	v_cmp_eq_u32_e32 vcc, 6, v3
	v_cndmask_b32_e64 v4, v4, v41, s[100:101]
	v_cmp_eq_u32_e64 s[100:101], 7, v3
	v_cndmask_b32_e64 v4, v4, v40, s[98:99]
	v_cmp_eq_u32_e64 s[98:99], 8, v3
	v_cndmask_b32_e32 v4, v4, v39, vcc
	v_cmp_eq_u32_e32 vcc, 9, v3
	v_cndmask_b32_e64 v4, v4, v38, s[100:101]
	v_cmp_eq_u32_e64 s[100:101], 10, v3
	v_cndmask_b32_e64 v4, v4, v37, s[98:99]
	v_cmp_eq_u32_e64 s[98:99], 11, v3
	v_cndmask_b32_e32 v4, v4, v36, vcc
	v_cmp_eq_u32_e32 vcc, 12, v3
	v_cndmask_b32_e64 v4, v4, v35, s[100:101]
	v_cmp_eq_u32_e64 s[100:101], 13, v3
	v_cndmask_b32_e64 v4, v4, v34, s[98:99]
	v_cmp_eq_u32_e64 s[98:99], 14, v3
	v_cndmask_b32_e32 v4, v4, v33, vcc
	v_cmp_eq_u32_e32 vcc, 15, v3
	v_cndmask_b32_e64 v4, v4, v32, s[100:101]
	v_cndmask_b32_e64 v4, v4, v11, s[98:99]
	v_cndmask_b32_e32 v3, v4, v6, vcc
	v_lshl_add_u32 v4, v2, 7, v3
	v_bfe_u32 v2, v82, 4, 4
	v_cmp_eq_u32_e32 vcc, 0, v2
	v_cmp_eq_u32_e64 s[100:101], 1, v2
	v_cmp_eq_u32_e64 s[98:99], 2, v2
	v_cndmask_b32_e32 v3, 0, v72, vcc
	v_cmp_eq_u32_e32 vcc, 3, v2
	v_cndmask_b32_e64 v3, v3, v71, s[100:101]
	v_cmp_eq_u32_e64 s[100:101], 4, v2
	v_cndmask_b32_e64 v3, v3, v70, s[98:99]
	v_cmp_eq_u32_e64 s[98:99], 5, v2
	v_cndmask_b32_e32 v3, v3, v69, vcc
	v_cmp_eq_u32_e32 vcc, 6, v2
	v_cndmask_b32_e64 v3, v3, v68, s[100:101]
	v_cmp_eq_u32_e64 s[100:101], 7, v2
	v_cndmask_b32_e64 v3, v3, v67, s[98:99]
	v_cmp_eq_u32_e64 s[98:99], 8, v2
	v_cndmask_b32_e32 v3, v3, v61, vcc
	v_cmp_eq_u32_e32 vcc, 9, v2
	v_cndmask_b32_e64 v3, v3, v60, s[100:101]
; __device__ __forceinline__ void phase_route(CArgs& A, int l, unsigned char* lds, int tid) {
;     ...
;         for (int k = 0; k < 16; ++k) { const unsigned ci = L3[k] & 0xFFu, i = ci >> 4, j = ci & 15u; unsigned e1 = 0u, e2 = 0u;
; #pragma unroll
;             for (int ii = 0; ii < 16; ++ii) { e1 = (i == (unsigned)ii) ? (L1[ii] & 0x7Fu) : e1; e2 = (j == (unsigned)ii) ? (L2[ii] & 0x7Fu) : e2; }
;             ex[k] = (int)(e1 * 128u + e2); e[k] *= inv; }
	v_cmp_eq_u32_e64 s[100:101], 10, v2
	v_cndmask_b32_e64 v3, v3, v53, s[98:99]
	v_cmp_eq_u32_e64 s[98:99], 11, v2
	v_cndmask_b32_e32 v3, v3, v52, vcc
	v_cmp_eq_u32_e32 vcc, 12, v2
	v_cndmask_b32_e64 v3, v3, v51, s[100:101]
	v_cmp_eq_u32_e64 s[100:101], 13, v2
	v_cndmask_b32_e64 v3, v3, v50, s[98:99]
	v_cmp_eq_u32_e64 s[98:99], 14, v2
	v_cndmask_b32_e32 v3, v3, v49, vcc
	v_cmp_eq_u32_e32 vcc, 15, v2
	v_cndmask_b32_e64 v3, v3, v48, s[100:101]
	v_cndmask_b32_e64 v3, v3, v47, s[98:99]
	v_cndmask_b32_e32 v2, v3, v46, vcc
	v_and_b32_e32 v3, 15, v82
	v_cmp_eq_u32_e32 vcc, 0, v3
	v_cmp_eq_u32_e64 s[100:101], 1, v3
	v_cmp_eq_u32_e64 s[98:99], 2, v3
	v_cndmask_b32_e32 v7, 0, v45, vcc
	v_cmp_eq_u32_e32 vcc, 3, v3
	v_cndmask_b32_e64 v7, v7, v44, s[100:101]
	v_cmp_eq_u32_e64 s[100:101], 4, v3
	v_cndmask_b32_e64 v7, v7, v43, s[98:99]
	v_cmp_eq_u32_e64 s[98:99], 5, v3
	v_cndmask_b32_e32 v7, v7, v42, vcc
	v_cmp_eq_u32_e32 vcc, 6, v3
	v_cndmask_b32_e64 v7, v7, v41, s[100:101]
	v_cmp_eq_u32_e64 s[100:101], 7, v3
	v_cndmask_b32_e64 v7, v7, v40, s[98:99]
	v_cmp_eq_u32_e64 s[98:99], 8, v3
	v_cndmask_b32_e32 v7, v7, v39, vcc
	v_cmp_eq_u32_e32 vcc, 9, v3
	v_cndmask_b32_e64 v7, v7, v38, s[100:101]
	v_cmp_eq_u32_e64 s[100:101], 10, v3
	v_cndmask_b32_e64 v7, v7, v37, s[98:99]
	v_cmp_eq_u32_e64 s[98:99], 11, v3
	v_cndmask_b32_e32 v7, v7, v36, vcc
	v_cmp_eq_u32_e32 vcc, 12, v3
	v_cndmask_b32_e64 v7, v7, v35, s[100:101]
	v_cmp_eq_u32_e64 s[100:101], 13, v3
	v_cndmask_b32_e64 v7, v7, v34, s[98:99]
	v_cmp_eq_u32_e64 s[98:99], 14, v3
	v_cndmask_b32_e32 v7, v7, v33, vcc
	v_cmp_eq_u32_e32 vcc, 15, v3
	v_cndmask_b32_e64 v7, v7, v32, s[100:101]
	v_cndmask_b32_e64 v7, v7, v11, s[98:99]
	v_cndmask_b32_e32 v3, v7, v6, vcc
	v_lshl_add_u32 v3, v2, 7, v3
	v_bfe_u32 v2, v80, 4, 4
	v_cmp_eq_u32_e32 vcc, 0, v2
	v_cmp_eq_u32_e64 s[100:101], 1, v2
	v_cmp_eq_u32_e64 s[98:99], 2, v2
	v_cndmask_b32_e32 v7, 0, v72, vcc
	v_cmp_eq_u32_e32 vcc, 3, v2
	v_cndmask_b32_e64 v7, v7, v71, s[100:101]
	v_cmp_eq_u32_e64 s[100:101], 4, v2
	v_cndmask_b32_e64 v7, v7, v70, s[98:99]
	v_cmp_eq_u32_e64 s[98:99], 5, v2
	v_cndmask_b32_e32 v7, v7, v69, vcc
	v_cmp_eq_u32_e32 vcc, 6, v2
	v_cndmask_b32_e64 v7, v7, v68, s[100:101]
	v_cmp_eq_u32_e64 s[100:101], 7, v2
	v_cndmask_b32_e64 v7, v7, v67, s[98:99]
	v_cmp_eq_u32_e64 s[98:99], 8, v2
	v_cndmask_b32_e32 v7, v7, v61, vcc
	v_cmp_eq_u32_e32 vcc, 9, v2
	v_cndmask_b32_e64 v7, v7, v60, s[100:101]
	v_cmp_eq_u32_e64 s[100:101], 10, v2
	v_cndmask_b32_e64 v7, v7, v53, s[98:99]
	v_cmp_eq_u32_e64 s[98:99], 11, v2
	v_cndmask_b32_e32 v7, v7, v52, vcc
	v_cmp_eq_u32_e32 vcc, 12, v2
	v_cndmask_b32_e64 v7, v7, v51, s[100:101]
	v_cmp_eq_u32_e64 s[100:101], 13, v2
	v_cndmask_b32_e64 v7, v7, v50, s[98:99]
	v_cmp_eq_u32_e64 s[98:99], 14, v2
	v_cndmask_b32_e32 v7, v7, v49, vcc
	v_cmp_eq_u32_e32 vcc, 15, v2
	v_cndmask_b32_e64 v7, v7, v48, s[100:101]
	v_cndmask_b32_e64 v7, v7, v47, s[98:99]
	v_cndmask_b32_e32 v2, v7, v46, vcc
	v_and_b32_e32 v7, 15, v80
	v_cmp_eq_u32_e32 vcc, 0, v7
	v_cmp_eq_u32_e64 s[100:101], 1, v7
	v_cmp_eq_u32_e64 s[98:99], 2, v7
	v_cndmask_b32_e32 v8, 0, v45, vcc
	v_cmp_eq_u32_e32 vcc, 3, v7
	v_cndmask_b32_e64 v8, v8, v44, s[100:101]
	v_cmp_eq_u32_e64 s[100:101], 4, v7
	v_cndmask_b32_e64 v8, v8, v43, s[98:99]
	v_cmp_eq_u32_e64 s[98:99], 5, v7
	v_cndmask_b32_e32 v8, v8, v42, vcc
	v_cmp_eq_u32_e32 vcc, 6, v7
	v_cndmask_b32_e64 v8, v8, v41, s[100:101]
	v_cmp_eq_u32_e64 s[100:101], 7, v7
	v_cndmask_b32_e64 v8, v8, v40, s[98:99]
	v_cmp_eq_u32_e64 s[98:99], 8, v7
	v_cndmask_b32_e32 v8, v8, v39, vcc
	v_cmp_eq_u32_e32 vcc, 9, v7
	v_cndmask_b32_e64 v8, v8, v38, s[100:101]
	v_cmp_eq_u32_e64 s[100:101], 10, v7
	v_cndmask_b32_e64 v8, v8, v37, s[98:99]
	v_cmp_eq_u32_e64 s[98:99], 11, v7
	v_cndmask_b32_e32 v8, v8, v36, vcc
	v_cmp_eq_u32_e32 vcc, 12, v7
	v_cndmask_b32_e64 v8, v8, v35, s[100:101]
	v_cmp_eq_u32_e64 s[100:101], 13, v7
	v_cndmask_b32_e64 v8, v8, v34, s[98:99]
	v_cmp_eq_u32_e64 s[98:99], 14, v7
	v_cndmask_b32_e32 v8, v8, v33, vcc
	v_cmp_eq_u32_e32 vcc, 15, v7
	v_cndmask_b32_e64 v8, v8, v32, s[100:101]
	v_cndmask_b32_e64 v8, v8, v11, s[98:99]
	v_cndmask_b32_e32 v7, v8, v6, vcc
	v_lshl_add_u32 v2, v2, 7, v7
	v_bfe_u32 v7, v78, 4, 4
	v_cmp_eq_u32_e32 vcc, 0, v7
	v_cmp_eq_u32_e64 s[100:101], 1, v7
	v_cmp_eq_u32_e64 s[98:99], 2, v7
	v_cndmask_b32_e32 v8, 0, v72, vcc
	v_cmp_eq_u32_e32 vcc, 3, v7
	v_cndmask_b32_e64 v8, v8, v71, s[100:101]
	v_cmp_eq_u32_e64 s[100:101], 4, v7
	v_cndmask_b32_e64 v8, v8, v70, s[98:99]
	v_cmp_eq_u32_e64 s[98:99], 5, v7
	v_cndmask_b32_e32 v8, v8, v69, vcc
	v_cmp_eq_u32_e32 vcc, 6, v7
	v_cndmask_b32_e64 v8, v8, v68, s[100:101]
	v_cmp_eq_u32_e64 s[100:101], 7, v7
	v_cndmask_b32_e64 v8, v8, v67, s[98:99]
	v_cmp_eq_u32_e64 s[98:99], 8, v7
	v_cndmask_b32_e32 v8, v8, v61, vcc
	v_cmp_eq_u32_e32 vcc, 9, v7
	v_cndmask_b32_e64 v8, v8, v60, s[100:101]
	v_cmp_eq_u32_e64 s[100:101], 10, v7
	v_cndmask_b32_e64 v8, v8, v53, s[98:99]
	v_cmp_eq_u32_e64 s[98:99], 11, v7
	v_cndmask_b32_e32 v8, v8, v52, vcc
	v_cmp_eq_u32_e32 vcc, 12, v7
	v_cndmask_b32_e64 v8, v8, v51, s[100:101]
	v_cmp_eq_u32_e64 s[100:101], 13, v7
	v_cndmask_b32_e64 v8, v8, v50, s[98:99]
	v_cmp_eq_u32_e64 s[98:99], 14, v7
	v_cndmask_b32_e32 v8, v8, v49, vcc
	v_cmp_eq_u32_e32 vcc, 15, v7
	v_cndmask_b32_e64 v8, v8, v48, s[100:101]
	v_cndmask_b32_e64 v8, v8, v47, s[98:99]
	v_cndmask_b32_e32 v7, v8, v46, vcc
	v_and_b32_e32 v8, 15, v78
	v_cmp_eq_u32_e32 vcc, 0, v8
	v_cmp_eq_u32_e64 s[100:101], 1, v8
	v_cmp_eq_u32_e64 s[98:99], 2, v8
	v_cndmask_b32_e32 v9, 0, v45, vcc
	v_cmp_eq_u32_e32 vcc, 3, v8
	v_cndmask_b32_e64 v9, v9, v44, s[100:101]
	v_cmp_eq_u32_e64 s[100:101], 4, v8
	v_cndmask_b32_e64 v9, v9, v43, s[98:99]
; __device__ __forceinline__ void phase_route(CArgs& A, int l, unsigned char* lds, int tid) {
;     ...
;         for (int k = 0; k < 16; ++k) { const unsigned ci = L3[k] & 0xFFu, i = ci >> 4, j = ci & 15u; unsigned e1 = 0u, e2 = 0u;
; #pragma unroll
;             for (int ii = 0; ii < 16; ++ii) { e1 = (i == (unsigned)ii) ? (L1[ii] & 0x7Fu) : e1; e2 = (j == (unsigned)ii) ? (L2[ii] & 0x7Fu) : e2; }
;             ex[k] = (int)(e1 * 128u + e2); e[k] *= inv; }
	v_cmp_eq_u32_e64 s[98:99], 5, v8
	v_cndmask_b32_e32 v9, v9, v42, vcc
	v_cmp_eq_u32_e32 vcc, 6, v8
	v_cndmask_b32_e64 v9, v9, v41, s[100:101]
	v_cmp_eq_u32_e64 s[100:101], 7, v8
	v_cndmask_b32_e64 v9, v9, v40, s[98:99]
	v_cmp_eq_u32_e64 s[98:99], 8, v8
	v_cndmask_b32_e32 v9, v9, v39, vcc
	v_cmp_eq_u32_e32 vcc, 9, v8
	v_cndmask_b32_e64 v9, v9, v38, s[100:101]
	v_cmp_eq_u32_e64 s[100:101], 10, v8
	v_cndmask_b32_e64 v9, v9, v37, s[98:99]
	v_cmp_eq_u32_e64 s[98:99], 11, v8
	v_cndmask_b32_e32 v9, v9, v36, vcc
	v_cmp_eq_u32_e32 vcc, 12, v8
	v_cndmask_b32_e64 v9, v9, v35, s[100:101]
	v_cmp_eq_u32_e64 s[100:101], 13, v8
	v_cndmask_b32_e64 v9, v9, v34, s[98:99]
	v_cmp_eq_u32_e64 s[98:99], 14, v8
	v_cndmask_b32_e32 v9, v9, v33, vcc
	v_cmp_eq_u32_e32 vcc, 15, v8
	v_cndmask_b32_e64 v9, v9, v32, s[100:101]
	v_cndmask_b32_e64 v9, v9, v11, s[98:99]
	v_cndmask_b32_e32 v8, v9, v6, vcc
	v_lshl_add_u32 v9, v7, 7, v8
	v_bfe_u32 v7, v76, 4, 4
	v_cmp_eq_u32_e32 vcc, 0, v7
	v_cmp_eq_u32_e64 s[100:101], 1, v7
	v_cmp_eq_u32_e64 s[98:99], 2, v7
	v_cndmask_b32_e32 v8, 0, v72, vcc
	v_cmp_eq_u32_e32 vcc, 3, v7
	v_cndmask_b32_e64 v8, v8, v71, s[100:101]
	v_cmp_eq_u32_e64 s[100:101], 4, v7
	v_cndmask_b32_e64 v8, v8, v70, s[98:99]
	v_cmp_eq_u32_e64 s[98:99], 5, v7
	v_cndmask_b32_e32 v8, v8, v69, vcc
	v_cmp_eq_u32_e32 vcc, 6, v7
	v_cndmask_b32_e64 v8, v8, v68, s[100:101]
	v_cmp_eq_u32_e64 s[100:101], 7, v7
	v_cndmask_b32_e64 v8, v8, v67, s[98:99]
	v_cmp_eq_u32_e64 s[98:99], 8, v7
	v_cndmask_b32_e32 v8, v8, v61, vcc
	v_cmp_eq_u32_e32 vcc, 9, v7
	v_cndmask_b32_e64 v8, v8, v60, s[100:101]
	v_cmp_eq_u32_e64 s[100:101], 10, v7
	v_cndmask_b32_e64 v8, v8, v53, s[98:99]
	v_cmp_eq_u32_e64 s[98:99], 11, v7
	v_cndmask_b32_e32 v8, v8, v52, vcc
	v_cmp_eq_u32_e32 vcc, 12, v7
	v_cndmask_b32_e64 v8, v8, v51, s[100:101]
	v_cmp_eq_u32_e64 s[100:101], 13, v7
	v_cndmask_b32_e64 v8, v8, v50, s[98:99]
	v_cmp_eq_u32_e64 s[98:99], 14, v7
	v_cndmask_b32_e32 v8, v8, v49, vcc
	v_cmp_eq_u32_e32 vcc, 15, v7
	v_cndmask_b32_e64 v8, v8, v48, s[100:101]
	v_cndmask_b32_e64 v8, v8, v47, s[98:99]
	v_cndmask_b32_e32 v7, v8, v46, vcc
	v_and_b32_e32 v8, 15, v76
	v_cmp_eq_u32_e32 vcc, 0, v8
	v_cmp_eq_u32_e64 s[100:101], 1, v8
	v_cmp_eq_u32_e64 s[98:99], 2, v8
	v_cndmask_b32_e32 v24, 0, v45, vcc
	v_cmp_eq_u32_e32 vcc, 3, v8
	v_cndmask_b32_e64 v24, v24, v44, s[100:101]
	v_cmp_eq_u32_e64 s[100:101], 4, v8
	v_cndmask_b32_e64 v24, v24, v43, s[98:99]
	v_cmp_eq_u32_e64 s[98:99], 5, v8
	v_cndmask_b32_e32 v24, v24, v42, vcc
	v_cmp_eq_u32_e32 vcc, 6, v8
	v_cndmask_b32_e64 v24, v24, v41, s[100:101]
	v_cmp_eq_u32_e64 s[100:101], 7, v8
	v_cndmask_b32_e64 v24, v24, v40, s[98:99]
	v_cmp_eq_u32_e64 s[98:99], 8, v8
	v_cndmask_b32_e32 v24, v24, v39, vcc
	v_cmp_eq_u32_e32 vcc, 9, v8
	v_cndmask_b32_e64 v24, v24, v38, s[100:101]
	v_cmp_eq_u32_e64 s[100:101], 10, v8
	v_cndmask_b32_e64 v24, v24, v37, s[98:99]
	v_cmp_eq_u32_e64 s[98:99], 11, v8
	v_cndmask_b32_e32 v24, v24, v36, vcc
	v_cmp_eq_u32_e32 vcc, 12, v8
	v_cndmask_b32_e64 v24, v24, v35, s[100:101]
	v_cmp_eq_u32_e64 s[100:101], 13, v8
	v_cndmask_b32_e64 v24, v24, v34, s[98:99]
	v_cmp_eq_u32_e64 s[98:99], 14, v8
	v_cndmask_b32_e32 v24, v24, v33, vcc
	v_cmp_eq_u32_e32 vcc, 15, v8
	v_cndmask_b32_e64 v24, v24, v32, s[100:101]
	v_cndmask_b32_e64 v24, v24, v11, s[98:99]
	v_cndmask_b32_e32 v8, v24, v6, vcc
	v_lshl_add_u32 v8, v7, 7, v8
	v_bfe_u32 v7, v74, 4, 4
	v_cmp_eq_u32_e32 vcc, 0, v7
	v_cmp_eq_u32_e64 s[100:101], 1, v7
	v_cmp_eq_u32_e64 s[98:99], 2, v7
	v_cndmask_b32_e32 v24, 0, v72, vcc
	v_cmp_eq_u32_e32 vcc, 3, v7
	v_cndmask_b32_e64 v24, v24, v71, s[100:101]
	v_cmp_eq_u32_e64 s[100:101], 4, v7
	v_cndmask_b32_e64 v24, v24, v70, s[98:99]
	v_cmp_eq_u32_e64 s[98:99], 5, v7
	v_cndmask_b32_e32 v24, v24, v69, vcc
	v_cmp_eq_u32_e32 vcc, 6, v7
	v_cndmask_b32_e64 v24, v24, v68, s[100:101]
	v_cmp_eq_u32_e64 s[100:101], 7, v7
	v_cndmask_b32_e64 v24, v24, v67, s[98:99]
	v_cmp_eq_u32_e64 s[98:99], 8, v7
	v_cndmask_b32_e32 v24, v24, v61, vcc
	v_cmp_eq_u32_e32 vcc, 9, v7
	v_cndmask_b32_e64 v24, v24, v60, s[100:101]
	v_cmp_eq_u32_e64 s[100:101], 10, v7
	v_cndmask_b32_e64 v24, v24, v53, s[98:99]
	v_cmp_eq_u32_e64 s[98:99], 11, v7
	v_cndmask_b32_e32 v24, v24, v52, vcc
	v_cmp_eq_u32_e32 vcc, 12, v7
	v_cndmask_b32_e64 v24, v24, v51, s[100:101]
	v_cmp_eq_u32_e64 s[100:101], 13, v7
	v_cndmask_b32_e64 v24, v24, v50, s[98:99]
; __device__ __forceinline__ void phase_route(CArgs& A, int l, unsigned char* lds, int tid) {
;     ...
;         for (int k = 0; k < 16; ++k) { const unsigned ci = L3[k] & 0xFFu, i = ci >> 4, j = ci & 15u; unsigned e1 = 0u, e2 = 0u;
; #pragma unroll
;             for (int ii = 0; ii < 16; ++ii) { e1 = (i == (unsigned)ii) ? (L1[ii] & 0x7Fu) : e1; e2 = (j == (unsigned)ii) ? (L2[ii] & 0x7Fu) : e2; }
;             ex[k] = (int)(e1 * 128u + e2); e[k] *= inv; }
;         int* ip = IDX + (size_t)t * 128 + hd * 16; float* gp = GATE + (size_t)t * 128 + hd * 16;
;         if (hf == 0) {
;             *(int4*)ip = make_int4(ex[0], ex[1], ex[2], ex[3]); *(int4*)(ip + 4) = make_int4(ex[4], ex[5], ex[6], ex[7]);
;             *(f32x4*)gp = (f32x4){e[0], e[1], e[2], e[3]}; *(f32x4*)(gp + 4) = (f32x4){e[4], e[5], e[6], e[7]};
	v_cmp_eq_u32_e64 s[98:99], 14, v7
	v_cndmask_b32_e32 v24, v24, v49, vcc
	v_cmp_eq_u32_e32 vcc, 15, v7
	v_cndmask_b32_e64 v24, v24, v48, s[100:101]
	v_cndmask_b32_e64 v24, v24, v47, s[98:99]
	v_cndmask_b32_e32 v7, v24, v46, vcc
	v_and_b32_e32 v24, 15, v74
	v_cmp_eq_u32_e32 vcc, 0, v24
	v_cmp_eq_u32_e64 s[100:101], 1, v24
	v_cmp_eq_u32_e64 s[98:99], 2, v24
	v_cndmask_b32_e32 v25, 0, v45, vcc
	v_cmp_eq_u32_e32 vcc, 3, v24
	v_cndmask_b32_e64 v25, v25, v44, s[100:101]
	v_cmp_eq_u32_e64 s[100:101], 4, v24
	v_cndmask_b32_e64 v25, v25, v43, s[98:99]
	v_cmp_eq_u32_e64 s[98:99], 5, v24
	v_cndmask_b32_e32 v25, v25, v42, vcc
	v_cmp_eq_u32_e32 vcc, 6, v24
	v_cndmask_b32_e64 v25, v25, v41, s[100:101]
	v_cmp_eq_u32_e64 s[100:101], 7, v24
	v_cndmask_b32_e64 v25, v25, v40, s[98:99]
	v_cmp_eq_u32_e64 s[98:99], 8, v24
	v_cndmask_b32_e32 v25, v25, v39, vcc
	v_cmp_eq_u32_e32 vcc, 9, v24
	v_cndmask_b32_e64 v25, v25, v38, s[100:101]
	v_cmp_eq_u32_e64 s[100:101], 10, v24
	v_cndmask_b32_e64 v25, v25, v37, s[98:99]
	v_cmp_eq_u32_e64 s[98:99], 11, v24
	v_cndmask_b32_e32 v25, v25, v36, vcc
	v_cmp_eq_u32_e32 vcc, 12, v24
	v_cndmask_b32_e64 v25, v25, v35, s[100:101]
	v_cmp_eq_u32_e64 s[100:101], 13, v24
	v_cndmask_b32_e64 v25, v25, v34, s[98:99]
	v_cmp_eq_u32_e64 s[98:99], 14, v24
	v_cndmask_b32_e32 v25, v25, v33, vcc
	v_cmp_eq_u32_e32 vcc, 15, v24
	v_cndmask_b32_e64 v25, v25, v32, s[100:101]
	v_cndmask_b32_e64 v25, v25, v11, s[98:99]
	v_cndmask_b32_e32 v24, v25, v6, vcc
	v_lshl_add_u32 v7, v7, 7, v24
	v_bfe_u32 v24, v73, 4, 4
	v_cmp_eq_u32_e32 vcc, 0, v24
	v_cmp_eq_u32_e64 s[100:101], 1, v24
	v_cmp_eq_u32_e64 s[98:99], 2, v24
	v_cndmask_b32_e32 v25, 0, v72, vcc
	v_cmp_eq_u32_e32 vcc, 3, v24
	v_cndmask_b32_e64 v25, v25, v71, s[100:101]
	v_cmp_eq_u32_e64 s[100:101], 4, v24
	v_cndmask_b32_e64 v25, v25, v70, s[98:99]
	v_cmp_eq_u32_e64 s[98:99], 5, v24
	v_cndmask_b32_e32 v25, v25, v69, vcc
	v_cmp_eq_u32_e32 vcc, 6, v24
	v_cndmask_b32_e64 v25, v25, v68, s[100:101]
	v_cmp_eq_u32_e64 s[100:101], 7, v24
	v_cndmask_b32_e64 v25, v25, v67, s[98:99]
	v_cmp_eq_u32_e64 s[98:99], 8, v24
	v_cndmask_b32_e32 v25, v25, v61, vcc
	v_cmp_eq_u32_e32 vcc, 9, v24
	v_cndmask_b32_e64 v25, v25, v60, s[100:101]
	v_cmp_eq_u32_e64 s[100:101], 10, v24
	v_cndmask_b32_e64 v25, v25, v53, s[98:99]
	v_cmp_eq_u32_e64 s[98:99], 11, v24
	v_cndmask_b32_e32 v25, v25, v52, vcc
	v_cmp_eq_u32_e32 vcc, 12, v24
	v_cndmask_b32_e64 v25, v25, v51, s[100:101]
	v_cmp_eq_u32_e64 s[100:101], 13, v24
	v_cndmask_b32_e64 v25, v25, v50, s[98:99]
	v_cmp_eq_u32_e64 s[98:99], 14, v24
	v_cndmask_b32_e32 v25, v25, v49, vcc
	v_cmp_eq_u32_e32 vcc, 15, v24
	v_cndmask_b32_e64 v25, v25, v48, s[100:101]
	v_cndmask_b32_e64 v25, v25, v47, s[98:99]
	v_cndmask_b32_e32 v24, v25, v46, vcc
	v_and_b32_e32 v25, 15, v73
	v_cmp_eq_u32_e32 vcc, 0, v25
	v_cmp_eq_u32_e64 s[100:101], 1, v25
	v_cmp_eq_u32_e64 s[98:99], 2, v25
	v_cndmask_b32_e32 v26, 0, v45, vcc
	v_cmp_eq_u32_e32 vcc, 3, v25
	v_cndmask_b32_e64 v26, v26, v44, s[100:101]
	v_cmp_eq_u32_e64 s[100:101], 4, v25
	v_cndmask_b32_e64 v26, v26, v43, s[98:99]
	v_cmp_eq_u32_e64 s[98:99], 5, v25
	v_cndmask_b32_e32 v26, v26, v42, vcc
	v_cmp_eq_u32_e32 vcc, 6, v25
	v_cndmask_b32_e64 v26, v26, v41, s[100:101]
	v_cmp_eq_u32_e64 s[100:101], 7, v25
	v_cndmask_b32_e64 v26, v26, v40, s[98:99]
	v_cmp_eq_u32_e64 s[98:99], 8, v25
	v_cndmask_b32_e32 v26, v26, v39, vcc
	v_cmp_eq_u32_e32 vcc, 9, v25
	v_cndmask_b32_e64 v26, v26, v38, s[100:101]
	v_cmp_eq_u32_e64 s[100:101], 10, v25
	v_cndmask_b32_e64 v26, v26, v37, s[98:99]
	v_cmp_eq_u32_e64 s[98:99], 11, v25
	v_cndmask_b32_e32 v26, v26, v36, vcc
	v_cmp_eq_u32_e32 vcc, 12, v25
	v_cndmask_b32_e64 v26, v26, v35, s[100:101]
	v_cmp_eq_u32_e64 s[100:101], 13, v25
	v_cndmask_b32_e64 v26, v26, v34, s[98:99]
	v_cmp_eq_u32_e64 s[98:99], 14, v25
	v_cndmask_b32_e32 v26, v26, v33, vcc
	v_cmp_eq_u32_e32 vcc, 15, v25
	v_cndmask_b32_e64 v26, v26, v32, s[100:101]
	v_cndmask_b32_e64 v11, v26, v11, s[98:99]
	v_cndmask_b32_e32 v6, v11, v6, vcc
	v_lshl_add_u32 v6, v24, 7, v6
	global_store_dwordx4 v[14:15], v[6:9], off
	global_store_dwordx4 v[14:15], v[2:5], off offset:16
	s_nop 1
	v_pk_mul_f32 v[4:5], v[18:19], v[10:11] op_sel_hi:[1,0]
	v_pk_mul_f32 v[2:3], v[16:17], v[10:11] op_sel_hi:[1,0]
	global_store_dwordx4 v[12:13], v[2:5], off
	s_nop 1
	v_mov_b64_e32 v[2:3], 16
	s_branch .LBB0_130

; __device__ __forceinline__ void phase_xattn(CArgs& A, int l, unsigned char* lds, int tid) {
;     ...
;         for (int kt = 0; kt < 4; ++kt) {
;             __syncthreads();
; #pragma unroll
;             for (int i = 0; i < 4; ++i) *(u32x4*)(Ks + skey * XA_KP + (sdc + i * 8) * 2) = kr[i];
; #pragma unroll
;             for (int i = 0; i < 4; ++i) *(u32x4*)(Vt + skey * XA_VP + (sdc + i * 8) * 2) = vr[i];
;             __syncthreads();
;             if (kt + 1 < 4) {
; #pragma unroll
;                 for (int i = 0; i < 4; ++i) { kr[i] = *(const u32x4*)(kvbase + (size_t)(kt + 1) * 64 * 4096 + i * 8); vr[i] = *(const u32x4*)(kvbase + (size_t)(kt + 1) * 64 * 4096 + 1024 + i * 8); } }
;             f32x4 sc[4];
; #pragma unroll
;             for (int blk = 0; blk < 4; ++blk) { sc[blk] = (f32x4){0.f, 0.f, 0.f, 0.f};
; #pragma unroll
;                 for (int ks = 0; ks < 8; ++ks) { const bf16x8 a = *(const bf16x8*)(Ks + (blk * 16 + r) * XA_KP + (32 * ks + 8 * g) * 2);
;                     sc[blk] = __builtin_amdgcn_mfma_f32_16x16x32_bf16(a, qf[ks], sc[blk], 0, 0, 0); } }
;             float mx = -INFINITY;
; #pragma unroll
;             for (int blk = 0; blk < 4; ++blk)
; #pragma unroll
;                 for (int e = 0; e < 4; ++e) { sc[blk][e] *= LOG2E; mx = fmaxf(mx, sc[blk][e]); }
;             mx = fmaxf(mx, __shfl_xor(mx, 16)); mx = fmaxf(mx, __shfl_xor(mx, 32));
;             const float mnew = fmaxf(m, mx); const float corr = __builtin_amdgcn_exp2f(m - mnew); m = mnew;
;             float ps = 0.f;
; #pragma unroll
;             for (int blk = 0; blk < 4; ++blk)
; #pragma unroll
;                 for (int e = 0; e < 4; ++e) { sc[blk][e] = __builtin_amdgcn_exp2f(sc[blk][e] - mnew); ps += sc[blk][e]; }
.LBB0_145:
	v_add_u32_e32 v157, v154, v146
	s_barrier
	s_waitcnt vmcnt(4)
	ds_write_b128 v157, v[110:113]
	ds_write_b128 v157, v[106:109] offset:16
	ds_write_b128 v157, v[102:105] offset:32
	ds_write_b128 v157, v[98:101] offset:48
	s_waitcnt vmcnt(0)
	ds_write_b128 v155, v[126:129] offset:33792
	ds_write_b128 v155, v[122:125] offset:33808
	ds_write_b128 v155, v[118:121] offset:33824
	ds_write_b128 v155, v[114:117] offset:33840
	v_lshl_add_u64 v[126:127], v[148:149], 0, s[44:45]
	v_mov_b32_e32 v158, v130
	s_waitcnt lgkmcnt(0)
	s_barrier
	ds_read_b128 v[204:207], v153
	ds_read_b128 v[208:211], v153 offset:64
	ds_read_b128 v[212:215], v153 offset:128
	ds_read_b128 v[216:219], v153 offset:192
	ds_read_b128 v[220:223], v153 offset:256
	ds_read_b128 v[224:227], v153 offset:320
	ds_read_b128 v[228:231], v153 offset:384
	ds_read_b128 v[232:235], v153 offset:448
	ds_read_b128 v[236:239], v153 offset:8448
	ds_read_b128 v[240:243], v153 offset:8512
	ds_read_b128 v[244:247], v153 offset:8576
	global_load_dwordx4 v[98:101], v[126:127], off offset:-2000
	global_load_dwordx4 v[102:105], v[126:127], off offset:-2016
	global_load_dwordx4 v[106:109], v[126:127], off offset:-2032
	global_load_dwordx4 v[110:113], v[126:127], off offset:-2048
	global_load_dwordx4 v[114:117], v[126:127], off offset:48
	global_load_dwordx4 v[118:121], v[126:127], off offset:32
	global_load_dwordx4 v[122:125], v[126:127], off offset:16
	s_nop 0
	global_load_dwordx4 v[126:129], v[126:127], off
	s_waitcnt lgkmcnt(10)
	s_nop 0
	s_nop 0
	v_mfma_f32_16x16x32_bf16 v[130:133], v[204:207], v[6:9], 0
	ds_read_b128 v[204:207], v153 offset:8640
	v_mov_b32_e32 v150, v156
	s_add_u32 s44, s44, 0x80000
	s_waitcnt lgkmcnt(10)
	v_mfma_f32_16x16x32_bf16 v[130:133], v[208:211], v[2:5], v[130:133]
	ds_read_b128 v[208:211], v153 offset:8704
	s_nop 0
	s_addc_u32 s45, s45, 0
	s_waitcnt lgkmcnt(10)
	v_mfma_f32_16x16x32_bf16 v[130:133], v[212:215], v[10:13], v[130:133]
	ds_read_b128 v[212:215], v153 offset:8768
	s_nop 0
	s_cmp_eq_u32 s44, 0x180000
	s_waitcnt lgkmcnt(10)
	v_mfma_f32_16x16x32_bf16 v[130:133], v[216:219], v[14:17], v[130:133]
	ds_read_b128 v[216:219], v153 offset:8832
	s_waitcnt lgkmcnt(10)
	v_mfma_f32_16x16x32_bf16 v[130:133], v[220:223], v[18:21], v[130:133]
	ds_read_b128 v[220:223], v153 offset:8896
	s_waitcnt lgkmcnt(10)
	v_mfma_f32_16x16x32_bf16 v[130:133], v[224:227], v[22:25], v[130:133]
	ds_read_b128 v[224:227], v153 offset:16896
	s_waitcnt lgkmcnt(10)
	v_mfma_f32_16x16x32_bf16 v[130:133], v[228:231], v[26:29], v[130:133]
	ds_read_b128 v[228:231], v153 offset:16960
	s_waitcnt lgkmcnt(10)
	v_mfma_f32_16x16x32_bf16 v[130:133], v[232:235], v[30:33], v[130:133]
	ds_read_b128 v[232:235], v153 offset:17024
	s_nop 6
	v_mul_f32_e32 v156, 0x3fb8aa3b, v130
	s_waitcnt lgkmcnt(10)
	v_mfma_f32_16x16x32_bf16 v[134:137], v[236:239], v[6:9], 0
	ds_read_b128 v[236:239], v153 offset:17088
	v_mul_f32_e32 v159, 0x3fb8aa3b, v131
	v_max3_f32 v156, v156, s78, v159
	v_mul_f32_e32 v159, 0x3fb8aa3b, v132
	s_waitcnt lgkmcnt(10)
	v_mfma_f32_16x16x32_bf16 v[134:137], v[240:243], v[2:5], v[134:137]
	ds_read_b128 v[240:243], v153 offset:17152
	v_mul_f32_e32 v160, 0x3fb8aa3b, v133
	v_max3_f32 v156, v156, v159, v160
	s_waitcnt lgkmcnt(10)
	v_mfma_f32_16x16x32_bf16 v[134:137], v[244:247], v[10:13], v[134:137]
	ds_read_b128 v[244:247], v153 offset:17216
	s_waitcnt lgkmcnt(10)
	v_mfma_f32_16x16x32_bf16 v[134:137], v[204:207], v[14:17], v[134:137]
	ds_read_b128 v[204:207], v153 offset:17280
	s_waitcnt lgkmcnt(10)
	v_mfma_f32_16x16x32_bf16 v[134:137], v[208:211], v[18:21], v[134:137]
	ds_read_b128 v[208:211], v153 offset:17344
	s_waitcnt lgkmcnt(10)
	v_mfma_f32_16x16x32_bf16 v[134:137], v[212:215], v[22:25], v[134:137]
	ds_read_b128 v[212:215], v153 offset:25344
	s_waitcnt lgkmcnt(10)
	v_mfma_f32_16x16x32_bf16 v[134:137], v[216:219], v[26:29], v[134:137]
	ds_read_b128 v[216:219], v153 offset:25408
	s_waitcnt lgkmcnt(10)
	v_mfma_f32_16x16x32_bf16 v[134:137], v[220:223], v[30:33], v[134:137]
	ds_read_b128 v[220:223], v153 offset:25472
	s_nop 6
	v_mul_f32_e32 v159, 0x3fb8aa3b, v134
	s_waitcnt lgkmcnt(10)
	v_mfma_f32_16x16x32_bf16 v[138:141], v[224:227], v[6:9], 0
	ds_read_b128 v[224:227], v153 offset:25536
	v_mul_f32_e32 v160, 0x3fb8aa3b, v135
	v_max3_f32 v156, v156, v159, v160
	v_mul_f32_e32 v159, 0x3fb8aa3b, v136
	s_waitcnt lgkmcnt(10)
	v_mfma_f32_16x16x32_bf16 v[138:141], v[228:231], v[2:5], v[138:141]
	ds_read_b128 v[228:231], v153 offset:25600
	v_mul_f32_e32 v160, 0x3fb8aa3b, v137
	v_max3_f32 v156, v156, v159, v160
	s_waitcnt lgkmcnt(10)
	v_mfma_f32_16x16x32_bf16 v[138:141], v[232:235], v[10:13], v[138:141]
	ds_read_b128 v[232:235], v153 offset:25664
	s_waitcnt lgkmcnt(10)
	v_mfma_f32_16x16x32_bf16 v[138:141], v[236:239], v[14:17], v[138:141]
	ds_read_b128 v[236:239], v153 offset:25728
	s_waitcnt lgkmcnt(10)
	v_mfma_f32_16x16x32_bf16 v[138:141], v[240:243], v[18:21], v[138:141]
	ds_read_b128 v[240:243], v153 offset:25792
	s_waitcnt lgkmcnt(10)
	v_mfma_f32_16x16x32_bf16 v[138:141], v[244:247], v[22:25], v[138:141]
	ds_read_b64_tr_b16 v[244:245], v152 offset:33792
	ds_read_b64_tr_b16 v[246:247], v152 offset:42496
	s_waitcnt lgkmcnt(11)
	v_mfma_f32_16x16x32_bf16 v[138:141], v[204:207], v[26:29], v[138:141]
	ds_read_b64_tr_b16 v[204:205], v152 offset:33856
	ds_read_b64_tr_b16 v[206:207], v152 offset:42560
	s_waitcnt lgkmcnt(12)
	v_mfma_f32_16x16x32_bf16 v[138:141], v[208:211], v[30:33], v[138:141]
	s_nop 0
	s_nop 6
	v_mul_f32_e32 v159, 0x3fb8aa3b, v138
	s_waitcnt lgkmcnt(11)
; #define LAS __attribute__((address_space(3)))
; __device__ __forceinline__ void phase_xattn(CArgs& A, int l, unsigned char* lds, int tid) {
;     ...
;             float mx = -INFINITY;
; #pragma unroll
;             for (int blk = 0; blk < 4; ++blk)
; #pragma unroll
;                 for (int e = 0; e < 4; ++e) { sc[blk][e] *= LOG2E; mx = fmaxf(mx, sc[blk][e]); }
;             mx = fmaxf(mx, __shfl_xor(mx, 16)); mx = fmaxf(mx, __shfl_xor(mx, 32));
;             const float mnew = fmaxf(m, mx); const float corr = __builtin_amdgcn_exp2f(m - mnew); m = mnew;
;             float ps = 0.f;
; #pragma unroll
;             for (int blk = 0; blk < 4; ++blk)
; #pragma unroll
;                 for (int e = 0; e < 4; ++e) { sc[blk][e] = __builtin_amdgcn_exp2f(sc[blk][e] - mnew); ps += sc[blk][e]; }
;             lsum = lsum * corr + ps;
; #pragma unroll
;             for (int i = 0; i < 16; ++i) o[i] *= corr;
; #pragma unroll
;             for (int m2 = 0; m2 < 2; ++m2) {
;                 const bf16x8 pb = pack_frag(sc[2 * m2][0], sc[2 * m2][1], sc[2 * m2][2], sc[2 * m2][3], sc[2 * m2 + 1][0], sc[2 * m2 + 1][1], sc[2 * m2 + 1][2], sc[2 * m2 + 1][3]);
; #pragma unroll
;                 for (int db = 0; db < 16; ++db) { const unsigned char* vp = Vt + (32 * m2 + 4 * g + (r >> 2)) * XA_VP + (16 * db + 4 * (r & 3)) * 2;
;                     const s16x4 lo = __builtin_amdgcn_ds_read_tr16_b64_v4i16((LAS s16x4*)vp), hi = __builtin_amdgcn_ds_read_tr16_b64_v4i16((LAS s16x4*)(vp + 16 * XA_VP));
;                     bf16x8 av; av[0] = lo[0]; av[1] = lo[1]; av[2] = lo[2]; av[3] = lo[3]; av[4] = hi[0]; av[5] = hi[1]; av[6] = hi[2]; av[7] = hi[3];
;                     o[db] = __builtin_amdgcn_mfma_f32_16x16x32_bf16(av, pb, o[db], 0, 0, 0); }
	v_mfma_f32_16x16x32_bf16 v[192:195], v[212:215], v[6:9], 0
	ds_read_b64_tr_b16 v[208:209], v152 offset:33888
	ds_read_b64_tr_b16 v[210:211], v152 offset:42592
	v_mul_f32_e32 v160, 0x3fb8aa3b, v139
	v_max3_f32 v156, v156, v159, v160
	v_mul_f32_e32 v159, 0x3fb8aa3b, v140
	s_waitcnt lgkmcnt(12)
	v_mfma_f32_16x16x32_bf16 v[192:195], v[216:219], v[2:5], v[192:195]
	s_nop 0
	v_mul_f32_e32 v160, 0x3fb8aa3b, v141
	v_max3_f32 v156, v156, v159, v160
	s_waitcnt lgkmcnt(11)
	v_mfma_f32_16x16x32_bf16 v[192:195], v[220:223], v[10:13], v[192:195]
	ds_read_b64_tr_b16 v[212:213], v152 offset:33920
	ds_read_b64_tr_b16 v[214:215], v152 offset:42624
	s_waitcnt lgkmcnt(12)
	v_mfma_f32_16x16x32_bf16 v[192:195], v[224:227], v[14:17], v[192:195]
	s_waitcnt lgkmcnt(11)
	s_nop 0
	v_mfma_f32_16x16x32_bf16 v[192:195], v[228:231], v[18:21], v[192:195]
	ds_read_b64_tr_b16 v[216:217], v152 offset:33952
	ds_read_b64_tr_b16 v[218:219], v152 offset:42656
	s_waitcnt lgkmcnt(12)
	v_mfma_f32_16x16x32_bf16 v[192:195], v[232:235], v[22:25], v[192:195]
	s_waitcnt lgkmcnt(11)
	s_nop 0
	v_mfma_f32_16x16x32_bf16 v[192:195], v[236:239], v[26:29], v[192:195]
	ds_read_b64_tr_b16 v[220:221], v152 offset:33984
	ds_read_b64_tr_b16 v[222:223], v152 offset:42688
	s_waitcnt lgkmcnt(12)
	v_mfma_f32_16x16x32_bf16 v[192:195], v[240:243], v[30:33], v[192:195]
	s_nop 7
	v_mul_f32_e32 v159, 0x3fb8aa3b, v192
	v_mul_f32_e32 v160, 0x3fb8aa3b, v193
	v_max3_f32 v156, v156, v159, v160
	v_mul_f32_e32 v159, 0x3fb8aa3b, v194
	v_mul_f32_e32 v160, 0x3fb8aa3b, v195
	v_max3_f32 v156, v156, v159, v160
	ds_bpermute_b32 v159, v151, v156
	s_waitcnt lgkmcnt(0)
	v_max_f32_e32 v159, v159, v159
	v_max_f32_e32 v156, v156, v159
	ds_bpermute_b32 v159, v147, v156
	s_waitcnt lgkmcnt(0)
	v_max3_f32 v156, v150, v156, v159
	v_fma_f32 v132, v132, s83, -v156
	v_exp_f32_e32 v160, v132
	v_fma_f32 v132, v133, s83, -v156
	v_fma_f32 v130, v130, s83, -v156
	v_exp_f32_e32 v133, v132
	v_fma_f32 v132, v134, s83, -v156
	v_exp_f32_e32 v159, v130
	v_fma_f32 v131, v131, s83, -v156
	v_exp_f32_e32 v134, v132
	v_fma_f32 v132, v135, s83, -v156
	v_exp_f32_e32 v131, v131
	v_exp_f32_e32 v135, v132
	v_fma_f32 v132, v136, s83, -v156
	v_exp_f32_e32 v136, v132
	v_fma_f32 v132, v137, s83, -v156
	v_exp_f32_e32 v137, v132
	v_fma_f32 v132, v138, s83, -v156
	v_add_f32_e32 v130, 0, v159
	v_exp_f32_e32 v161, v132
	v_fma_f32 v132, v139, s83, -v156
	v_add_f32_e32 v130, v131, v130
	v_exp_f32_e32 v196, v132
	v_fma_f32 v132, v140, s83, -v156
	v_add_f32_e32 v130, v160, v130
	v_exp_f32_e32 v140, v132
	v_fma_f32 v132, v141, s83, -v156
	v_add_f32_e32 v130, v133, v130
	v_exp_f32_e32 v141, v132
	v_fma_f32 v132, v192, s83, -v156
	v_add_f32_e32 v130, v134, v130
	v_exp_f32_e32 v197, v132
	v_fma_f32 v132, v193, s83, -v156
	v_sub_f32_e32 v150, v150, v156
	v_add_f32_e32 v130, v135, v130
	v_exp_f32_e32 v198, v132
	v_fma_f32 v132, v194, s83, -v156
	v_exp_f32_e32 v150, v150
	v_add_f32_e32 v130, v136, v130
	v_exp_f32_e32 v199, v132
	v_fma_f32 v132, v195, s83, -v156
	v_add_f32_e32 v130, v137, v130
	v_exp_f32_e32 v200, v132
	v_cvt_pk_bf16_f32 v132, v159, v131
	v_cvt_pk_bf16_f32 v133, v160, v133
	v_cvt_pk_bf16_f32 v134, v134, v135
	v_cvt_pk_bf16_f32 v135, v136, v137
	s_nop 0
	s_nop 0
	s_nop 0
	v_pk_mul_f32 v[88:89], v[88:89], v[150:151] op_sel_hi:[1,0]
	v_pk_mul_f32 v[86:87], v[86:87], v[150:151] op_sel_hi:[1,0]
	s_nop 0
	v_pk_mul_f32 v[64:65], v[64:65], v[150:151] op_sel_hi:[1,0]
	s_nop 0
	v_mfma_f32_16x16x32_bf16 v[86:89], v[244:247], v[132:135], v[86:89]
	ds_read_b64_tr_b16 v[224:225], v152 offset:34016
	ds_read_b64_tr_b16 v[226:227], v152 offset:42720
	ds_read_b64_tr_b16 v[228:229], v152 offset:34048
	ds_read_b64_tr_b16 v[230:231], v152 offset:42752
	ds_read_b64_tr_b16 v[232:233], v152 offset:34080
	ds_read_b64_tr_b16 v[234:235], v152 offset:42784
	ds_read_b64_tr_b16 v[236:237], v152 offset:34112
	ds_read_b64_tr_b16 v[238:239], v152 offset:42816
	ds_read_b64_tr_b16 v[240:241], v152 offset:34144
	ds_read_b64_tr_b16 v[242:243], v152 offset:42848
	ds_read_b64_tr_b16 v[244:245], v152 offset:34176
	ds_read_b64_tr_b16 v[246:247], v152 offset:42880
	v_pk_mul_f32 v[62:63], v[62:63], v[150:151] op_sel_hi:[1,0]
	v_pk_mul_f32 v[72:73], v[72:73], v[150:151] op_sel_hi:[1,0]
	v_pk_mul_f32 v[70:71], v[70:71], v[150:151] op_sel_hi:[1,0]
	s_nop 0
	v_mfma_f32_16x16x32_bf16 v[62:65], v[204:207], v[132:135], v[62:65]
	s_nop 0
	s_nop 0
	v_pk_mul_f32 v[80:81], v[80:81], v[150:151] op_sel_hi:[1,0]
	v_pk_mul_f32 v[78:79], v[78:79], v[150:151] op_sel_hi:[1,0]
	s_nop 0
	v_mfma_f32_16x16x32_bf16 v[70:73], v[208:211], v[132:135], v[70:73]
	s_nop 0
	s_nop 0
	v_pk_mul_f32 v[92:93], v[92:93], v[150:151] op_sel_hi:[1,0]
	v_pk_mul_f32 v[90:91], v[90:91], v[150:151] op_sel_hi:[1,0]
	s_nop 0
	v_mfma_f32_16x16x32_bf16 v[78:81], v[212:215], v[132:135], v[78:81]
	s_nop 0
	s_nop 0
	v_pk_mul_f32 v[84:85], v[84:85], v[150:151] op_sel_hi:[1,0]
	v_pk_mul_f32 v[82:83], v[82:83], v[150:151] op_sel_hi:[1,0]
	s_nop 0
	v_mfma_f32_16x16x32_bf16 v[90:93], v[216:219], v[132:135], v[90:93]
	s_nop 0
	s_nop 0
	v_pk_mul_f32 v[96:97], v[96:97], v[150:151] op_sel_hi:[1,0]
	v_pk_mul_f32 v[94:95], v[94:95], v[150:151] op_sel_hi:[1,0]
	s_nop 0
	v_mfma_f32_16x16x32_bf16 v[82:85], v[220:223], v[132:135], v[82:85]
	s_nop 0
	s_nop 0
	v_pk_mul_f32 v[76:77], v[76:77], v[150:151] op_sel_hi:[1,0]
	v_pk_mul_f32 v[74:75], v[74:75], v[150:151] op_sel_hi:[1,0]
	s_waitcnt lgkmcnt(10)
	v_mfma_f32_16x16x32_bf16 v[94:97], v[224:227], v[132:135], v[94:97]
	ds_read_b64_tr_b16 v[204:205], v152 offset:34208
	ds_read_b64_tr_b16 v[206:207], v152 offset:42912
	v_pk_mul_f32 v[60:61], v[60:61], v[150:151] op_sel_hi:[1,0]
	v_pk_mul_f32 v[58:59], v[58:59], v[150:151] op_sel_hi:[1,0]
	s_waitcnt lgkmcnt(10)
; #define LAS __attribute__((address_space(3)))
; __device__ __forceinline__ void phase_xattn(CArgs& A, int l, unsigned char* lds, int tid) {
;     ...
;             lsum = lsum * corr + ps;
; #pragma unroll
;             for (int i = 0; i < 16; ++i) o[i] *= corr;
; #pragma unroll
;             for (int m2 = 0; m2 < 2; ++m2) {
;                 const bf16x8 pb = pack_frag(sc[2 * m2][0], sc[2 * m2][1], sc[2 * m2][2], sc[2 * m2][3], sc[2 * m2 + 1][0], sc[2 * m2 + 1][1], sc[2 * m2 + 1][2], sc[2 * m2 + 1][3]);
; #pragma unroll
;                 for (int db = 0; db < 16; ++db) { const unsigned char* vp = Vt + (32 * m2 + 4 * g + (r >> 2)) * XA_VP + (16 * db + 4 * (r & 3)) * 2;
;                     const s16x4 lo = __builtin_amdgcn_ds_read_tr16_b64_v4i16((LAS s16x4*)vp), hi = __builtin_amdgcn_ds_read_tr16_b64_v4i16((LAS s16x4*)(vp + 16 * XA_VP));
;                     bf16x8 av; av[0] = lo[0]; av[1] = lo[1]; av[2] = lo[2]; av[3] = lo[3]; av[4] = hi[0]; av[5] = hi[1]; av[6] = hi[2]; av[7] = hi[3];
;                     o[db] = __builtin_amdgcn_mfma_f32_16x16x32_bf16(av, pb, o[db], 0, 0, 0); }
	v_mfma_f32_16x16x32_bf16 v[74:77], v[228:231], v[132:135], v[74:77]
	ds_read_b64_tr_b16 v[208:209], v152 offset:34240
	ds_read_b64_tr_b16 v[210:211], v152 offset:42944
	v_pk_mul_f32 v[56:57], v[56:57], v[150:151] op_sel_hi:[1,0]
	v_pk_mul_f32 v[54:55], v[54:55], v[150:151] op_sel_hi:[1,0]
	s_waitcnt lgkmcnt(10)
	v_mfma_f32_16x16x32_bf16 v[58:61], v[232:235], v[132:135], v[58:61]
	ds_read_b64_tr_b16 v[212:213], v152 offset:33824
	ds_read_b64_tr_b16 v[214:215], v152 offset:42528
	v_pk_mul_f32 v[52:53], v[52:53], v[150:151] op_sel_hi:[1,0]
	v_pk_mul_f32 v[50:51], v[50:51], v[150:151] op_sel_hi:[1,0]
	s_waitcnt lgkmcnt(10)
	v_mfma_f32_16x16x32_bf16 v[54:57], v[236:239], v[132:135], v[54:57]
	ds_read_b64_tr_b16 v[216:217], v152 offset:34272
	ds_read_b64_tr_b16 v[218:219], v152 offset:42976
	v_pk_mul_f32 v[48:49], v[48:49], v[150:151] op_sel_hi:[1,0]
	v_pk_mul_f32 v[46:47], v[46:47], v[150:151] op_sel_hi:[1,0]
	s_waitcnt lgkmcnt(10)
	v_mfma_f32_16x16x32_bf16 v[50:53], v[240:243], v[132:135], v[50:53]
	ds_read_b64_tr_b16 v[220:221], v152 offset:51200
	ds_read_b64_tr_b16 v[222:223], v152 offset:59904
	v_pk_mul_f32 v[44:45], v[44:45], v[150:151] op_sel_hi:[1,0]
	v_pk_mul_f32 v[42:43], v[42:43], v[150:151] op_sel_hi:[1,0]
	s_waitcnt lgkmcnt(10)
	v_mfma_f32_16x16x32_bf16 v[46:49], v[244:247], v[132:135], v[46:49]
	ds_read_b64_tr_b16 v[224:225], v152 offset:51264
	ds_read_b64_tr_b16 v[226:227], v152 offset:59968
	v_pk_mul_f32 v[40:41], v[40:41], v[150:151] op_sel_hi:[1,0]
	v_pk_mul_f32 v[38:39], v[38:39], v[150:151] op_sel_hi:[1,0]
	s_waitcnt lgkmcnt(10)
	v_mfma_f32_16x16x32_bf16 v[42:45], v[204:207], v[132:135], v[42:45]
	ds_read_b64_tr_b16 v[228:229], v152 offset:51296
	ds_read_b64_tr_b16 v[230:231], v152 offset:60000
	v_pk_mul_f32 v[68:69], v[68:69], v[150:151] op_sel_hi:[1,0]
	v_pk_mul_f32 v[66:67], v[66:67], v[150:151] op_sel_hi:[1,0]
	s_waitcnt lgkmcnt(10)
	v_mfma_f32_16x16x32_bf16 v[38:41], v[208:211], v[132:135], v[38:41]
	ds_read_b64_tr_b16 v[232:233], v152 offset:51328
	ds_read_b64_tr_b16 v[234:235], v152 offset:60032
	v_pk_mul_f32 v[36:37], v[36:37], v[150:151] op_sel_hi:[1,0]
	v_pk_mul_f32 v[34:35], v[34:35], v[150:151] op_sel_hi:[1,0]
	s_waitcnt lgkmcnt(10)
	v_mfma_f32_16x16x32_bf16 v[66:69], v[212:215], v[132:135], v[66:69]
	ds_read_b64_tr_b16 v[236:237], v152 offset:51360
	ds_read_b64_tr_b16 v[238:239], v152 offset:60064
	v_add_f32_e32 v130, v161, v130
	v_add_f32_e32 v130, v196, v130
	v_add_f32_e32 v130, v140, v130
	s_waitcnt lgkmcnt(10)
	v_mfma_f32_16x16x32_bf16 v[34:37], v[216:219], v[132:135], v[34:37]
	ds_read_b64_tr_b16 v[240:241], v152 offset:51392
	ds_read_b64_tr_b16 v[242:243], v152 offset:60096
	v_cvt_pk_bf16_f32 v132, v161, v196
	v_cvt_pk_bf16_f32 v133, v140, v141
	v_cvt_pk_bf16_f32 v134, v197, v198
	v_cvt_pk_bf16_f32 v135, v199, v200
	s_waitcnt lgkmcnt(10)
	s_nop 0
	s_nop 0
	s_nop 0
	v_mfma_f32_16x16x32_bf16 v[86:89], v[220:223], v[132:135], v[86:89]
	ds_read_b64_tr_b16 v[244:245], v152 offset:51424
	ds_read_b64_tr_b16 v[246:247], v152 offset:60128
	s_nop 0
	v_add_f32_e32 v130, v141, v130
	s_waitcnt lgkmcnt(10)
	v_mfma_f32_16x16x32_bf16 v[62:65], v[224:227], v[132:135], v[62:65]
	ds_read_b64_tr_b16 v[204:205], v152 offset:51456
	ds_read_b64_tr_b16 v[206:207], v152 offset:60160
	v_add_f32_e32 v130, v197, v130
	v_add_f32_e32 v130, v198, v130
	s_waitcnt lgkmcnt(10)
	v_mfma_f32_16x16x32_bf16 v[70:73], v[228:231], v[132:135], v[70:73]
	ds_read_b64_tr_b16 v[208:209], v152 offset:51488
	ds_read_b64_tr_b16 v[210:211], v152 offset:60192
	v_add_f32_e32 v130, v199, v130
	v_add_f32_e32 v130, v200, v130
	s_waitcnt lgkmcnt(10)
	v_mfma_f32_16x16x32_bf16 v[78:81], v[232:235], v[132:135], v[78:81]
	ds_read_b64_tr_b16 v[212:213], v152 offset:51520
	ds_read_b64_tr_b16 v[214:215], v152 offset:60224
	v_fmac_f32_e32 v130, v158, v150
	s_waitcnt lgkmcnt(10)
	v_mfma_f32_16x16x32_bf16 v[90:93], v[236:239], v[132:135], v[90:93]
	ds_read_b64_tr_b16 v[216:217], v152 offset:51552
	ds_read_b64_tr_b16 v[218:219], v152 offset:60256
	s_waitcnt lgkmcnt(10)
	v_mfma_f32_16x16x32_bf16 v[82:85], v[240:243], v[132:135], v[82:85]
	ds_read_b64_tr_b16 v[220:221], v152 offset:51584
	ds_read_b64_tr_b16 v[222:223], v152 offset:60288
	s_waitcnt lgkmcnt(10)
	v_mfma_f32_16x16x32_bf16 v[94:97], v[244:247], v[132:135], v[94:97]
	ds_read_b64_tr_b16 v[224:225], v152 offset:51616
	ds_read_b64_tr_b16 v[226:227], v152 offset:60320
	s_waitcnt lgkmcnt(10)
	v_mfma_f32_16x16x32_bf16 v[74:77], v[204:207], v[132:135], v[74:77]
	ds_read_b64_tr_b16 v[228:229], v152 offset:51648
	ds_read_b64_tr_b16 v[230:231], v152 offset:60352
	s_waitcnt lgkmcnt(10)
	v_mfma_f32_16x16x32_bf16 v[58:61], v[208:211], v[132:135], v[58:61]
	ds_read_b64_tr_b16 v[232:233], v152 offset:51232
	ds_read_b64_tr_b16 v[234:235], v152 offset:59936
	s_waitcnt lgkmcnt(10)
	v_mfma_f32_16x16x32_bf16 v[54:57], v[212:215], v[132:135], v[54:57]
	ds_read_b64_tr_b16 v[236:237], v152 offset:51680
	ds_read_b64_tr_b16 v[238:239], v152 offset:60384
	s_waitcnt lgkmcnt(10)
	v_mfma_f32_16x16x32_bf16 v[50:53], v[216:219], v[132:135], v[50:53]
	s_waitcnt lgkmcnt(8)
	s_nop 0
	s_nop 0
	v_mfma_f32_16x16x32_bf16 v[46:49], v[220:223], v[132:135], v[46:49]
	s_waitcnt lgkmcnt(6)
	s_nop 0
	s_nop 0
	v_mfma_f32_16x16x32_bf16 v[42:45], v[224:227], v[132:135], v[42:45]
	s_waitcnt lgkmcnt(4)
	s_nop 0
	s_nop 0
	v_mfma_f32_16x16x32_bf16 v[38:41], v[228:231], v[132:135], v[38:41]
	s_waitcnt lgkmcnt(2)
	s_nop 0
	v_mfma_f32_16x16x32_bf16 v[66:69], v[232:235], v[132:135], v[66:69]
	s_waitcnt lgkmcnt(0)
	v_mfma_f32_16x16x32_bf16 v[34:37], v[236:239], v[132:135], v[34:37]
	s_cbranch_scc0 .LBB0_145
	s_barrier
; __device__ __forceinline__ void phase_xattn(CArgs& A, int l, unsigned char* lds, int tid) {
;     ...
;             __syncthreads();
; #pragma unroll
;             for (int i = 0; i < 4; ++i) *(u32x4*)(Ks + skey * XA_KP + (sdc + i * 8) * 2) = kr[i];
; #pragma unroll
;             for (int i = 0; i < 4; ++i) *(u32x4*)(Vt + skey * XA_VP + (sdc + i * 8) * 2) = vr[i];
;             __syncthreads();
;             if (kt + 1 < 4) {
; #pragma unroll
;                 for (int i = 0; i < 4; ++i) { kr[i] = *(const u32x4*)(kvbase + (size_t)(kt + 1) * 64 * 4096 + i * 8); vr[i] = *(const u32x4*)(kvbase + (size_t)(kt + 1) * 64 * 4096 + 1024 + i * 8); } }
;             f32x4 sc[4];
; #pragma unroll
;             for (int blk = 0; blk < 4; ++blk) { sc[blk] = (f32x4){0.f, 0.f, 0.f, 0.f};
; #pragma unroll
;                 for (int ks = 0; ks < 8; ++ks) { const bf16x8 a = *(const bf16x8*)(Ks + (blk * 16 + r) * XA_KP + (32 * ks + 8 * g) * 2);
;                     sc[blk] = __builtin_amdgcn_mfma_f32_16x16x32_bf16(a, qf[ks], sc[blk], 0, 0, 0); } }
	s_waitcnt vmcnt(4)
	ds_write_b128 v157, v[110:113]
	ds_write_b128 v157, v[106:109] offset:16
	ds_write_b128 v157, v[102:105] offset:32
	ds_write_b128 v157, v[98:101] offset:48
	s_waitcnt vmcnt(0)
	ds_write_b128 v155, v[126:129] offset:33792
	ds_write_b128 v155, v[122:125] offset:33808
	ds_write_b128 v155, v[118:121] offset:33824
	ds_write_b128 v155, v[114:117] offset:33840
	s_waitcnt lgkmcnt(0)
	s_barrier
	ds_read_b128 v[204:207], v153
	ds_read_b128 v[208:211], v153 offset:64
	ds_read_b128 v[212:215], v153 offset:128
	ds_read_b128 v[216:219], v153 offset:192
	ds_read_b128 v[220:223], v153 offset:256
	ds_read_b128 v[224:227], v153 offset:320
	ds_read_b128 v[228:231], v153 offset:384
	ds_read_b128 v[232:235], v153 offset:448
	ds_read_b128 v[236:239], v153 offset:8448
	ds_read_b128 v[240:243], v153 offset:8512
	ds_read_b128 v[244:247], v153 offset:8576
	s_waitcnt lgkmcnt(10)
	v_mfma_f32_16x16x32_bf16 v[98:101], v[204:207], v[6:9], 0
	ds_read_b128 v[204:207], v153 offset:8640
	s_lshl_b32 s14, s36, 1
	s_waitcnt lgkmcnt(10)
	s_nop 0
	v_mfma_f32_16x16x32_bf16 v[98:101], v[208:211], v[2:5], v[98:101]
	ds_read_b128 v[208:211], v153 offset:8704
	s_waitcnt lgkmcnt(10)
	v_mfma_f32_16x16x32_bf16 v[98:101], v[212:215], v[10:13], v[98:101]
	ds_read_b128 v[212:215], v153 offset:8768
	s_waitcnt lgkmcnt(10)
	v_mfma_f32_16x16x32_bf16 v[98:101], v[216:219], v[14:17], v[98:101]
	ds_read_b128 v[216:219], v153 offset:8832
	s_waitcnt lgkmcnt(10)
	v_mfma_f32_16x16x32_bf16 v[98:101], v[220:223], v[18:21], v[98:101]
	ds_read_b128 v[220:223], v153 offset:8896
	s_waitcnt lgkmcnt(10)
	v_mfma_f32_16x16x32_bf16 v[98:101], v[224:227], v[22:25], v[98:101]
	ds_read_b128 v[224:227], v153 offset:16896
	s_waitcnt lgkmcnt(10)
	v_mfma_f32_16x16x32_bf16 v[98:101], v[228:231], v[26:29], v[98:101]
	ds_read_b128 v[228:231], v153 offset:16960
	s_waitcnt lgkmcnt(10)
	v_mfma_f32_16x16x32_bf16 v[98:101], v[232:235], v[30:33], v[98:101]
	ds_read_b128 v[232:235], v153 offset:17024
	s_waitcnt lgkmcnt(10)
	v_mfma_f32_16x16x32_bf16 v[102:105], v[236:239], v[6:9], 0
	ds_read_b128 v[236:239], v153 offset:17088
	s_waitcnt lgkmcnt(10)
	v_mfma_f32_16x16x32_bf16 v[102:105], v[240:243], v[2:5], v[102:105]
	ds_read_b128 v[240:243], v153 offset:17152
	s_waitcnt lgkmcnt(10)
	v_mfma_f32_16x16x32_bf16 v[102:105], v[244:247], v[10:13], v[102:105]
	ds_read_b128 v[244:247], v153 offset:17216
	s_waitcnt lgkmcnt(10)
	v_mfma_f32_16x16x32_bf16 v[102:105], v[204:207], v[14:17], v[102:105]
	ds_read_b128 v[204:207], v153 offset:17280
	s_waitcnt lgkmcnt(10)
	v_mfma_f32_16x16x32_bf16 v[102:105], v[208:211], v[18:21], v[102:105]
	ds_read_b128 v[208:211], v153 offset:17344
	s_waitcnt lgkmcnt(10)
	v_mfma_f32_16x16x32_bf16 v[102:105], v[212:215], v[22:25], v[102:105]
	ds_read_b128 v[212:215], v153 offset:25344
	s_waitcnt lgkmcnt(10)
	v_mfma_f32_16x16x32_bf16 v[102:105], v[216:219], v[26:29], v[102:105]
	ds_read_b128 v[216:219], v153 offset:25408
	s_waitcnt lgkmcnt(10)
	v_mfma_f32_16x16x32_bf16 v[102:105], v[220:223], v[30:33], v[102:105]
	ds_read_b128 v[220:223], v153 offset:25472
	s_waitcnt lgkmcnt(10)
	v_mfma_f32_16x16x32_bf16 v[106:109], v[224:227], v[6:9], 0
	ds_read_b128 v[224:227], v153 offset:25536
	s_waitcnt lgkmcnt(10)
	v_mfma_f32_16x16x32_bf16 v[106:109], v[228:231], v[2:5], v[106:109]
	ds_read_b128 v[228:231], v153 offset:25600
	s_waitcnt lgkmcnt(10)
	v_mfma_f32_16x16x32_bf16 v[106:109], v[232:235], v[10:13], v[106:109]
	ds_read_b128 v[232:235], v153 offset:25664
	s_waitcnt lgkmcnt(10)
	v_mfma_f32_16x16x32_bf16 v[106:109], v[236:239], v[14:17], v[106:109]
	ds_read_b128 v[236:239], v153 offset:25728
	s_waitcnt lgkmcnt(10)
	v_mfma_f32_16x16x32_bf16 v[106:109], v[240:243], v[18:21], v[106:109]
	ds_read_b128 v[240:243], v153 offset:25792
	s_waitcnt lgkmcnt(10)
	v_mfma_f32_16x16x32_bf16 v[106:109], v[244:247], v[22:25], v[106:109]
	ds_read_b64_tr_b16 v[244:245], v152 offset:33984
	ds_read_b64_tr_b16 v[246:247], v152 offset:42688
	s_waitcnt lgkmcnt(11)
	v_mfma_f32_16x16x32_bf16 v[106:109], v[204:207], v[26:29], v[106:109]
	ds_read_b64_tr_b16 v[204:205], v152 offset:34016
	ds_read_b64_tr_b16 v[206:207], v152 offset:42720
	s_waitcnt lgkmcnt(12)
	v_mfma_f32_16x16x32_bf16 v[106:109], v[208:211], v[30:33], v[106:109]
	s_waitcnt lgkmcnt(11)
	s_nop 0
	v_mfma_f32_16x16x32_bf16 v[6:9], v[212:215], v[6:9], 0
	ds_read_b64_tr_b16 v[208:209], v152 offset:34048
	ds_read_b64_tr_b16 v[210:211], v152 offset:42752
	s_waitcnt lgkmcnt(12)
	v_mfma_f32_16x16x32_bf16 v[2:5], v[216:219], v[2:5], v[6:9]
	s_nop 4
	s_waitcnt lgkmcnt(11)
	s_nop 0
	v_mfma_f32_16x16x32_bf16 v[2:5], v[220:223], v[10:13], v[2:5]
	ds_read_b64_tr_b16 v[212:213], v152 offset:34080
	ds_read_b64_tr_b16 v[214:215], v152 offset:42784
	s_waitcnt lgkmcnt(12)
	v_mfma_f32_16x16x32_bf16 v[2:5], v[224:227], v[14:17], v[2:5]
	s_waitcnt lgkmcnt(11)
	s_nop 0
	v_mfma_f32_16x16x32_bf16 v[2:5], v[228:231], v[18:21], v[2:5]
	ds_read_b64_tr_b16 v[216:217], v152 offset:34112
	ds_read_b64_tr_b16 v[218:219], v152 offset:42816
	s_waitcnt lgkmcnt(12)
	v_mfma_f32_16x16x32_bf16 v[2:5], v[232:235], v[22:25], v[2:5]
	s_waitcnt lgkmcnt(11)
	s_nop 0
	v_mfma_f32_16x16x32_bf16 v[2:5], v[236:239], v[26:29], v[2:5]
	ds_read_b64_tr_b16 v[220:221], v152 offset:34144
	ds_read_b64_tr_b16 v[222:223], v152 offset:42848
	s_waitcnt lgkmcnt(12)
; #define LAS __attribute__((address_space(3)))
; __device__ __forceinline__ void phase_xattn(CArgs& A, int l, unsigned char* lds, int tid) {
;     ...
;             float mx = -INFINITY;
; #pragma unroll
;             for (int blk = 0; blk < 4; ++blk)
; #pragma unroll
;                 for (int e = 0; e < 4; ++e) { sc[blk][e] *= LOG2E; mx = fmaxf(mx, sc[blk][e]); }
;             mx = fmaxf(mx, __shfl_xor(mx, 16)); mx = fmaxf(mx, __shfl_xor(mx, 32));
;             const float mnew = fmaxf(m, mx); const float corr = __builtin_amdgcn_exp2f(m - mnew); m = mnew;
;             float ps = 0.f;
; #pragma unroll
;             for (int blk = 0; blk < 4; ++blk)
; #pragma unroll
;                 for (int e = 0; e < 4; ++e) { sc[blk][e] = __builtin_amdgcn_exp2f(sc[blk][e] - mnew); ps += sc[blk][e]; }
;             lsum = lsum * corr + ps;
; #pragma unroll
;             for (int i = 0; i < 16; ++i) o[i] *= corr;
; #pragma unroll
;             for (int m2 = 0; m2 < 2; ++m2) {
;                 const bf16x8 pb = pack_frag(sc[2 * m2][0], sc[2 * m2][1], sc[2 * m2][2], sc[2 * m2][3], sc[2 * m2 + 1][0], sc[2 * m2 + 1][1], sc[2 * m2 + 1][2], sc[2 * m2 + 1][3]);
; #pragma unroll
;                 for (int db = 0; db < 16; ++db) { const unsigned char* vp = Vt + (32 * m2 + 4 * g + (r >> 2)) * XA_VP + (16 * db + 4 * (r & 3)) * 2;
;                     const s16x4 lo = __builtin_amdgcn_ds_read_tr16_b64_v4i16((LAS s16x4*)vp), hi = __builtin_amdgcn_ds_read_tr16_b64_v4i16((LAS s16x4*)(vp + 16 * XA_VP));
;                     bf16x8 av; av[0] = lo[0]; av[1] = lo[1]; av[2] = lo[2]; av[3] = lo[3]; av[4] = hi[0]; av[5] = hi[1]; av[6] = hi[2]; av[7] = hi[3];
;                     o[db] = __builtin_amdgcn_mfma_f32_16x16x32_bf16(av, pb, o[db], 0, 0, 0); }
	v_mfma_f32_16x16x32_bf16 v[2:5], v[240:243], v[30:33], v[2:5]
	v_mul_f32_e32 v6, 0x3fb8aa3b, v98
	v_mul_f32_e32 v7, 0x3fb8aa3b, v99
	v_max3_f32 v6, v6, s78, v7
	v_mul_f32_e32 v7, 0x3fb8aa3b, v100
	v_mul_f32_e32 v8, 0x3fb8aa3b, v101
	v_max3_f32 v6, v6, v7, v8
	v_mul_f32_e32 v7, 0x3fb8aa3b, v102
	v_mul_f32_e32 v8, 0x3fb8aa3b, v103
	v_max3_f32 v6, v6, v7, v8
	v_mul_f32_e32 v7, 0x3fb8aa3b, v104
	v_mul_f32_e32 v8, 0x3fb8aa3b, v105
	v_max3_f32 v6, v6, v7, v8
	v_mul_f32_e32 v7, 0x3fb8aa3b, v106
	v_mul_f32_e32 v8, 0x3fb8aa3b, v107
	v_max3_f32 v6, v6, v7, v8
	v_mul_f32_e32 v7, 0x3fb8aa3b, v108
	v_mul_f32_e32 v8, 0x3fb8aa3b, v109
	v_max3_f32 v6, v6, v7, v8
	v_mul_f32_e32 v7, 0x3fb8aa3b, v2
	v_mul_f32_e32 v8, 0x3fb8aa3b, v3
	v_max3_f32 v6, v6, v7, v8
	v_mul_f32_e32 v7, 0x3fb8aa3b, v4
	v_mul_f32_e32 v8, 0x3fb8aa3b, v5
	v_max3_f32 v6, v6, v7, v8
	ds_bpermute_b32 v7, v151, v6
	s_waitcnt lgkmcnt(0)
	v_max_f32_e32 v7, v7, v7
	v_max_f32_e32 v6, v6, v7
	ds_bpermute_b32 v7, v147, v6
	s_waitcnt lgkmcnt(0)
	v_max3_f32 v6, v156, v6, v7
	v_sub_f32_e32 v7, v156, v6
	v_exp_f32_e32 v110, v7
	v_fma_f32 v7, v98, s83, -v6
	v_exp_f32_e32 v119, v7
	v_fma_f32 v8, v99, s83, -v6
	v_exp_f32_e32 v120, v8
	v_fma_f32 v8, v100, s83, -v6
	v_exp_f32_e32 v121, v8
	v_fma_f32 v8, v101, s83, -v6
	v_exp_f32_e32 v122, v8
	v_fma_f32 v8, v102, s83, -v6
	v_add_f32_e32 v7, 0, v119
	v_exp_f32_e32 v123, v8
	v_fma_f32 v8, v103, s83, -v6
	v_add_f32_e32 v7, v120, v7
	v_exp_f32_e32 v124, v8
	v_fma_f32 v8, v104, s83, -v6
	v_add_f32_e32 v7, v121, v7
	v_exp_f32_e32 v125, v8
	v_fma_f32 v8, v105, s83, -v6
	v_add_f32_e32 v7, v122, v7
	v_exp_f32_e32 v126, v8
	v_fma_f32 v8, v106, s83, -v6
	v_add_f32_e32 v7, v123, v7
	v_exp_f32_e32 v111, v8
	v_fma_f32 v8, v107, s83, -v6
	v_add_f32_e32 v7, v124, v7
	v_exp_f32_e32 v112, v8
	v_fma_f32 v8, v108, s83, -v6
	v_add_f32_e32 v7, v125, v7
	v_exp_f32_e32 v113, v8
	v_fma_f32 v8, v109, s83, -v6
	v_add_f32_e32 v7, v126, v7
	v_exp_f32_e32 v114, v8
	v_fma_f32 v2, v2, s83, -v6
	v_add_f32_e32 v7, v111, v7
	v_exp_f32_e32 v115, v2
	v_fma_f32 v2, v3, s83, -v6
	v_add_f32_e32 v7, v112, v7
	v_exp_f32_e32 v116, v2
	v_fma_f32 v2, v4, s83, -v6
	v_add_f32_e32 v7, v113, v7
	v_exp_f32_e32 v117, v2
	v_fma_f32 v2, v5, s83, -v6
	v_add_f32_e32 v127, v114, v7
	v_exp_f32_e32 v118, v2
	v_pk_mul_f32 v[2:3], v[34:35], v[110:111] op_sel_hi:[1,0]
	v_add_f32_e32 v34, v115, v127
	v_add_f32_e32 v34, v116, v34
	v_add_f32_e32 v34, v117, v34
	v_pk_mul_f32 v[102:103], v[66:67], v[110:111] op_sel_hi:[1,0]
	v_pk_mul_f32 v[66:67], v[82:83], v[110:111] op_sel_hi:[1,0]
	v_pk_mul_f32 v[32:33], v[76:77], v[110:111] op_sel_hi:[1,0]
	v_pk_mul_f32 v[30:31], v[74:75], v[110:111] op_sel_hi:[1,0]
	v_pk_mul_f32 v[28:29], v[60:61], v[110:111] op_sel_hi:[1,0]
	v_pk_mul_f32 v[26:27], v[58:59], v[110:111] op_sel_hi:[1,0]
	v_pk_mul_f32 v[24:25], v[56:57], v[110:111] op_sel_hi:[1,0]
	v_pk_mul_f32 v[22:23], v[54:55], v[110:111] op_sel_hi:[1,0]
	v_pk_mul_f32 v[20:21], v[52:53], v[110:111] op_sel_hi:[1,0]
	v_pk_mul_f32 v[18:19], v[50:51], v[110:111] op_sel_hi:[1,0]
	v_pk_mul_f32 v[16:17], v[48:49], v[110:111] op_sel_hi:[1,0]
	v_pk_mul_f32 v[14:15], v[46:47], v[110:111] op_sel_hi:[1,0]
	v_pk_mul_f32 v[12:13], v[44:45], v[110:111] op_sel_hi:[1,0]
	v_pk_mul_f32 v[10:11], v[42:43], v[110:111] op_sel_hi:[1,0]
	v_pk_mul_f32 v[8:9], v[40:41], v[110:111] op_sel_hi:[1,0]
	v_pk_mul_f32 v[6:7], v[38:39], v[110:111] op_sel_hi:[1,0]
	v_pk_mul_f32 v[4:5], v[36:37], v[110:111] op_sel_hi:[1,0]
	v_add_f32_e32 v82, v118, v34
	v_cvt_pk_bf16_f32 v74, v119, v120
	v_cvt_pk_bf16_f32 v75, v121, v122
	v_cvt_pk_bf16_f32 v76, v123, v124
	v_cvt_pk_bf16_f32 v77, v125, v126
	s_nop 0
	s_nop 0
	s_nop 0
	s_nop 0
	s_nop 0
	s_nop 0
	s_nop 0
	s_nop 0
	s_nop 0
	s_nop 0
	s_nop 0
	s_nop 0
	s_nop 0
	s_nop 0
	v_pk_mul_f32 v[104:105], v[68:69], v[110:111] op_sel_hi:[1,0]
	v_pk_mul_f32 v[68:69], v[84:85], v[110:111] op_sel_hi:[1,0]
	v_pk_mul_f32 v[100:101], v[64:65], v[110:111] op_sel_hi:[1,0]
	v_pk_mul_f32 v[98:99], v[62:63], v[110:111] op_sel_hi:[1,0]
	s_nop 0
	v_mfma_f32_16x16x32_bf16 v[58:61], v[244:247], v[74:77], v[66:69]
	ds_read_b64_tr_b16 v[224:225], v152 offset:34176
	ds_read_b64_tr_b16 v[226:227], v152 offset:42880
	ds_read_b64_tr_b16 v[228:229], v152 offset:34208
	ds_read_b64_tr_b16 v[230:231], v152 offset:42912
	ds_read_b64_tr_b16 v[232:233], v152 offset:34240
	ds_read_b64_tr_b16 v[234:235], v152 offset:42944
	ds_read_b64_tr_b16 v[236:237], v152 offset:33792
	ds_read_b64_tr_b16 v[238:239], v152 offset:42496
	ds_read_b64_tr_b16 v[240:241], v152 offset:33824
	ds_read_b64_tr_b16 v[242:243], v152 offset:42528
	ds_read_b64_tr_b16 v[244:245], v152 offset:33856
	ds_read_b64_tr_b16 v[246:247], v152 offset:42560
	s_nop 2
	s_nop 0
	s_nop 0
	v_pk_mul_f32 v[64:65], v[96:97], v[110:111] op_sel_hi:[1,0]
	v_pk_mul_f32 v[62:63], v[94:95], v[110:111] op_sel_hi:[1,0]
	v_pk_mul_f32 v[108:109], v[88:89], v[110:111] op_sel_hi:[1,0]
	v_pk_mul_f32 v[106:107], v[86:87], v[110:111] op_sel_hi:[1,0]
	s_nop 0
	v_mfma_f32_16x16x32_bf16 v[62:65], v[204:207], v[74:77], v[62:65]
	s_nop 0
	s_nop 0
	v_pk_mul_f32 v[88:89], v[72:73], v[110:111] op_sel_hi:[1,0]
	v_pk_mul_f32 v[86:87], v[70:71], v[110:111] op_sel_hi:[1,0]
	s_nop 0
	v_mfma_f32_16x16x32_bf16 v[30:33], v[208:211], v[74:77], v[30:33]
	s_nop 0
	s_nop 0
	v_pk_mul_f32 v[80:81], v[80:81], v[110:111] op_sel_hi:[1,0]
	v_pk_mul_f32 v[78:79], v[78:79], v[110:111] op_sel_hi:[1,0]
	s_nop 0
	v_mfma_f32_16x16x32_bf16 v[26:29], v[212:215], v[74:77], v[26:29]
	s_nop 0
	s_nop 0
	v_pk_mul_f32 v[72:73], v[92:93], v[110:111] op_sel_hi:[1,0]
	v_pk_mul_f32 v[70:71], v[90:91], v[110:111] op_sel_hi:[1,0]
	s_nop 0
	v_mfma_f32_16x16x32_bf16 v[22:25], v[216:219], v[74:77], v[22:25]
	s_nop 0
	s_nop 0
	v_fmac_f32_e32 v82, v130, v110
	s_nop 0
	v_mfma_f32_16x16x32_bf16 v[18:21], v[220:223], v[74:77], v[18:21]
	s_waitcnt lgkmcnt(10)
; #define LAS __attribute__((address_space(3)))
; __device__ __forceinline__ void phase_xattn(CArgs& A, int l, unsigned char* lds, int tid) {
;     ...
;             for (int m2 = 0; m2 < 2; ++m2) {
;                 const bf16x8 pb = pack_frag(sc[2 * m2][0], sc[2 * m2][1], sc[2 * m2][2], sc[2 * m2][3], sc[2 * m2 + 1][0], sc[2 * m2 + 1][1], sc[2 * m2 + 1][2], sc[2 * m2 + 1][3]);
; #pragma unroll
;                 for (int db = 0; db < 16; ++db) { const unsigned char* vp = Vt + (32 * m2 + 4 * g + (r >> 2)) * XA_VP + (16 * db + 4 * (r & 3)) * 2;
;                     const s16x4 lo = __builtin_amdgcn_ds_read_tr16_b64_v4i16((LAS s16x4*)vp), hi = __builtin_amdgcn_ds_read_tr16_b64_v4i16((LAS s16x4*)(vp + 16 * XA_VP));
;                     bf16x8 av; av[0] = lo[0]; av[1] = lo[1]; av[2] = lo[2]; av[3] = lo[3]; av[4] = hi[0]; av[5] = hi[1]; av[6] = hi[2]; av[7] = hi[3];
;                     o[db] = __builtin_amdgcn_mfma_f32_16x16x32_bf16(av, pb, o[db], 0, 0, 0); }
	s_nop 0
	s_nop 0
	v_mfma_f32_16x16x32_bf16 v[14:17], v[224:227], v[74:77], v[14:17]
	ds_read_b64_tr_b16 v[204:205], v152 offset:33888
	ds_read_b64_tr_b16 v[206:207], v152 offset:42592
	s_waitcnt lgkmcnt(10)
	v_mfma_f32_16x16x32_bf16 v[10:13], v[228:231], v[74:77], v[10:13]
	ds_read_b64_tr_b16 v[208:209], v152 offset:33920
	ds_read_b64_tr_b16 v[210:211], v152 offset:42624
	s_waitcnt lgkmcnt(10)
	v_mfma_f32_16x16x32_bf16 v[66:69], v[232:235], v[74:77], v[6:9]
	ds_read_b64_tr_b16 v[212:213], v152 offset:33952
	ds_read_b64_tr_b16 v[214:215], v152 offset:42656
	s_nop 2
	s_waitcnt lgkmcnt(10)
	s_nop 0
	v_mfma_f32_16x16x32_bf16 v[34:37], v[236:239], v[74:77], v[106:109]
	ds_read_b64_tr_b16 v[216:217], v152 offset:34272
	ds_read_b64_tr_b16 v[218:219], v152 offset:42976
	s_waitcnt lgkmcnt(10)
	v_mfma_f32_16x16x32_bf16 v[38:41], v[240:243], v[74:77], v[102:105]
	ds_read_b64_tr_b16 v[220:221], v152 offset:51200
	ds_read_b64_tr_b16 v[222:223], v152 offset:59904
	s_waitcnt lgkmcnt(10)
	v_mfma_f32_16x16x32_bf16 v[42:45], v[244:247], v[74:77], v[98:101]
	ds_read_b64_tr_b16 v[224:225], v152 offset:51232
	ds_read_b64_tr_b16 v[226:227], v152 offset:59936
	s_waitcnt lgkmcnt(10)
	v_mfma_f32_16x16x32_bf16 v[46:49], v[204:207], v[74:77], v[86:89]
	ds_read_b64_tr_b16 v[228:229], v152 offset:51264
	ds_read_b64_tr_b16 v[230:231], v152 offset:59968
	s_waitcnt lgkmcnt(10)
	v_mfma_f32_16x16x32_bf16 v[50:53], v[208:211], v[74:77], v[78:81]
	ds_read_b64_tr_b16 v[232:233], v152 offset:51296
	ds_read_b64_tr_b16 v[234:235], v152 offset:60000
	s_waitcnt lgkmcnt(10)
	v_mfma_f32_16x16x32_bf16 v[54:57], v[212:215], v[74:77], v[70:73]
	ds_read_b64_tr_b16 v[236:237], v152 offset:51328
	ds_read_b64_tr_b16 v[238:239], v152 offset:60032
	s_waitcnt lgkmcnt(10)
	v_mfma_f32_16x16x32_bf16 v[70:73], v[216:219], v[74:77], v[2:5]
	ds_read_b64_tr_b16 v[240:241], v152 offset:51360
	ds_read_b64_tr_b16 v[242:243], v152 offset:60064
	v_cvt_pk_bf16_f32 v74, v111, v112
	v_cvt_pk_bf16_f32 v75, v113, v114
	v_cvt_pk_bf16_f32 v76, v115, v116
	v_cvt_pk_bf16_f32 v77, v117, v118
	s_nop 2
	s_waitcnt lgkmcnt(10)
	s_nop 0
	s_nop 0
	s_nop 0
	s_nop 0
	v_mfma_f32_16x16x32_bf16 v[2:5], v[220:223], v[74:77], v[34:37]
	ds_read_b64_tr_b16 v[244:245], v152 offset:51392
	ds_read_b64_tr_b16 v[246:247], v152 offset:60096
	s_nop 2
	s_waitcnt lgkmcnt(10)
	s_nop 0
	s_nop 0
	v_mfma_f32_16x16x32_bf16 v[6:9], v[224:227], v[74:77], v[38:41]
	ds_read_b64_tr_b16 v[204:205], v152 offset:51456
	ds_read_b64_tr_b16 v[206:207], v152 offset:60160
	s_nop 2
	s_waitcnt lgkmcnt(10)
	s_nop 0
	s_nop 0
	v_mfma_f32_16x16x32_bf16 v[34:37], v[228:231], v[74:77], v[42:45]
	ds_read_b64_tr_b16 v[208:209], v152 offset:51488
	ds_read_b64_tr_b16 v[210:211], v152 offset:60192
	s_nop 2
	s_waitcnt lgkmcnt(10)
	s_nop 0
	s_nop 0
	v_mfma_f32_16x16x32_bf16 v[38:41], v[232:235], v[74:77], v[46:49]
	ds_read_b64_tr_b16 v[212:213], v152 offset:51520
	ds_read_b64_tr_b16 v[214:215], v152 offset:60224
	s_nop 2
	s_waitcnt lgkmcnt(10)
	s_nop 0
	s_nop 0
	v_mfma_f32_16x16x32_bf16 v[42:45], v[236:239], v[74:77], v[50:53]
	ds_read_b64_tr_b16 v[216:217], v152 offset:51552
	ds_read_b64_tr_b16 v[218:219], v152 offset:60256
	s_nop 2
	s_waitcnt lgkmcnt(10)
	s_nop 0
	s_nop 0
	v_mfma_f32_16x16x32_bf16 v[46:49], v[240:243], v[74:77], v[54:57]
	ds_read_b64_tr_b16 v[220:221], v152 offset:51584
	ds_read_b64_tr_b16 v[222:223], v152 offset:60288
	s_nop 2
	s_waitcnt lgkmcnt(10)
	s_nop 0
	s_nop 0
	v_mfma_f32_16x16x32_bf16 v[50:53], v[244:247], v[74:77], v[58:61]
	ds_read_b64_tr_b16 v[224:225], v152 offset:51616
	ds_read_b64_tr_b16 v[226:227], v152 offset:60320
	s_nop 2
	s_waitcnt lgkmcnt(10)
	s_nop 0
	s_nop 0
	v_mfma_f32_16x16x32_bf16 v[30:33], v[204:207], v[74:77], v[30:33]
	ds_read_b64_tr_b16 v[228:229], v152 offset:51648
	ds_read_b64_tr_b16 v[230:231], v152 offset:60352
	s_waitcnt lgkmcnt(10)
	v_mfma_f32_16x16x32_bf16 v[26:29], v[208:211], v[74:77], v[26:29]
	ds_read_b64_tr_b16 v[232:233], v152 offset:51424
	ds_read_b64_tr_b16 v[234:235], v152 offset:60128
	s_waitcnt lgkmcnt(10)
	v_mfma_f32_16x16x32_bf16 v[22:25], v[212:215], v[74:77], v[22:25]
	ds_read_b64_tr_b16 v[236:237], v152 offset:51680
	ds_read_b64_tr_b16 v[238:239], v152 offset:60384
	s_waitcnt lgkmcnt(10)
	v_mfma_f32_16x16x32_bf16 v[18:21], v[216:219], v[74:77], v[18:21]
	s_waitcnt lgkmcnt(8)
	s_nop 0
	s_nop 0
	v_mfma_f32_16x16x32_bf16 v[14:17], v[220:223], v[74:77], v[14:17]
	s_waitcnt lgkmcnt(6)
	s_nop 0
	s_nop 0
	v_mfma_f32_16x16x32_bf16 v[10:13], v[224:227], v[74:77], v[10:13]
	s_waitcnt lgkmcnt(4)
	s_nop 0
	s_nop 0
	v_mfma_f32_16x16x32_bf16 v[58:61], v[228:231], v[74:77], v[66:69]
	s_nop 2
	ds_bpermute_b32 v66, v151, v82
	s_waitcnt lgkmcnt(0)
; #define LAS __attribute__((address_space(3)))
; __device__ __forceinline__ unsigned cvtpk(float lo, float hi) { unsigned r; asm volatile("v_cvt_pk_bf16_f32 %0, %1, %2" : "=v"(r) : "v"(lo), "v"(hi)); return r; }
; __device__ __forceinline__ void phase_xattn(CArgs& A, int l, unsigned char* lds, int tid) {
;     ...
;             for (int m2 = 0; m2 < 2; ++m2) {
;                 const bf16x8 pb = pack_frag(sc[2 * m2][0], sc[2 * m2][1], sc[2 * m2][2], sc[2 * m2][3], sc[2 * m2 + 1][0], sc[2 * m2 + 1][1], sc[2 * m2 + 1][2], sc[2 * m2 + 1][3]);
; #pragma unroll
;                 for (int db = 0; db < 16; ++db) { const unsigned char* vp = Vt + (32 * m2 + 4 * g + (r >> 2)) * XA_VP + (16 * db + 4 * (r & 3)) * 2;
;                     const s16x4 lo = __builtin_amdgcn_ds_read_tr16_b64_v4i16((LAS s16x4*)vp), hi = __builtin_amdgcn_ds_read_tr16_b64_v4i16((LAS s16x4*)(vp + 16 * XA_VP));
;                     bf16x8 av; av[0] = lo[0]; av[1] = lo[1]; av[2] = lo[2]; av[3] = lo[3]; av[4] = hi[0]; av[5] = hi[1]; av[6] = hi[2]; av[7] = hi[3];
;                     o[db] = __builtin_amdgcn_mfma_f32_16x16x32_bf16(av, pb, o[db], 0, 0, 0); }
;     ...
;         float ltot = lsum + __shfl_xor(lsum, 16); ltot += __shfl_xor(ltot, 32);
;         const float inv = 1.f / ltot;
;         bf16* op = O + row * DM + h * 256 + 4 * g;
; #pragma unroll
;         for (int db = 0; db < 16; ++db) { u32x2 w; w.x = cvtpk(o[db][0] * inv, o[db][1] * inv); w.y = cvtpk(o[db][2] * inv, o[db][3] * inv); *(u32x2*)(op + db * 16) = w; }
;     }
	v_add_f32_e32 v66, v82, v66
	ds_bpermute_b32 v67, v147, v66
	v_mfma_f32_16x16x32_bf16 v[54:57], v[232:235], v[74:77], v[62:65]
	s_nop 2
	s_waitcnt lgkmcnt(0)
	s_nop 0
	s_nop 0
	v_add_f32_e32 v66, v66, v67
	v_div_scale_f32 v67, s[0:1], v66, v66, 1.0
	v_rcp_f32_e32 v68, v67
	s_nop 0
	v_mfma_f32_16x16x32_bf16 v[62:65], v[236:239], v[74:77], v[70:73]
	v_readlane_b32 s0, v251, 6
	v_readlane_b32 s1, v251, 7
	v_fma_f32 v69, -v67, v68, 1.0
	v_fmac_f32_e32 v68, v69, v68
	v_div_scale_f32 v69, vcc, 1.0, v66, 1.0
	v_mul_f32_e32 v70, v69, v68
	v_fma_f32 v71, -v67, v70, v69
	v_fmac_f32_e32 v70, v71, v68
	v_fma_f32 v67, -v67, v70, v69
	v_div_fmas_f32 v67, v67, v68, v70
	v_div_fixup_f32 v70, v67, v66, 1.0
	v_lshl_add_u64 v[66:67], s[6:7], 0, v[144:145]
	v_mul_f32_e32 v2, v2, v70
	v_mul_f32_e32 v3, v3, v70
	v_lshl_add_u64 v[66:67], v[66:67], 0, s[14:15]
	v_lshlrev_b32_e32 v68, 1, v143
	v_mov_b32_e32 v69, v0
	v_cvt_pk_bf16_f32 v2, v2, v3
	v_mul_f32_e32 v3, v4, v70
	v_lshl_add_u64 v[66:67], v[66:67], 0, v[68:69]
	v_mul_f32_e32 v4, v5, v70
	v_cvt_pk_bf16_f32 v3, v3, v4
	global_store_dwordx2 v[66:67], v[2:3], off
	v_mul_f32_e32 v2, v6, v70
	v_mul_f32_e32 v3, v7, v70
	v_cvt_pk_bf16_f32 v2, v2, v3
	v_mul_f32_e32 v3, v8, v70
	v_mul_f32_e32 v4, v9, v70
	v_cvt_pk_bf16_f32 v3, v3, v4
	global_store_dwordx2 v[66:67], v[2:3], off offset:32
	v_mul_f32_e32 v2, v34, v70
	v_mul_f32_e32 v3, v35, v70
	v_cvt_pk_bf16_f32 v2, v2, v3
	v_mul_f32_e32 v3, v36, v70
	v_mul_f32_e32 v4, v37, v70
	v_cvt_pk_bf16_f32 v3, v3, v4
	global_store_dwordx2 v[66:67], v[2:3], off offset:64
	v_mul_f32_e32 v2, v38, v70
	v_mul_f32_e32 v3, v39, v70
	v_cvt_pk_bf16_f32 v2, v2, v3
	v_mul_f32_e32 v3, v40, v70
	v_mul_f32_e32 v4, v41, v70
	v_cvt_pk_bf16_f32 v3, v3, v4
	global_store_dwordx2 v[66:67], v[2:3], off offset:96
	v_mul_f32_e32 v2, v42, v70
	v_mul_f32_e32 v3, v43, v70
	v_cvt_pk_bf16_f32 v2, v2, v3
	v_mul_f32_e32 v3, v44, v70
	v_mul_f32_e32 v4, v45, v70
	v_cvt_pk_bf16_f32 v3, v3, v4
	global_store_dwordx2 v[66:67], v[2:3], off offset:128
	v_mul_f32_e32 v2, v46, v70
	v_mul_f32_e32 v3, v47, v70
	v_cvt_pk_bf16_f32 v2, v2, v3
	v_mul_f32_e32 v3, v48, v70
	v_mul_f32_e32 v4, v49, v70
	v_cvt_pk_bf16_f32 v3, v3, v4
	global_store_dwordx2 v[66:67], v[2:3], off offset:160
	v_mul_f32_e32 v2, v50, v70
	v_mul_f32_e32 v3, v51, v70
	v_cvt_pk_bf16_f32 v2, v2, v3
	v_mul_f32_e32 v3, v52, v70
	v_mul_f32_e32 v4, v53, v70
	v_cvt_pk_bf16_f32 v3, v3, v4
	global_store_dwordx2 v[66:67], v[2:3], off offset:192
	v_mul_f32_e32 v2, v54, v70
	v_mul_f32_e32 v3, v55, v70
	v_cvt_pk_bf16_f32 v2, v2, v3
	v_mul_f32_e32 v3, v56, v70
	v_mul_f32_e32 v4, v57, v70
	v_cvt_pk_bf16_f32 v3, v3, v4
	global_store_dwordx2 v[66:67], v[2:3], off offset:224
	v_mul_f32_e32 v2, v30, v70
	v_mul_f32_e32 v3, v31, v70
	v_cvt_pk_bf16_f32 v2, v2, v3
	v_mul_f32_e32 v3, v32, v70
	v_mul_f32_e32 v4, v33, v70
	v_cvt_pk_bf16_f32 v3, v3, v4
	global_store_dwordx2 v[66:67], v[2:3], off offset:256
	v_mul_f32_e32 v2, v26, v70
	v_mul_f32_e32 v3, v27, v70
	v_cvt_pk_bf16_f32 v2, v2, v3
	v_mul_f32_e32 v3, v28, v70
	v_mul_f32_e32 v4, v29, v70
	v_cvt_pk_bf16_f32 v3, v3, v4
	global_store_dwordx2 v[66:67], v[2:3], off offset:288
	v_mul_f32_e32 v2, v22, v70
	v_mul_f32_e32 v3, v23, v70
	v_cvt_pk_bf16_f32 v2, v2, v3
	v_mul_f32_e32 v3, v24, v70
	v_mul_f32_e32 v4, v25, v70
	v_cvt_pk_bf16_f32 v3, v3, v4
	global_store_dwordx2 v[66:67], v[2:3], off offset:320
	v_mul_f32_e32 v2, v18, v70
	v_mul_f32_e32 v3, v19, v70
	v_cvt_pk_bf16_f32 v2, v2, v3
	v_mul_f32_e32 v3, v20, v70
	v_mul_f32_e32 v4, v21, v70
	v_cvt_pk_bf16_f32 v3, v3, v4
	global_store_dwordx2 v[66:67], v[2:3], off offset:352
	v_mul_f32_e32 v2, v14, v70
	v_mul_f32_e32 v3, v15, v70
	v_cvt_pk_bf16_f32 v2, v2, v3
	v_mul_f32_e32 v3, v16, v70
	v_mul_f32_e32 v4, v17, v70
	v_cvt_pk_bf16_f32 v3, v3, v4
	global_store_dwordx2 v[66:67], v[2:3], off offset:384
	v_mul_f32_e32 v2, v10, v70
	v_mul_f32_e32 v3, v11, v70
	v_cvt_pk_bf16_f32 v2, v2, v3
	v_mul_f32_e32 v3, v12, v70
	v_mul_f32_e32 v4, v13, v70
	v_cvt_pk_bf16_f32 v3, v3, v4
	global_store_dwordx2 v[66:67], v[2:3], off offset:416
	v_mul_f32_e32 v2, v58, v70
	v_mul_f32_e32 v3, v59, v70
	v_cvt_pk_bf16_f32 v2, v2, v3
	v_mul_f32_e32 v3, v60, v70
	v_mul_f32_e32 v4, v61, v70
	v_cvt_pk_bf16_f32 v3, v3, v4
	global_store_dwordx2 v[66:67], v[2:3], off offset:448
	v_mul_f32_e32 v2, v62, v70
	v_mul_f32_e32 v3, v63, v70
	v_cvt_pk_bf16_f32 v2, v2, v3
	v_mul_f32_e32 v3, v64, v70
	v_mul_f32_e32 v4, v65, v70
	v_cvt_pk_bf16_f32 v3, v3, v4
	global_store_dwordx2 v[66:67], v[2:3], off offset:480
	s_load_dword s0, s[0:1], 0x0
	s_waitcnt lgkmcnt(0)
	s_add_i32 s11, s0, s11
	s_cmpk_gt_i32 s11, 0x3ff
	s_cbranch_scc0 .LBB0_144

; template <int MODE>
; __device__ __forceinline__ void attn_unit(const bf16* P, bf16* Y, int b, int h, int qb, unsigned char* lds, int tid) {
;     ...
; #pragma unroll
;             for (int i = 0; i < 16; ++i) mx = fmaxf(mx, fmaxf(s0[i], s1[i]));
;             mx = fmaxf(mx, __shfl_xor(mx, 32));
;             if (__any(mx > m + 8.f)) {
;                 const float mnew = fmaxf(m, mx); const float corr = __builtin_amdgcn_exp2f(m - mnew); m = mnew;
;                 lsum *= corr;
; #pragma unroll
;                 for (int i = 0; i < 16; ++i) { o0[i] *= corr; o1[i] *= corr; }
;             }
.LBB0_227:
	s_or_b64 exec, exec, s[54:55]
	v_max3_f32 v60, v48, v64, s78
	v_max3_f32 v60, v60, v49, v65
	v_max3_f32 v60, v60, v50, v66
	v_max3_f32 v60, v60, v51, v67
	v_max3_f32 v60, v60, v52, v68
	v_max3_f32 v60, v60, v53, v69
	v_max3_f32 v60, v60, v54, v12
	v_max3_f32 v60, v60, v55, v13
	v_max3_f32 v60, v60, v56, v8
	v_max3_f32 v60, v60, v57, v9
	v_max3_f32 v60, v60, v58, v6
	v_max3_f32 v60, v60, v59, v7
	v_max3_f32 v60, v60, v14, v4
	v_max3_f32 v60, v60, v15, v5
	v_max3_f32 v60, v60, v10, v2
	v_max3_f32 v60, v60, v11, v3
	ds_bpermute_b32 v61, v151, v60
	s_waitcnt lgkmcnt(0)
	v_max_f32_e32 v61, v61, v61
	v_max_f32_e32 v60, v60, v61
	v_add_f32_e32 v61, 0x41000000, v137
	v_cmp_gt_f32_e32 vcc, v60, v61
	s_cbranch_vccz .LBB0_222
	v_max_f32_e32 v60, v60, v60
	v_max_f32_e32 v61, v137, v137
	v_max_f32_e32 v61, v61, v60
	v_sub_f32_e32 v60, v137, v61
	v_exp_f32_e32 v60, v60
	v_mov_b32_e32 v137, v61
	v_pk_mul_f32 v[30:31], v[30:31], v[60:61] op_sel_hi:[1,0]
	v_pk_mul_f32 v[28:29], v[28:29], v[60:61] op_sel_hi:[1,0]
	v_pk_mul_f32 v[26:27], v[26:27], v[60:61] op_sel_hi:[1,0]
	v_pk_mul_f32 v[24:25], v[24:25], v[60:61] op_sel_hi:[1,0]
	v_pk_mul_f32 v[22:23], v[22:23], v[60:61] op_sel_hi:[1,0]
	v_pk_mul_f32 v[20:21], v[20:21], v[60:61] op_sel_hi:[1,0]
	v_pk_mul_f32 v[18:19], v[18:19], v[60:61] op_sel_hi:[1,0]
	v_pk_mul_f32 v[16:17], v[16:17], v[60:61] op_sel_hi:[1,0]
	v_pk_mul_f32 v[46:47], v[46:47], v[60:61] op_sel_hi:[1,0]
	v_pk_mul_f32 v[44:45], v[44:45], v[60:61] op_sel_hi:[1,0]
	v_pk_mul_f32 v[42:43], v[42:43], v[60:61] op_sel_hi:[1,0]
	v_pk_mul_f32 v[40:41], v[40:41], v[60:61] op_sel_hi:[1,0]
	v_pk_mul_f32 v[38:39], v[38:39], v[60:61] op_sel_hi:[1,0]
	v_pk_mul_f32 v[36:37], v[36:37], v[60:61] op_sel_hi:[1,0]
	v_pk_mul_f32 v[34:35], v[34:35], v[60:61] op_sel_hi:[1,0]
	v_pk_mul_f32 v[32:33], v[32:33], v[60:61] op_sel_hi:[1,0]
	v_mul_f32_e32 v135, v135, v60
	s_branch .LBB0_222

; template <int ENM>
; __global__ void __launch_bounds__(NTHREADS, 2) mega_fwd(Args A_) {
	.amdhsa_kernel _Z8mega_fwdILi255EEv4Args
		.amdhsa_group_segment_fixed_size 0
		.amdhsa_private_segment_fixed_size 0
		.amdhsa_kernarg_size 504
		.amdhsa_user_sgpr_count 2
		.amdhsa_user_sgpr_dispatch_ptr 0
		.amdhsa_user_sgpr_queue_ptr 0
		.amdhsa_user_sgpr_kernarg_segment_ptr 1
		.amdhsa_user_sgpr_dispatch_id 0
		.amdhsa_user_sgpr_kernarg_preload_length 0
		.amdhsa_user_sgpr_kernarg_preload_offset 0
		.amdhsa_user_sgpr_private_segment_size 0
		.amdhsa_uses_dynamic_stack 0
		.amdhsa_enable_private_segment 0
		.amdhsa_system_sgpr_workgroup_id_x 1
		.amdhsa_system_sgpr_workgroup_id_y 0
		.amdhsa_system_sgpr_workgroup_id_z 0
		.amdhsa_system_sgpr_workgroup_info 0
		.amdhsa_system_vgpr_workitem_id 2
		.amdhsa_next_free_vgpr 252
		.amdhsa_next_free_sgpr 102
		.amdhsa_accum_offset 252
		.amdhsa_reserve_vcc 1
		.amdhsa_float_round_mode_32 0
		.amdhsa_float_round_mode_16_64 0
		.amdhsa_float_denorm_mode_32 3
		.amdhsa_float_denorm_mode_16_64 3
		.amdhsa_dx10_clamp 1
		.amdhsa_ieee_mode 1
		.amdhsa_fp16_overflow 0
		.amdhsa_tg_split 0
		.amdhsa_exception_fp_ieee_invalid_op 0
		.amdhsa_exception_fp_denorm_src 0
		.amdhsa_exception_fp_ieee_div_zero 0
		.amdhsa_exception_fp_ieee_overflow 0
		.amdhsa_exception_fp_ieee_underflow 0
		.amdhsa_exception_fp_ieee_inexact 0
		.amdhsa_exception_int_div_zero 0
	.end_amdhsa_kernel

; template <int ENM>
; __global__ void __launch_bounds__(NTHREADS, 2) mega_fwd(Args A_) {
amdhsa.kernels:
  - .agpr_count:     0
    .args:
      - .offset:         0
        .size:           248
        .value_kind:     by_value
      - .offset:         248
        .size:           4
        .value_kind:     hidden_block_count_x
      - .offset:         252
        .size:           4
        .value_kind:     hidden_block_count_y
      - .offset:         256
        .size:           4
        .value_kind:     hidden_block_count_z
      - .offset:         260
        .size:           2
        .value_kind:     hidden_group_size_x
      - .offset:         262
        .size:           2
        .value_kind:     hidden_group_size_y
      - .offset:         264
        .size:           2
        .value_kind:     hidden_group_size_z
      - .offset:         266
        .size:           2
        .value_kind:     hidden_remainder_x
      - .offset:         268
        .size:           2
        .value_kind:     hidden_remainder_y
      - .offset:         270
        .size:           2
        .value_kind:     hidden_remainder_z
      - .offset:         288
        .size:           8
        .value_kind:     hidden_global_offset_x
      - .offset:         296
        .size:           8
        .value_kind:     hidden_global_offset_y
      - .offset:         304
        .size:           8
        .value_kind:     hidden_global_offset_z
      - .offset:         312
        .size:           2
        .value_kind:     hidden_grid_dims
      - .offset:         336
        .size:           8
        .value_kind:     hidden_multigrid_sync_arg
      - .offset:         368
        .size:           4
        .value_kind:     hidden_dynamic_lds_size
    .group_segment_fixed_size: 0
    .kernarg_segment_align: 8
    .kernarg_segment_size: 504
    .language:       OpenCL C
    .language_version:
      - 2
      - 0
    .max_flat_workgroup_size: 512
    .name:           _Z8mega_fwdILi255EEv4Args
    .private_segment_fixed_size: 0
    .sgpr_count:     108
    .sgpr_spill_count: 175
    .symbol:         _Z8mega_fwdILi255EEv4Args.kd
    .uniform_work_group_size: 1
    .uses_dynamic_stack: false
    .vgpr_count:     252
    .vgpr_spill_count: 0
    .wavefront_size: 64
